# adds P6-P1 group barrier (split-phase P6-done check in P1 first epilogue, write-through weight copies + conv-done counter)
# speedup vs baseline: 1.0327x; 1.0059x over previous
; #define LAS __attribute__((address_space(3)))
; __global__ void __launch_bounds__(NWAVES * 64, 2) mk_fwd(Args a) {
;     ...
;     float* rope = (float*)(ws + WS_ROPE); float* ssqA = (float*)(ws + WS_SSQA); float* ssqB = (float*)(ws + WS_SSQB); float* lamtab = (float*)(ws + WS_LAM);
;     bf16u* XB = (bf16u*)(ws + WS_XB);
;     bf16u* Qb = (bf16u*)(ws + WS_Q); bf16u* Kb = Qb + BUFE; bf16u* Vb = Qb + 2 * BUFE; bf16u* BGb = Qb + 3 * BUFE; bf16u* CGb = Qb + 4 * BUFE; bf16u* Ub = Qb + 5 * BUFE;
;     bf16u* SGA = Qb + 6 * BUFE; bf16u* SGB = Qb + 7 * BUFE;
;     bf16u* ACT = (bf16u*)(ws + WS_ACT); float* STASH = (float*)(ws + WS_STASH);
;     bf16u* O1 = (bf16u*)(ws + WS_O1); bf16u* O2 = (bf16u*)(ws + WS_O2); bf16u* MIXED = O1;
;     const int gw = vcu * NWAVES + wave, NGW = G * NWAVES;
;     volatile LAS unsigned* MISC = (volatile LAS unsigned*)(L + LDS_BYTES - 64);
;     if (tid < 2) MISC[tid] = 0u;
;     __syncthreads();
;     const XcdBarrier bar = xcd_barrier_post((unsigned*)(ws + WS_BAR), MISC);
; #pragma unroll 1
;     for (int rep0 = 0; rep0 < REP_P0; ++rep0) {
;         CONVERT_LAYER(0, gw, NGW, lane);
;         for (int idx = (vcu * NWAVES * 64) + tid; idx < NTOK * 8; idx += G * NWAVES * 64) {
;             const int row = idx >> 3, j = idx & 7;
;             const float ang = (float)positions[row] * a.freq[j];
;             rope[(size_t)row * 16 + j] = cosf(ang); rope[(size_t)row * 16 + 8 + j] = sinf(ang);
;         }
;         for (int m = gw; m < NTOK; m += NGW) {
;             const f32x4* xr = (const f32x4*)(x_in + (size_t)m * DMOD) + lane;
;             f32x4 v[4]; float s = 0.f;
; #pragma unroll
;             for (int j = 0; j < 4; ++j) { v[j] = xr[64 * j]; s += (v[j].x * v[j].x + v[j].y * v[j].y) + (v[j].z * v[j].z + v[j].w * v[j].w); }
;             s = wave_sum(s);
;             unsigned long long* o8 = (unsigned long long*)(XB + (size_t)m * DMOD) + lane;
; #pragma unroll
;             for (int j = 0; j < 4; ++j) o8[64 * j] = (unsigned long long)pk2(v[j].x, v[j].y) | ((unsigned long long)pk2(v[j].z, v[j].w) << 32);
;             if (lane < 16) ssqA[(size_t)m * 16 + lane] = (lane == 0) ? s : 0.f;
;         }
;         if (vcu == 0 && wave == 0) {
;             for (int l = 0; l < NLAYER; ++l) {
;                 const float s1 = wave_sum(lq1[l * 64 + lane] * lk1[l * 64 + lane]), s2 = wave_sum(lq2[l * 64 + lane] * lk2[l * 64 + lane]);
.LBB0_135:
	v_writelane_b32 v255, s72, 2
	s_nop 1
	v_writelane_b32 v255, s73, 3
	s_or_b64 exec, exec, s[2:3]
	s_add_u32 s0, s42, 0x100000
	s_addc_u32 s1, s43, 0
	v_writelane_b32 v255, s0, 4
	v_readlane_b32 s4, v253, 38
	s_mov_b32 s91, 0
	v_writelane_b32 v255, s1, 5
	s_add_u32 s0, s42, 0x200000
	s_addc_u32 s1, s43, 0
	s_add_u32 s82, s42, 0x9e00000
	s_addc_u32 s83, s43, 0
	s_add_u32 s6, s42, 0xbe00000
	v_writelane_b32 v255, s0, 6
	s_addc_u32 s7, s43, 0
	v_mov_b32_e32 v245, 0x358637bd
	v_writelane_b32 v255, s1, 7
	s_add_u32 s0, s42, 0xde00000
	v_writelane_b32 v255, s0, 8
	s_addc_u32 s0, s43, 0
	v_writelane_b32 v255, s0, 9
	s_add_u32 s0, s42, 0xfe00000
	v_writelane_b32 v255, s0, 10
	s_addc_u32 s0, s43, 0
	s_add_u32 s28, s42, 0x11e00000
	s_addc_u32 s29, s43, 0
	s_add_u32 s30, s42, 0x13e00000
	s_addc_u32 s31, s43, 0
	v_writelane_b32 v255, s0, 11
	s_add_u32 s0, s42, 0x17e00000
	s_addc_u32 s1, s43, 0
	v_writelane_b32 v255, s0, 12
	s_movk_i32 s61, 0x2000
	v_mov_b32_e32 v1, 0
	v_writelane_b32 v255, s1, 13
	s_add_u32 s0, s42, 0x19e00000
	s_addc_u32 s1, s43, 0
	s_add_u32 s14, s42, 0x1be00000
	s_addc_u32 s15, s43, 0
	s_add_u32 s86, s42, 0x1de00000
	s_addc_u32 s87, s43, 0
	s_ashr_i32 s79, s80, 31
	v_writelane_b32 v255, s0, 14
	s_cmpk_eq_i32 s80, 0x100
	s_mov_b32 s88, 0x8000
	v_writelane_b32 v255, s1, 15
	s_cselect_b64 s[0:1], -1, 0
	v_writelane_b32 v255, s0, 16
	s_lshl_b32 s89, s80, 2
	s_mov_b32 s27, 0xa000
	v_writelane_b32 v255, s1, 17
	s_abs_i32 s0, s80
	s_waitcnt lgkmcnt(0)
	v_cvt_f32_u32_e32 v0, s0
	s_lshl_b32 s1, s4, 5
	v_writelane_b32 v255, s1, 18
	s_sub_i32 s1, 0, s0
	v_rcp_iflag_f32_e32 v0, v0
	s_mov_b32 s26, 0xc000
	v_mov_b32_e32 v234, 1
	s_movk_i32 s10, 0x3ff
	v_mul_f32_e32 v0, 0x4f7ffffe, v0
	v_cvt_u32_f32_e32 v0, v0
	v_mov_b64_e32 v[236:237], 0x800
	v_mov_b32_e32 v235, 0x3e38aa3b
	v_mov_b32_e32 v248, 0xff800000
	v_readfirstlane_b32 s2, v0
	s_mul_i32 s1, s1, s2
	s_mul_hi_u32 s1, s2, s1
	s_add_i32 s2, s2, s1
	s_mul_hi_u32 s1, s2, 0x580
	s_mul_i32 s1, s1, s0
	s_sub_i32 s1, 0x580, s1
	s_sub_i32 s2, s1, s0
	s_cmp_ge_u32 s1, s0
	s_cselect_b32 s1, s2, s1
	s_sub_i32 s2, s1, s0
	s_cmp_ge_u32 s1, s0
	s_cselect_b32 s5, s2, s1
	s_cmp_eq_u32 s5, 0
	s_cselect_b64 s[2:3], -1, 0
	s_sub_i32 s0, s80, s5
	s_lshl_b32 s0, s0, 3
	v_writelane_b32 v255, s0, 19
	s_lshl_b32 s0, s80, 4
	v_writelane_b32 v255, s0, 20
	s_lshl_b32 s0, s4, 6
	s_lshl_b32 s1, s5, 9
	s_sub_i32 s8, s0, s1
	s_sub_i32 s0, s34, s1
	v_writelane_b32 v255, s0, 21
	s_lshl_b32 s0, s4, 2
	s_lshl_b32 s1, s5, 5
	s_sub_i32 s0, s0, s1
	v_writelane_b32 v255, s0, 22
	s_lshl_b32 s0, s80, 5
	s_sub_i32 s0, s0, s1
	v_writelane_b32 v255, s0, 23
	s_lshl_b32 s0, s4, 7
	s_lshl_b32 s1, s5, 10
	s_sub_i32 s0, s0, s1
	s_add_i32 s0, s0, 0xfff92000
	v_writelane_b32 v255, s0, 24
	s_lshl_b32 s0, s80, 10
	s_sub_i32 s0, s0, s1
	v_writelane_b32 v255, s0, 25
	s_lshl_b32 s0, s5, 3
	s_sub_i32 s1, s4, s0
	s_add_i32 s4, s1, 0xfffff240
	v_writelane_b32 v255, s4, 26
	s_mov_b32 s4, s74
	v_writelane_b32 v255, s4, 27
	s_sub_i32 s0, s74, s0
	s_xor_b64 s[2:3], s[2:3], -1
	v_writelane_b32 v255, s5, 28
	v_writelane_b32 v255, s0, 29
	s_add_i32 s0, s8, 0xfffc9000
	v_writelane_b32 v255, s0, 30
	s_add_i32 s0, s1, 0xfffff500
	v_writelane_b32 v255, s0, 31
	s_add_i32 s0, s1, 0xf500
	v_writelane_b32 v255, s0, 32
	v_writelane_b32 v255, s8, 33
	s_add_i32 s0, s8, 0xfffd4000
	v_writelane_b32 v255, s0, 34
	s_lshl_b32 s0, s80, 12
	s_lshl_b32 s1, s5, 12
	v_writelane_b32 v255, s5, 35
	s_sub_i32 s0, s0, s1
	v_writelane_b32 v255, s0, 36
	s_add_i32 s1, 0, 0x23fc0
	v_writelane_b32 v255, s1, 37
	s_add_i32 s1, 0, 0x23fc4
	v_writelane_b32 v255, s1, 38
	v_writelane_b32 v255, s2, 39
	s_lshl_b32 s44, s80, 6
	s_mov_b32 s5, 0x18000
	v_writelane_b32 v255, s3, 40
	v_writelane_b32 v255, s78, 41
	v_writelane_b32 v255, s82, 42
	s_mov_b32 s0, 0x50000
	v_mov_b64_e32 v[230:231], 0xff
	v_writelane_b32 v255, s83, 43
	s_mov_b32 s11, 0x41000000
	s_mov_b64 s[8:9], 0x40000
	s_mov_b64 s[70:71], 0x80
	s_mov_b64 s[62:63], 0x2000
	s_mov_b64 s[94:95], 0x20000
	s_mov_b64 s[72:73], 0x60000
	s_mov_b64 s[74:75], 0x80000
	s_mov_b64 s[66:67], 0xfe40000
	s_mov_b64 s[84:85], 0xfe40080
	s_mov_b32 s92, s91
	v_writelane_b32 v255, s79, 44
	s_barrier
	s_mov_b32 s98, 0
	s_mov_b32 s99, 0
	s_mov_b32 s100, 0
	s_cmpk_lg_i32 s80, 0x100
	s_cbranch_scc1 .Lgb_setup_done
	s_add_u32 s12, s42, 0x318000
	s_addc_u32 s13, s43, 0
	v_and_b32_e32 v2, 63, v244
	v_lshlrev_b32_e32 v3, 4, v2
	global_load_dwordx4 v[4:7], v3, s[12:13] sc1
	v_and_b32_e32 v8, 1, v2
	s_waitcnt vmcnt(0)
	v_readlane_b32 s1, v4, 0
	v_readlane_b32 s2, v5, 0
	v_readlane_b32 s3, v6, 0
	v_readlane_b32 s4, v7, 0
	v_readlane_b32 s16, v4, 1
	v_readlane_b32 s17, v5, 1
	v_readlane_b32 s18, v6, 1
	v_readlane_b32 s19, v7, 1
	v_cmp_eq_u32_e32 vcc, 1, v8
	s_nop 3
	v_mov_b32_e32 v9, s1
	v_mov_b32_e32 v10, s16
	v_cndmask_b32_e32 v9, v9, v10, vcc
	v_mov_b32_e32 v11, s2
	v_mov_b32_e32 v10, s17
	v_cndmask_b32_e32 v11, v11, v10, vcc
	v_mov_b32_e32 v12, s3
	v_mov_b32_e32 v10, s18
	v_cndmask_b32_e32 v12, v12, v10, vcc
	v_mov_b32_e32 v13, s4
	v_mov_b32_e32 v10, s19
	v_cndmask_b32_e32 v13, v13, v10, vcc
	v_xor_b32_e32 v9, v9, v4
	v_xor_b32_e32 v11, v11, v5
	v_xor_b32_e32 v12, v12, v6
	v_xor_b32_e32 v13, v13, v7
	v_or3_b32 v9, v9, v11, v12
	v_or_b32_e32 v9, v9, v13
	v_min_u32_e32 v10, v4, v5
	v_min3_u32 v10, v10, v6, v7
	v_cmp_ne_u32_e32 vcc, 0, v9
	v_cmp_eq_u32_e64 s[2:3], 0, v10
	s_nop 1
	s_or_b64 s[2:3], s[2:3], vcc
	s_cmp_lg_u64 s[2:3], 0
	s_cbranch_scc1 .Lgb_setup_done
	s_mov_b32 s98, 1

; __global__ void __launch_bounds__(NWAVES * 64, 2) mk_fwd(Args a) {
;     ...
;     for (int l = 0; l < NLAYER; ++l) {
;         unsigned char* wl = ws + WS_W + (size_t)l * W_LAYER;
; #pragma unroll 1
;         for (int rep1 = 0; rep1 < REP_P1; ++rep1) {
;             pg8::Gemm g{XB, (const bf16u*)(wl + WL_IN), NTOK, INW, DMOD}; int bxp = bx; asm volatile("" : "+s"(bxp)); pg8::StaticOrder S; S.init(NTOK, INW, G, bxp);
.LBB0_137:
	s_or_b64 exec, exec, s[16:17]
	s_cmp_lg_u32 s98, 0
	s_cbranch_scc0 .Lgb_arm_skip
	v_readlane_b32 s100, v253, 56
	v_readlane_b32 s101, v253, 57
	s_nop 3
	s_add_u32 s100, s100, 0x5e80
	s_addc_u32 s101, s101, 0
.Lgb_arm_skip:
	s_cmp_eq_u32 s2, 4
	s_mov_b32 s92, s2
	s_waitcnt lgkmcnt(0)
	s_barrier
	s_cbranch_scc1 .LBB0_759

; #define PG8_BAR __builtin_amdgcn_s_barrier()
;     __device__ __forceinline__ void operator()(const f32x4 (&acc)[2][2][4][2], const Unit& u, int wr, int wc, int fr_in, int fq_in) const {
;         int fr = fr_in, fq = fq_in; asm volatile("" : "+v"(fr), "+v"(fq));
;         const int colt = u.pn * BM, sec = colt >> 11, row0 = u.pm * BM + wr * 64 + fr;
;         float rstd[2][4];
;         if (u.pm == pm0) {
; template <class Epi, class Sched, bool ALIGN_EPI = false, bool SP2 = false, bool SPLITK = false>
; __device__ __forceinline__ void gemm_phase(PG8_LAS unsigned char* lds, const Gemm g, const Sched& S, const Epi& E) {
;     ...
;         if constexpr (ALIGN_EPI) { if (wr == 0) PG8_BAR; }
;         if constexpr (!Epi::AFTER_DRAIN) { E(acc, cur, wr, wc, fr, fq); S.done(cur); }
.LBB0_168:
	s_cmp_eq_u32 s100, 0
	s_cbranch_scc1 .Lgb_p6_skip
	v_mov_b32_e32 v130, 0
	s_mov_b32 vcc_lo, 0
.Lgb_p6_spin:
	global_load_dword v131, v130, s[100:101] sc1
	s_waitcnt vmcnt(0)
	v_readfirstlane_b32 s4, v131
	s_nop 3
	s_lshr_b32 s4, s4, 8
	s_cmp_ge_u32 s4, s92
	s_cbranch_scc1 .Lgb_p6_ok
	s_sleep 1
	s_add_i32 vcc_lo, vcc_lo, 1
	s_cmp_lt_u32 vcc_lo, 0x40000
	s_cbranch_scc1 .Lgb_p6_spin
.Lgb_p6_ok:
	s_mov_b32 s100, 0

; __device__ __forceinline__ unsigned xb_ld(unsigned* p)              { return __hip_atomic_load(p, __ATOMIC_RELAXED, __HIP_MEMORY_SCOPE_AGENT); }
; __device__ __forceinline__ unsigned xb_add(unsigned* p, unsigned v) { return __hip_atomic_fetch_add(p, v, __ATOMIC_RELAXED, __HIP_MEMORY_SCOPE_AGENT); }
; #define XB_SPIN(cond, bar) do { unsigned _sp = 0; while (cond) { __builtin_amdgcn_s_sleep(1); \
;     if ((++_sp & 255u) == 0u) { if (xb_ld(&(bar)[XB_TMO])) break; if (_sp > XB_SPIN_CAP) { atomicAdd(&(bar)[XB_TMO], 1u); break; } } } } while (0)
; #define GSYNC() do { for (int r_ = 0; r_ < REP_SYNC; ++r_) xcd_barrier(bar); } while (0)
; __device__ __forceinline__ void xcd_barrier(const XcdBarrier& b) {
;     asm volatile("s_waitcnt vmcnt(0)" ::: "memory");
;     __syncthreads();
;     if (threadIdx.x == 0) {
;         unsigned* bar = b.bar;
;         __builtin_amdgcn_s_waitcnt(0);
;         unsigned nloc = b.st[0], nx = b.st[1];
;         if (nloc == 0u) { xcd_barrier_complete(bar, b.x, nloc, nx); b.st[0] = nloc; b.st[1] = nx; }
;         const unsigned old = xb_add(&bar[XB_XSUB(b.x)], 1u);
;         const unsigned gen = old / nloc;
;         if (old + 1u == (gen + 1u) * nloc) {
;             __builtin_amdgcn_fence(__ATOMIC_RELEASE, "agent");
;             asm volatile("s_waitcnt vmcnt(0)" ::: "memory");
;             const unsigned og = xb_add(&bar[XB_TOP], 1u);
;             const unsigned tg = og / nx;
;             if (og + 1u == (tg + 1u) * nx) xb_add(&bar[XB_TOPGEN], 1u);
;             else XB_SPIN(xb_ld(&bar[XB_TOPGEN]) == tg, bar);
;             __builtin_amdgcn_fence(__ATOMIC_ACQUIRE, "agent");
;             xb_add(&bar[XB_XGEN(b.x)], 1u);
;             asm volatile("s_waitcnt vmcnt(0)" ::: "memory");
;         } else {
;             XB_SPIN(xb_ld(&bar[XB_XGEN(b.x)]) == gen, bar);
;             __builtin_amdgcn_fence(__ATOMIC_ACQUIRE, "agent");
;             asm volatile("s_waitcnt vmcnt(0)" ::: "memory");
;         }
;     }
;     __syncthreads();
; }
; __global__ void __launch_bounds__(NWAVES * 64, 2) mk_fwd(Args a) {
;     ...
;         GSYNC();
.LBB0_441:
	s_waitcnt vmcnt(0)
	s_barrier
	s_mov_b64 s[2:3], exec
	v_readlane_b32 s12, v253, 36
	v_readlane_b32 s13, v253, 37
	s_and_b64 s[12:13], s[2:3], s[12:13]
	s_mov_b64 exec, s[12:13]
	s_cbranch_execz .LBB0_493
	s_cmp_lg_u32 s98, 0
	s_cbranch_scc0 .Lgb_full_493
	v_readlane_b32 s4, v253, 1
	v_readlane_b32 s12, v253, 56
	v_readlane_b32 s13, v253, 57
	s_add_i32 s99, s99, 4
	s_nop 2
	s_and_b32 s4, s4, 63
	s_lshl_b32 s4, s4, 7
	s_add_i32 s4, s4, 0x3e00
	v_mov_b32_e32 v2, s4
	s_mov_b32 s1, 0
	s_nop 1
	global_atomic_add v2, v234, s[12:13]
	v_mov_b32_e32 v4, 0x5e00
	global_atomic_add v4, v234, s[12:13]

; #define GSYNC() do { for (int r_ = 0; r_ < REP_SYNC; ++r_) xcd_barrier(bar); } while (0)
; __global__ void __launch_bounds__(NWAVES * 64, 2) mk_fwd(Args a) {
;     ...
;         GSYNC();
.Lgb_grp_ok_569:
	v_mov_b32_e32 v4, 0x5e00
	s_lshl_b32 s16, s92, 8
	s_add_i32 s16, s16, 0x100
.Lgb_p3_569:
	global_load_dword v3, v4, s[12:13] sc1
	s_waitcnt vmcnt(0)
	v_readfirstlane_b32 s17, v3
	s_nop 3
	s_cmp_ge_u32 s17, s16
	s_cbranch_scc1 .Lgb_p3_ok_569
	s_sleep 1
	s_add_i32 s1, s1, 1
	s_cmp_lt_u32 s1, 0x40000
	s_cbranch_scc1 .Lgb_p3_569

; #define LAS __attribute__((address_space(3)))
; template <int MODE>
; __device__ __forceinline__ void p0_item(const float* W, int K, int N, bf16u* WT, const float* ks, LAS float* scr, int item, int lane) {
;     const int nblk = N / 64, kb = item / nblk, nb = item - kb * nblk, k0 = 64 * kb, n0 = 64 * nb;
;     int nn = n0 + lane;
;     if (MODE == 1) {
;         if (nn < 2048) { const int p = nn & 63; if (p < 16) nn = (nn & ~15) | (p & 3) | ((p & 4) << 1) | ((p & 8) >> 1); }
;         else if (nn >= 4096) { const int sec = nn >= 6144 ? 6144 : 4096, r = nn - sec, q = r & 255; nn = sec + ((q >> 7) << 10) + 128 * (r >> 8) + (q & 127); }
;     }
;     int drow = n0;
;     if (MODE == 2) drow = 256 * (n0 >> 7) + (n0 & 127);
;     if (MODE == 3) drow = 256 * (n0 >> 7) + 128 + (n0 & 127);
;     const float* src = W + (size_t)k0 * N + nn;
;     float v[64];
; #pragma unroll
;     for (int kk = 0; kk < 64; ++kk) v[kk] = src[(size_t)kk * N];
.LBB0_597:
	s_or_b64 exec, exec, s[16:17]
	s_lshl_b32 s16, s4, 6
	s_ashr_i32 s17, s16, 31
	s_lshl_b64 s[20:21], s[16:17], 15
	s_add_u32 s20, s3, s20
	s_addc_u32 s21, s49, s21
	v_ashrrev_i32_e32 v3, 31, v2
	v_lshl_add_u64 v[2:3], v[2:3], 2, s[20:21]
	v_add_co_u32_e32 v6, vcc, s88, v2
	s_mov_b32 s4, 0x10000
	s_nop 0
	v_addc_co_u32_e32 v7, vcc, 0, v3, vcc
	global_load_dword v4, v[2:3], off
	global_load_dword v5, v[6:7], off
	v_add_co_u32_e32 v6, vcc, s4, v2
	s_mov_b32 s4, 0x20000
	s_nop 0
	v_addc_co_u32_e32 v7, vcc, 0, v3, vcc
	v_add_co_u32_e32 v8, vcc, s5, v2
	global_load_dword v6, v[6:7], off
	s_nop 0
	v_addc_co_u32_e32 v9, vcc, 0, v3, vcc
	global_load_dword v7, v[8:9], off
	v_add_co_u32_e32 v8, vcc, s4, v2
	s_mov_b32 s4, 0x28000
	s_nop 0
	v_addc_co_u32_e32 v9, vcc, 0, v3, vcc
	v_add_co_u32_e32 v10, vcc, s4, v2
	s_mov_b32 s4, 0x30000
	s_nop 0
	v_addc_co_u32_e32 v11, vcc, 0, v3, vcc
	v_add_co_u32_e32 v12, vcc, s4, v2
	s_mov_b32 s4, 0x38000
	s_nop 0
	v_addc_co_u32_e32 v13, vcc, 0, v3, vcc
	v_add_co_u32_e32 v14, vcc, s4, v2
	s_mov_b32 s4, 0x40000
	s_nop 0
	v_addc_co_u32_e32 v15, vcc, 0, v3, vcc
	global_load_dword v8, v[8:9], off
	s_lshl_b64 s[20:21], s[16:17], 2
	global_load_dword v10, v[10:11], off
	s_add_u32 s20, s50, s20
	global_load_dword v12, v[12:13], off
	s_addc_u32 s21, s51, s21
	global_load_dword v61, v[14:15], off
	v_add_co_u32_e32 v14, vcc, s4, v2
	s_mov_b32 s4, 0x48000
	s_nop 0
	v_addc_co_u32_e32 v15, vcc, 0, v3, vcc
	global_load_dword v62, v[14:15], off
	v_add_co_u32_e32 v14, vcc, s4, v2
	s_mov_b32 s4, 0x58000
	s_nop 0
	v_addc_co_u32_e32 v15, vcc, 0, v3, vcc
	global_load_dword v65, v[14:15], off
	v_add_co_u32_e32 v14, vcc, s0, v2
	s_add_i32 s1, s1, s59
	s_nop 0
	v_addc_co_u32_e32 v15, vcc, 0, v3, vcc
	global_load_dword v67, v[14:15], off
	v_add_co_u32_e32 v14, vcc, s4, v2
	s_mov_b32 s4, 0x60000
	s_nop 0
	v_addc_co_u32_e32 v15, vcc, 0, v3, vcc
	global_load_dword v69, v[14:15], off
	v_add_co_u32_e32 v14, vcc, s4, v2
	s_mov_b32 s4, 0x68000
	s_nop 0
	v_addc_co_u32_e32 v15, vcc, 0, v3, vcc
	global_load_dword v71, v[14:15], off
	v_add_co_u32_e32 v14, vcc, s4, v2
	s_mov_b32 s4, 0x70000
	s_nop 0
	v_addc_co_u32_e32 v15, vcc, 0, v3, vcc
	global_load_dword v75, v[14:15], off
	v_add_co_u32_e32 v14, vcc, s4, v2
	s_mov_b32 s4, 0x78000
	s_nop 0
	v_addc_co_u32_e32 v15, vcc, 0, v3, vcc
	global_load_dword v82, v[14:15], off
	v_add_co_u32_e32 v14, vcc, s4, v2
	s_mov_b32 s4, 0x80000
	s_nop 0
	v_addc_co_u32_e32 v15, vcc, 0, v3, vcc
	global_load_dword v92, v[14:15], off
	v_add_co_u32_e32 v14, vcc, s4, v2
	s_mov_b32 s4, 0x88000
	s_nop 0
	v_addc_co_u32_e32 v15, vcc, 0, v3, vcc
	global_load_dword v9, v[14:15], off
	v_add_co_u32_e32 v14, vcc, s4, v2
	s_mov_b32 s4, 0x90000
	s_nop 0
	v_addc_co_u32_e32 v15, vcc, 0, v3, vcc
	global_load_dword v11, v[14:15], off
	v_add_co_u32_e32 v14, vcc, s4, v2
	s_mov_b32 s4, 0x98000
	s_nop 0
	v_addc_co_u32_e32 v15, vcc, 0, v3, vcc
	global_load_dword v13, v[14:15], off
	v_add_co_u32_e32 v14, vcc, s4, v2
	s_mov_b32 s4, 0xa0000
	s_nop 0
	v_addc_co_u32_e32 v15, vcc, 0, v3, vcc
	global_load_dword v58, v[14:15], off
	v_add_co_u32_e32 v14, vcc, s4, v2
	s_mov_b32 s4, 0xa8000
	s_nop 0
	v_addc_co_u32_e32 v15, vcc, 0, v3, vcc
	global_load_dword v59, v[14:15], off
	v_add_co_u32_e32 v14, vcc, s4, v2
	s_mov_b32 s4, 0xb0000
	s_nop 0
	v_addc_co_u32_e32 v15, vcc, 0, v3, vcc
	global_load_dword v60, v[14:15], off
	v_add_co_u32_e32 v14, vcc, s4, v2
	s_mov_b32 s4, 0xb8000
	s_nop 0
	v_addc_co_u32_e32 v15, vcc, 0, v3, vcc
	global_load_dword v63, v[14:15], off
	v_add_co_u32_e32 v14, vcc, s4, v2
	s_mov_b32 s4, 0xc0000
	s_nop 0
	v_addc_co_u32_e32 v15, vcc, 0, v3, vcc
	global_load_dword v72, v[14:15], off
	v_add_co_u32_e32 v14, vcc, s4, v2
	s_mov_b32 s4, 0xc8000
	s_nop 0
	v_addc_co_u32_e32 v15, vcc, 0, v3, vcc
	global_load_dword v73, v[14:15], off
	v_add_co_u32_e32 v14, vcc, s4, v2
	s_mov_b32 s4, 0xd0000
	s_nop 0
	v_addc_co_u32_e32 v15, vcc, 0, v3, vcc
	global_load_dword v76, v[14:15], off
	v_add_co_u32_e32 v14, vcc, s4, v2
	s_mov_b32 s4, 0xd8000
	s_nop 0
	v_addc_co_u32_e32 v15, vcc, 0, v3, vcc
	global_load_dword v87, v[14:15], off
	v_add_co_u32_e32 v14, vcc, s4, v2
	s_mov_b32 s4, 0xe0000
	s_nop 0
	v_addc_co_u32_e32 v15, vcc, 0, v3, vcc
	global_load_dword v89, v[14:15], off
	v_add_co_u32_e32 v14, vcc, s4, v2
	s_mov_b32 s4, 0xe8000
	s_nop 0
	v_addc_co_u32_e32 v15, vcc, 0, v3, vcc
	global_load_dword v90, v[14:15], off
	v_add_co_u32_e32 v14, vcc, s4, v2
	s_mov_b32 s4, 0xf0000
	s_nop 0
	v_addc_co_u32_e32 v15, vcc, 0, v3, vcc
	global_load_dword v91, v[14:15], off
	v_add_co_u32_e32 v14, vcc, s4, v2
	s_mov_b32 s4, 0xf8000
	s_nop 0
	v_addc_co_u32_e32 v15, vcc, 0, v3, vcc
	global_load_dword v93, v[14:15], off
	v_add_co_u32_e32 v14, vcc, s4, v2
	s_mov_b32 s4, 0x100000
	s_nop 0
	v_addc_co_u32_e32 v15, vcc, 0, v3, vcc
	global_load_dword v99, v[14:15], off
	v_add_co_u32_e32 v14, vcc, s4, v2
	s_mov_b32 s4, 0x108000
	s_nop 0
	v_addc_co_u32_e32 v15, vcc, 0, v3, vcc
	global_load_dword v64, v[14:15], off
	v_add_co_u32_e32 v14, vcc, s4, v2
	s_mov_b32 s4, 0x110000
	s_nop 0
	v_addc_co_u32_e32 v15, vcc, 0, v3, vcc
	global_load_dword v66, v[14:15], off
	v_add_co_u32_e32 v14, vcc, s4, v2
	s_mov_b32 s4, 0x118000
	s_nop 0
	v_addc_co_u32_e32 v15, vcc, 0, v3, vcc
	global_load_dword v68, v[14:15], off
	v_add_co_u32_e32 v14, vcc, s4, v2
	s_mov_b32 s4, 0x120000
	s_nop 0
	v_addc_co_u32_e32 v15, vcc, 0, v3, vcc
	global_load_dword v70, v[14:15], off
	v_add_co_u32_e32 v14, vcc, s4, v2
	s_mov_b32 s4, 0x128000
	s_nop 0
	v_addc_co_u32_e32 v15, vcc, 0, v3, vcc
	global_load_dword v74, v[14:15], off
	v_add_co_u32_e32 v14, vcc, s4, v2
	s_mov_b32 s4, 0x130000
	s_nop 0
; template <int MODE>
; __device__ __forceinline__ void p0_item(const float* W, int K, int N, bf16u* WT, const float* ks, LAS float* scr, int item, int lane) {
;     ...
;     const float* src = W + (size_t)k0 * N + nn;
;     float v[64];
; #pragma unroll
;     for (int kk = 0; kk < 64; ++kk) v[kk] = src[(size_t)kk * N];
;     if (ks) {
; #pragma unroll
;         for (int kk = 0; kk < 64; ++kk) v[kk] *= ks[k0 + kk];
	v_addc_co_u32_e32 v15, vcc, 0, v3, vcc
	global_load_dword v78, v[14:15], off
	v_add_co_u32_e32 v14, vcc, s4, v2
	s_mov_b32 s4, 0x138000
	s_nop 0
	v_addc_co_u32_e32 v15, vcc, 0, v3, vcc
	global_load_dword v88, v[14:15], off
	v_add_co_u32_e32 v14, vcc, s4, v2
	s_mov_b32 s4, 0x140000
	s_nop 0
	v_addc_co_u32_e32 v15, vcc, 0, v3, vcc
	global_load_dword v94, v[14:15], off
	v_add_co_u32_e32 v14, vcc, s4, v2
	s_mov_b32 s4, 0x148000
	s_nop 0
	v_addc_co_u32_e32 v15, vcc, 0, v3, vcc
	global_load_dword v95, v[14:15], off
	v_add_co_u32_e32 v14, vcc, s4, v2
	s_mov_b32 s4, 0x150000
	s_nop 0
	v_addc_co_u32_e32 v15, vcc, 0, v3, vcc
	global_load_dword v96, v[14:15], off
	v_add_co_u32_e32 v14, vcc, s4, v2
	s_mov_b32 s4, 0x158000
	s_nop 0
	v_addc_co_u32_e32 v15, vcc, 0, v3, vcc
	global_load_dword v97, v[14:15], off
	v_add_co_u32_e32 v14, vcc, s4, v2
	s_mov_b32 s4, 0x160000
	s_nop 0
	v_addc_co_u32_e32 v15, vcc, 0, v3, vcc
	global_load_dword v98, v[14:15], off
	v_add_co_u32_e32 v14, vcc, s4, v2
	s_mov_b32 s4, 0x168000
	s_nop 0
	v_addc_co_u32_e32 v15, vcc, 0, v3, vcc
	global_load_dword v100, v[14:15], off
	v_add_co_u32_e32 v14, vcc, s4, v2
	s_mov_b32 s4, 0x170000
	s_nop 0
	v_addc_co_u32_e32 v15, vcc, 0, v3, vcc
	global_load_dword v101, v[14:15], off
	v_add_co_u32_e32 v14, vcc, s4, v2
	s_mov_b32 s4, 0x178000
	s_nop 0
	v_addc_co_u32_e32 v15, vcc, 0, v3, vcc
	global_load_dword v102, v[14:15], off
	v_add_co_u32_e32 v14, vcc, s4, v2
	s_mov_b32 s4, 0x180000
	s_nop 0
	v_addc_co_u32_e32 v15, vcc, 0, v3, vcc
	global_load_dword v103, v[14:15], off
	v_add_co_u32_e32 v14, vcc, s4, v2
	s_mov_b32 s4, 0x188000
	s_nop 0
	v_addc_co_u32_e32 v15, vcc, 0, v3, vcc
	global_load_dword v0, v[14:15], off
	v_add_co_u32_e32 v14, vcc, s4, v2
	s_mov_b32 s4, 0x190000
	s_nop 0
	v_addc_co_u32_e32 v15, vcc, 0, v3, vcc
	v_add_co_u32_e32 v16, vcc, s4, v2
	s_mov_b32 s4, 0x198000
	s_nop 0
	v_addc_co_u32_e32 v17, vcc, 0, v3, vcc
	global_load_dword v14, v[14:15], off
	s_nop 0
	global_load_dword v15, v[16:17], off
	v_add_co_u32_e32 v16, vcc, s4, v2
	s_mov_b32 s4, 0x1a0000
	s_nop 0
	v_addc_co_u32_e32 v17, vcc, 0, v3, vcc
	v_add_co_u32_e32 v48, vcc, s4, v2
	s_mov_b32 s4, 0x1a8000
	s_nop 0
	v_addc_co_u32_e32 v49, vcc, 0, v3, vcc
	global_load_dword v16, v[16:17], off
	s_nop 0
	global_load_dword v17, v[48:49], off
	v_add_co_u32_e32 v48, vcc, s4, v2
	s_mov_b32 s4, 0x1b0000
	s_nop 0
	v_addc_co_u32_e32 v49, vcc, 0, v3, vcc
	global_load_dword v47, v[48:49], off
	v_add_co_u32_e32 v48, vcc, s4, v2
	s_mov_b32 s4, 0x1b8000
	s_nop 0
	v_addc_co_u32_e32 v49, vcc, 0, v3, vcc
	v_add_co_u32_e32 v50, vcc, s4, v2
	s_mov_b32 s4, 0x1c0000
	s_nop 0
	v_addc_co_u32_e32 v51, vcc, 0, v3, vcc
	global_load_dword v48, v[48:49], off
	s_nop 0
	global_load_dword v49, v[50:51], off
	v_add_co_u32_e32 v50, vcc, s4, v2
	s_mov_b32 s4, 0x1c8000
	s_nop 0
	v_addc_co_u32_e32 v51, vcc, 0, v3, vcc
	v_add_co_u32_e32 v52, vcc, s4, v2
	s_mov_b32 s4, 0x1d0000
	s_nop 0
	v_addc_co_u32_e32 v53, vcc, 0, v3, vcc
	global_load_dword v50, v[50:51], off
	s_nop 0
	global_load_dword v51, v[52:53], off
	v_add_co_u32_e32 v52, vcc, s4, v2
	s_mov_b32 s4, 0x1d8000
	s_nop 0
	v_addc_co_u32_e32 v53, vcc, 0, v3, vcc
	v_add_co_u32_e32 v54, vcc, s4, v2
	s_mov_b32 s4, 0x1e0000
	s_nop 0
	v_addc_co_u32_e32 v55, vcc, 0, v3, vcc
	global_load_dword v52, v[52:53], off
	s_nop 0
	global_load_dword v53, v[54:55], off
	v_add_co_u32_e32 v54, vcc, s4, v2
	s_mov_b32 s4, 0x1e8000
	s_nop 0
	v_addc_co_u32_e32 v55, vcc, 0, v3, vcc
	v_add_co_u32_e32 v56, vcc, s4, v2
	s_mov_b32 s4, 0x1f0000
	s_nop 0
	v_addc_co_u32_e32 v57, vcc, 0, v3, vcc
	global_load_dword v54, v[54:55], off
	s_nop 0
	global_load_dword v55, v[56:57], off
	v_add_co_u32_e32 v56, vcc, s4, v2
	s_mov_b32 s4, 0x1f8000
	s_nop 0
	v_addc_co_u32_e32 v57, vcc, 0, v3, vcc
	v_add_co_u32_e32 v2, vcc, s4, v2
	global_load_dword v56, v[56:57], off
	s_nop 0
	v_addc_co_u32_e32 v3, vcc, 0, v3, vcc
	global_load_dword v57, v[2:3], off
	global_load_dwordx4 v[104:107], v1, s[20:21] offset:48
	global_load_dwordx4 v[108:111], v1, s[20:21] offset:32
	global_load_dwordx4 v[112:115], v1, s[20:21] offset:16
	global_load_dwordx4 v[116:119], v1, s[20:21]
	s_waitcnt vmcnt(0)
	v_mul_f32_e32 v69, v69, v111
	v_mul_f32_e32 v81, v8, v112
	v_mul_f32_e32 v77, v4, v116
	v_mul_f32_e32 v79, v5, v117
	v_mul_f32_e32 v84, v10, v113
	v_mul_f32_e32 v85, v12, v114
	v_mul_f32_e32 v86, v61, v115
	v_mul_f32_e32 v61, v62, v108
	v_mul_f32_e32 v62, v65, v109
	v_mul_f32_e32 v65, v67, v110
	v_mul_f32_e32 v67, v71, v104
	v_mul_f32_e32 v71, v75, v105
	v_mul_f32_e32 v75, v82, v106
	v_mul_f32_e32 v82, v92, v107
	global_load_dwordx4 v[2:5], v1, s[20:21] offset:112
	global_load_dwordx4 v[108:111], v1, s[20:21] offset:96
	global_load_dwordx4 v[112:115], v1, s[20:21] offset:80
	global_load_dwordx4 v[104:107], v1, s[20:21] offset:64
	v_mul_f32_e32 v80, v6, v118
	v_mul_f32_e32 v83, v7, v119
	s_waitcnt vmcnt(2)
	v_mul_f32_e32 v89, v89, v111
	s_waitcnt vmcnt(1)
	v_mul_f32_e32 v72, v72, v115
	s_waitcnt vmcnt(0)
	v_mul_f32_e32 v92, v9, v104
	v_mul_f32_e32 v104, v11, v105
	v_mul_f32_e32 v105, v13, v106
	v_mul_f32_e32 v106, v58, v107
	v_mul_f32_e32 v58, v59, v112
	v_mul_f32_e32 v59, v60, v113
	v_mul_f32_e32 v60, v63, v114
	v_mul_f32_e32 v63, v73, v108
	v_mul_f32_e32 v73, v76, v109
	v_mul_f32_e32 v76, v87, v110
	v_mul_f32_e32 v87, v90, v2
	v_mul_f32_e32 v90, v91, v3
	v_mul_f32_e32 v91, v93, v4
	v_mul_f32_e32 v93, v99, v5
	global_load_dwordx4 v[2:5], v1, s[20:21] offset:176
	global_load_dwordx4 v[6:9], v1, s[20:21] offset:160
	global_load_dwordx4 v[10:13], v1, s[20:21] offset:144
	global_load_dwordx4 v[108:111], v1, s[20:21] offset:128
	s_waitcnt vmcnt(3)
	v_mul_f32_e32 v100, v100, v2
	s_waitcnt vmcnt(2)
; template <int MODE>
; __device__ __forceinline__ void p0_item(const float* W, int K, int N, bf16u* WT, const float* ks, LAS float* scr, int item, int lane) {
;     ...
;         for (int kk = 0; kk < 64; ++kk) v[kk] *= ks[k0 + kk];
;     }
; #pragma unroll
;     for (int kk = 0; kk < 64; ++kk) scr[kk * 65 + lane] = v[kk];
;     asm volatile("s_waitcnt lgkmcnt(0)" ::: "memory");
	v_mul_f32_e32 v107, v95, v6
	s_waitcnt vmcnt(1)
	v_mul_f32_e32 v74, v74, v10
	s_waitcnt vmcnt(0)
	v_mul_f32_e32 v64, v64, v108
	v_mul_f32_e32 v66, v66, v109
	v_mul_f32_e32 v78, v78, v11
	v_mul_f32_e32 v88, v88, v12
	v_mul_f32_e32 v99, v94, v13
	v_mul_f32_e32 v108, v96, v7
	v_mul_f32_e32 v109, v97, v8
	v_mul_f32_e32 v98, v98, v9
	v_mul_f32_e32 v101, v101, v3
	v_mul_f32_e32 v102, v102, v4
	v_mul_f32_e32 v103, v103, v5
	global_load_dwordx4 v[2:5], v1, s[20:21] offset:240
	global_load_dwordx4 v[6:9], v1, s[20:21] offset:224
	global_load_dwordx4 v[10:13], v1, s[20:21] offset:208
	global_load_dwordx4 v[94:97], v1, s[20:21] offset:192
	ds_write2_b32 v31, v77, v79 offset1:65
	ds_write2_b32 v31, v80, v83 offset0:130 offset1:195
	v_mul_f32_e32 v68, v68, v110
	v_mul_f32_e32 v70, v70, v111
	s_waitcnt vmcnt(3)
	v_mul_f32_e32 v2, v54, v2
	s_waitcnt vmcnt(2)
	v_mul_f32_e32 v6, v50, v6
	s_waitcnt vmcnt(1)
	v_mul_f32_e32 v10, v17, v10
	v_add_u32_e32 v17, 0x400, v31
	ds_write2_b32 v17, v81, v84 offset0:4 offset1:69
	ds_write2_b32 v17, v85, v86 offset0:134 offset1:199
	v_add_u32_e32 v17, 0x800, v31
	ds_write2_b32 v17, v61, v62 offset0:8 offset1:73
	ds_write2_b32 v17, v65, v69 offset0:138 offset1:203
	v_add_u32_e32 v17, 0xc00, v31
	ds_write2_b32 v17, v67, v71 offset0:12 offset1:77
	ds_write2_b32 v17, v75, v82 offset0:142 offset1:207
	v_add_u32_e32 v17, 0x1000, v31
	ds_write2_b32 v17, v92, v104 offset0:16 offset1:81
	ds_write2_b32 v17, v105, v106 offset0:146 offset1:211
	v_add_u32_e32 v17, 0x1400, v31
	ds_write2_b32 v17, v58, v59 offset0:20 offset1:85
	ds_write2_b32 v17, v60, v72 offset0:150 offset1:215
	v_add_u32_e32 v17, 0x1800, v31
	ds_write2_b32 v17, v63, v73 offset0:24 offset1:89
	ds_write2_b32 v17, v76, v89 offset0:154 offset1:219
	v_add_u32_e32 v17, 0x1c00, v31
	ds_write2_b32 v17, v87, v90 offset0:28 offset1:93
	ds_write2_b32 v17, v91, v93 offset0:158 offset1:223
	v_add_u32_e32 v17, 0x2000, v31
	ds_write2_b32 v17, v64, v66 offset0:32 offset1:97
	ds_write2_b32 v17, v68, v70 offset0:162 offset1:227
	v_add_u32_e32 v17, 0x2400, v31
	ds_write2_b32 v17, v74, v78 offset0:36 offset1:101
	ds_write2_b32 v17, v88, v99 offset0:166 offset1:231
	v_add_u32_e32 v17, 0x2800, v31
	ds_write2_b32 v17, v107, v108 offset0:40 offset1:105
	ds_write2_b32 v17, v109, v98 offset0:170 offset1:235
	v_add_u32_e32 v17, 0x2c00, v31
	s_waitcnt vmcnt(0)
	v_mul_f32_e32 v0, v0, v94
	v_mul_f32_e32 v14, v14, v95
	ds_write2_b32 v17, v100, v101 offset0:44 offset1:109
	ds_write2_b32 v17, v102, v103 offset0:174 offset1:239
	v_add_u32_e32 v17, 0x3000, v31
	v_mul_f32_e32 v15, v15, v96
	v_mul_f32_e32 v16, v16, v97
	v_mul_f32_e32 v11, v47, v11
	ds_write2_b32 v17, v0, v14 offset0:48 offset1:113
	ds_write2_b32 v17, v15, v16 offset0:178 offset1:243
	v_add_u32_e32 v0, 0x3400, v31
	v_mul_f32_e32 v12, v48, v12
	v_mul_f32_e32 v13, v49, v13
	v_mul_f32_e32 v7, v51, v7
	ds_write2_b32 v0, v10, v11 offset0:52 offset1:117
	ds_write2_b32 v0, v12, v13 offset0:182 offset1:247
	v_add_u32_e32 v0, 0x3800, v31
	v_mul_f32_e32 v8, v52, v8
	v_mul_f32_e32 v9, v53, v9
	v_mul_f32_e32 v3, v55, v3
	ds_write2_b32 v0, v6, v7 offset0:56 offset1:121
	ds_write2_b32 v0, v8, v9 offset0:186 offset1:251
	v_add_u32_e32 v0, 0x3c00, v31
	v_mul_f32_e32 v4, v56, v4
	v_mul_f32_e32 v5, v57, v5
	ds_write2_b32 v0, v2, v3 offset0:60 offset1:125
	ds_write2_b32 v0, v4, v5 offset0:190 offset1:255
	s_waitcnt lgkmcnt(0)
	v_add_u32_e32 v0, 0x400, v33
	ds_read2_b32 v[8:9], v33 offset0:65 offset1:73
	ds_read2_b32 v[10:11], v33 offset1:8
	ds_read2_b32 v[12:13], v33 offset0:130 offset1:138
	ds_read2_b32 v[14:15], v33 offset0:195 offset1:203
	ds_read2_b32 v[16:17], v0 offset0:4 offset1:12
	ds_read2_b32 v[48:49], v0 offset0:69 offset1:77
	ds_read2_b32 v[50:51], v0 offset0:134 offset1:142
	ds_read2_b32 v[52:53], v0 offset0:199 offset1:207
	v_add_u32_e32 v54, s1, v45
	v_ashrrev_i32_e32 v55, 31, v54
	v_lshl_add_u64 v[2:3], s[16:17], 1, v[18:19]
	v_lshlrev_b64 v[56:57], 11, v[54:55]
	s_waitcnt lgkmcnt(6)
; #define LAS __attribute__((address_space(3)))
; __device__ __forceinline__ unsigned pk2(float lo, float hi) { return pg8::cvt_pk_bf16(lo, hi); }
; template <int MODE>
; __device__ __forceinline__ void p0_item(const float* W, int K, int N, bf16u* WT, const float* ks, LAS float* scr, int item, int lane) {
;     ...
;     const int c = lane & 7;
; #pragma unroll
;     for (int j = 0; j < 8; ++j) { const int n = (lane >> 3) + 8 * j; const LAS float* s = scr + (8 * c) * 65 + n;
;         v4u o; o.x = pk2(s[0 * 65], s[1 * 65]); o.y = pk2(s[2 * 65], s[3 * 65]); o.z = pk2(s[4 * 65], s[5 * 65]); o.w = pk2(s[6 * 65], s[7 * 65]);
;         *(v4u*)(WT + (size_t)(drow + n) * K + k0 + 8 * c) = o; }
;     asm volatile("s_waitcnt lgkmcnt(0)" ::: "memory");
	v_cvt_pk_bf16_f32 v4, v10, v8
	s_waitcnt lgkmcnt(4)
	v_cvt_pk_bf16_f32 v5, v12, v14
	s_waitcnt lgkmcnt(2)
	v_cvt_pk_bf16_f32 v6, v16, v48
	s_waitcnt lgkmcnt(0)
	v_cvt_pk_bf16_f32 v7, v50, v52
	v_lshl_add_u64 v[56:57], v[2:3], 0, v[56:57]
	v_add_u32_e32 v8, 8, v54
	global_store_dwordx4 v[56:57], v[4:7], off sc1
	v_add_u32_e32 v56, 16, v54
	v_ashrrev_i32_e32 v57, 31, v56
	v_cvt_pk_bf16_f32 v4, v11, v9
	v_ashrrev_i32_e32 v9, 31, v8
	v_lshlrev_b64 v[8:9], 11, v[8:9]
	v_cvt_pk_bf16_f32 v5, v13, v15
	v_cvt_pk_bf16_f32 v6, v17, v49
	v_cvt_pk_bf16_f32 v7, v51, v53
	v_lshl_add_u64 v[8:9], v[2:3], 0, v[8:9]
	global_store_dwordx4 v[8:9], v[4:7], off sc1
	ds_read2_b32 v[8:9], v33 offset0:81 offset1:89
	ds_read2_b32 v[10:11], v33 offset0:16 offset1:24
	ds_read2_b32 v[12:13], v33 offset0:146 offset1:154
	ds_read2_b32 v[14:15], v33 offset0:211 offset1:219
	ds_read2_b32 v[16:17], v0 offset0:20 offset1:28
	ds_read2_b32 v[48:49], v0 offset0:85 offset1:93
	ds_read2_b32 v[50:51], v0 offset0:150 offset1:158
	ds_read2_b32 v[52:53], v0 offset0:215 offset1:223
	v_lshlrev_b64 v[56:57], 11, v[56:57]
	s_waitcnt lgkmcnt(6)
	v_cvt_pk_bf16_f32 v4, v10, v8
	s_waitcnt lgkmcnt(4)
	v_cvt_pk_bf16_f32 v5, v12, v14
	s_waitcnt lgkmcnt(2)
	v_cvt_pk_bf16_f32 v6, v16, v48
	s_waitcnt lgkmcnt(0)
	v_cvt_pk_bf16_f32 v7, v50, v52
	v_lshl_add_u64 v[56:57], v[2:3], 0, v[56:57]
	v_add_u32_e32 v8, 24, v54
	global_store_dwordx4 v[56:57], v[4:7], off sc1
	v_add_u32_e32 v56, 32, v54
	v_ashrrev_i32_e32 v57, 31, v56
	v_cvt_pk_bf16_f32 v4, v11, v9
	v_ashrrev_i32_e32 v9, 31, v8
	v_lshlrev_b64 v[8:9], 11, v[8:9]
	v_cvt_pk_bf16_f32 v5, v13, v15
	v_cvt_pk_bf16_f32 v6, v17, v49
	v_cvt_pk_bf16_f32 v7, v51, v53
	v_lshl_add_u64 v[8:9], v[2:3], 0, v[8:9]
	global_store_dwordx4 v[8:9], v[4:7], off sc1
	ds_read2_b32 v[8:9], v33 offset0:32 offset1:40
	ds_read2_b32 v[10:11], v33 offset0:97 offset1:105
	ds_read2_b32 v[12:13], v33 offset0:162 offset1:170
	ds_read2_b32 v[14:15], v33 offset0:227 offset1:235
	ds_read2_b32 v[16:17], v0 offset0:36 offset1:44
	ds_read2_b32 v[48:49], v0 offset0:101 offset1:109
	ds_read2_b32 v[50:51], v0 offset0:166 offset1:174
	ds_read2_b32 v[52:53], v0 offset0:231 offset1:239
	v_lshlrev_b64 v[56:57], 11, v[56:57]
	s_waitcnt lgkmcnt(6)
	v_cvt_pk_bf16_f32 v4, v8, v10
	s_waitcnt lgkmcnt(4)
	v_cvt_pk_bf16_f32 v5, v12, v14
	s_waitcnt lgkmcnt(2)
	v_cvt_pk_bf16_f32 v6, v16, v48
	s_waitcnt lgkmcnt(0)
	v_cvt_pk_bf16_f32 v7, v50, v52
	v_lshl_add_u64 v[56:57], v[2:3], 0, v[56:57]
	v_add_u32_e32 v8, 40, v54
	global_store_dwordx4 v[56:57], v[4:7], off sc1
	v_add_u32_e32 v56, 48, v54
	v_ashrrev_i32_e32 v57, 31, v56
	v_cvt_pk_bf16_f32 v4, v9, v11
	v_ashrrev_i32_e32 v9, 31, v8
	v_lshlrev_b64 v[8:9], 11, v[8:9]
	v_cvt_pk_bf16_f32 v5, v13, v15
	v_cvt_pk_bf16_f32 v6, v17, v49
	v_cvt_pk_bf16_f32 v7, v51, v53
	v_lshl_add_u64 v[8:9], v[2:3], 0, v[8:9]
	global_store_dwordx4 v[8:9], v[4:7], off sc1
	ds_read2_b32 v[8:9], v33 offset0:48 offset1:56
	ds_read2_b32 v[10:11], v33 offset0:113 offset1:121
	ds_read2_b32 v[12:13], v33 offset0:178 offset1:186
	ds_read2_b32 v[14:15], v33 offset0:243 offset1:251
	ds_read2_b32 v[16:17], v0 offset0:52 offset1:60
	ds_read2_b32 v[48:49], v0 offset0:117 offset1:125
	ds_read2_b32 v[50:51], v0 offset0:182 offset1:190
	ds_read2_b32 v[52:53], v0 offset0:247 offset1:255
	v_lshlrev_b64 v[56:57], 11, v[56:57]
	s_waitcnt lgkmcnt(6)
	v_cvt_pk_bf16_f32 v4, v8, v10
	s_waitcnt lgkmcnt(4)
	v_cvt_pk_bf16_f32 v5, v12, v14
	s_waitcnt lgkmcnt(2)
	v_cvt_pk_bf16_f32 v6, v16, v48
	s_waitcnt lgkmcnt(0)
	v_cvt_pk_bf16_f32 v7, v50, v52
	v_lshl_add_u64 v[56:57], v[2:3], 0, v[56:57]
	v_add_u32_e32 v8, 56, v54
	global_store_dwordx4 v[56:57], v[4:7], off sc1
	s_nop 1
	v_cvt_pk_bf16_f32 v4, v9, v11
	v_ashrrev_i32_e32 v9, 31, v8
	v_lshlrev_b64 v[8:9], 11, v[8:9]
	v_cvt_pk_bf16_f32 v5, v13, v15
	v_cvt_pk_bf16_f32 v6, v17, v49
	v_cvt_pk_bf16_f32 v7, v51, v53
	v_lshl_add_u64 v[2:3], v[2:3], 0, v[8:9]
	global_store_dwordx4 v[2:3], v[4:7], off sc1
	s_waitcnt lgkmcnt(0)

; template <int MODE>
; __device__ __forceinline__ void p0_item(const float* W, int K, int N, bf16u* WT, const float* ks, LAS float* scr, int item, int lane) {
;     ...
;     const float* src = W + (size_t)k0 * N + nn;
;     float v[64];
; #pragma unroll
;     for (int kk = 0; kk < 64; ++kk) v[kk] = src[(size_t)kk * N];
.LBB0_599:
	s_add_i32 s1, s55, 0xdc0
	s_cmpk_gt_i32 s1, 0x7ff
	s_mov_b64 s[16:17], -1
	s_cbranch_scc0 .LBB0_621
	s_cmpk_gt_u32 s1, 0x8ff
	s_cbranch_scc0 .LBB0_618
	s_cmpk_gt_u32 s1, 0x9ff
	s_cbranch_scc0 .LBB0_615
	s_cmpk_gt_u32 s1, 0xaff
	s_cbranch_scc0 .LBB0_612
	s_cmpk_gt_u32 s1, 0xdbf
	s_cbranch_scc0 .LBB0_609
	s_cmpk_gt_u32 s1, 0x107f
	s_cbranch_scc0 .LBB0_606
	s_add_i32 s4, s53, 0xffffbe00
	s_and_b32 s12, s4, 0xfc0
	s_add_i32 s4, s52, s59
	s_add_i32 s4, s4, 0xfffbe000
	s_and_b32 s4, s4, 0x3c0
	s_lshl_b32 s16, s12, 12
	v_or_b32_e32 v0, s4, v30
	s_add_u32 s16, s13, s16
	s_addc_u32 s17, s34, 0
	v_lshlrev_b32_e32 v0, 2, v0
	v_lshl_add_u64 v[2:3], s[16:17], 0, v[0:1]
	v_add_co_u32_e32 v4, vcc, s61, v2
	global_load_dword v0, v0, s[16:17]
	s_nop 0
	v_addc_co_u32_e32 v5, vcc, 0, v3, vcc
	s_movk_i32 s16, 0x4000
	global_load_dword v6, v[4:5], off offset:-4096
	global_load_dword v7, v[4:5], off
	v_add_co_u32_e32 v4, vcc, s16, v2
	s_movk_i32 s16, 0x6000
	s_nop 0
	v_addc_co_u32_e32 v5, vcc, 0, v3, vcc
	global_load_dword v8, v[4:5], off offset:-4096
	global_load_dword v9, v[4:5], off
	v_add_co_u32_e32 v4, vcc, s16, v2
	s_mov_b32 s16, 0xe000
	s_nop 0
	v_addc_co_u32_e32 v5, vcc, 0, v3, vcc
	global_load_dword v10, v[4:5], off offset:-4096
	global_load_dword v11, v[4:5], off
	v_add_co_u32_e32 v4, vcc, s88, v2
	s_lshl_b32 s90, s12, 1
	s_nop 0
	v_addc_co_u32_e32 v5, vcc, 0, v3, vcc
	global_load_dword v12, v[4:5], off offset:-4096
	global_load_dword v13, v[4:5], off
	v_add_co_u32_e32 v4, vcc, s27, v2
	s_nop 1
	v_addc_co_u32_e32 v5, vcc, 0, v3, vcc
	global_load_dword v14, v[4:5], off offset:-4096
	global_load_dword v15, v[4:5], off
	v_add_co_u32_e32 v4, vcc, s26, v2
	s_nop 1
	v_addc_co_u32_e32 v5, vcc, 0, v3, vcc
	global_load_dword v16, v[4:5], off offset:-4096
	global_load_dword v17, v[4:5], off
	v_add_co_u32_e32 v4, vcc, s16, v2
	s_mov_b32 s16, 0x10000
	s_nop 0
	v_addc_co_u32_e32 v5, vcc, 0, v3, vcc
	global_load_dword v47, v[4:5], off offset:-4096
	global_load_dword v48, v[4:5], off
	v_add_co_u32_e32 v4, vcc, s16, v2
	s_mov_b32 s16, 0x14000
	s_nop 0
	v_addc_co_u32_e32 v5, vcc, 0, v3, vcc
	global_load_dword v49, v[4:5], off offset:-4096
	global_load_dword v50, v[4:5], off
	v_add_co_u32_e32 v4, vcc, s22, v2
	s_nop 1
	v_addc_co_u32_e32 v5, vcc, 0, v3, vcc
	global_load_dword v51, v[4:5], off offset:-4096
	global_load_dword v52, v[4:5], off
	v_add_co_u32_e32 v4, vcc, s16, v2
	s_mov_b32 s16, 0x16000
	s_nop 0
	v_addc_co_u32_e32 v5, vcc, 0, v3, vcc
	global_load_dword v53, v[4:5], off offset:-4096
	global_load_dword v54, v[4:5], off
	v_add_co_u32_e32 v4, vcc, s16, v2
	s_mov_b32 s16, 0x1a000
	s_nop 0
	v_addc_co_u32_e32 v5, vcc, 0, v3, vcc
	global_load_dword v55, v[4:5], off offset:-4096
	global_load_dword v56, v[4:5], off
	v_add_co_u32_e32 v4, vcc, s5, v2
	s_nop 1
	v_addc_co_u32_e32 v5, vcc, 0, v3, vcc
	global_load_dword v57, v[4:5], off offset:-4096
	global_load_dword v58, v[4:5], off
	v_add_co_u32_e32 v4, vcc, s16, v2
	s_mov_b32 s16, 0x1c000
	s_nop 0
	v_addc_co_u32_e32 v5, vcc, 0, v3, vcc
	global_load_dword v59, v[4:5], off offset:-4096
	global_load_dword v60, v[4:5], off
	v_add_co_u32_e32 v4, vcc, s16, v2
	s_mov_b32 s16, 0x1e000
	s_nop 0
	v_addc_co_u32_e32 v5, vcc, 0, v3, vcc
	global_load_dword v61, v[4:5], off offset:-4096
	global_load_dword v62, v[4:5], off
	v_add_co_u32_e32 v4, vcc, s16, v2
	s_mov_b32 s16, 0x20000
	s_nop 0
	v_addc_co_u32_e32 v5, vcc, 0, v3, vcc
	global_load_dword v63, v[4:5], off offset:-4096
	global_load_dword v64, v[4:5], off
	v_add_co_u32_e32 v4, vcc, s16, v2
	s_mov_b32 s16, 0x22000
	s_nop 0
	v_addc_co_u32_e32 v5, vcc, 0, v3, vcc
	global_load_dword v65, v[4:5], off offset:-4096
	global_load_dword v66, v[4:5], off
	v_add_co_u32_e32 v4, vcc, s16, v2
	s_mov_b32 s16, 0x24000
	s_nop 0
	v_addc_co_u32_e32 v5, vcc, 0, v3, vcc
	global_load_dword v67, v[4:5], off offset:-4096
	global_load_dword v68, v[4:5], off
	v_add_co_u32_e32 v4, vcc, s16, v2
	s_mov_b32 s16, 0x26000
	s_nop 0
	v_addc_co_u32_e32 v5, vcc, 0, v3, vcc
	global_load_dword v69, v[4:5], off offset:-4096
	global_load_dword v70, v[4:5], off
	v_add_co_u32_e32 v4, vcc, s16, v2
	s_mov_b32 s16, 0x28000
	s_nop 0
	v_addc_co_u32_e32 v5, vcc, 0, v3, vcc
	global_load_dword v71, v[4:5], off offset:-4096
	global_load_dword v72, v[4:5], off
	v_add_co_u32_e32 v4, vcc, s16, v2
	s_mov_b32 s16, 0x2a000
	s_nop 0
	v_addc_co_u32_e32 v5, vcc, 0, v3, vcc
	global_load_dword v73, v[4:5], off offset:-4096
	global_load_dword v74, v[4:5], off
	v_add_co_u32_e32 v4, vcc, s16, v2
	s_mov_b32 s16, 0x2c000
	s_nop 0
	v_addc_co_u32_e32 v5, vcc, 0, v3, vcc
	global_load_dword v75, v[4:5], off offset:-4096
	global_load_dword v76, v[4:5], off
	v_add_co_u32_e32 v4, vcc, s16, v2
	s_mov_b32 s16, 0x2e000
	s_nop 0
	v_addc_co_u32_e32 v5, vcc, 0, v3, vcc
	global_load_dword v77, v[4:5], off offset:-4096
	global_load_dword v78, v[4:5], off
	v_add_co_u32_e32 v4, vcc, s16, v2
	s_mov_b32 s16, 0x30000
	s_nop 0
	v_addc_co_u32_e32 v5, vcc, 0, v3, vcc
	global_load_dword v79, v[4:5], off offset:-4096
	global_load_dword v80, v[4:5], off
	v_add_co_u32_e32 v4, vcc, s16, v2
	s_mov_b32 s16, 0x32000
	s_nop 0
	v_addc_co_u32_e32 v5, vcc, 0, v3, vcc
	global_load_dword v81, v[4:5], off offset:-4096
	global_load_dword v82, v[4:5], off
	v_add_co_u32_e32 v4, vcc, s16, v2
	s_mov_b32 s16, 0x34000
	s_nop 0
	v_addc_co_u32_e32 v5, vcc, 0, v3, vcc
	global_load_dword v83, v[4:5], off offset:-4096
	global_load_dword v84, v[4:5], off
	v_add_co_u32_e32 v4, vcc, s16, v2
	s_mov_b32 s16, 0x36000
	s_nop 0
	v_addc_co_u32_e32 v5, vcc, 0, v3, vcc
	global_load_dword v85, v[4:5], off offset:-4096
	global_load_dword v86, v[4:5], off
	v_add_co_u32_e32 v4, vcc, s16, v2
	s_mov_b32 s16, 0x38000
	s_nop 0
	v_addc_co_u32_e32 v5, vcc, 0, v3, vcc
	global_load_dword v87, v[4:5], off offset:-4096
	global_load_dword v88, v[4:5], off
	v_add_co_u32_e32 v4, vcc, s16, v2
	s_mov_b32 s16, 0x3a000
	s_nop 0
	v_addc_co_u32_e32 v5, vcc, 0, v3, vcc
	global_load_dword v89, v[4:5], off offset:-4096
	global_load_dword v90, v[4:5], off
	v_add_co_u32_e32 v4, vcc, s16, v2
	s_mov_b32 s16, 0x3c000
	s_nop 0
	v_addc_co_u32_e32 v5, vcc, 0, v3, vcc
	global_load_dword v91, v[4:5], off offset:-4096
	global_load_dword v92, v[4:5], off
	v_add_co_u32_e32 v4, vcc, s16, v2
	s_mov_b32 s16, 0x3e000
	s_nop 0
	v_addc_co_u32_e32 v5, vcc, 0, v3, vcc
	global_load_dword v93, v[4:5], off offset:-4096
	global_load_dword v94, v[4:5], off
	v_add_co_u32_e32 v4, vcc, s16, v2
	s_mov_b32 s16, 0x3f000
	s_nop 0
	v_addc_co_u32_e32 v5, vcc, 0, v3, vcc
	v_add_co_u32_e32 v2, vcc, s16, v2
	global_load_dword v95, v[4:5], off offset:-4096
	s_nop 0
	global_load_dword v4, v[4:5], off
	v_addc_co_u32_e32 v3, vcc, 0, v3, vcc
	global_load_dword v2, v[2:3], off
	s_waitcnt vmcnt(0)
; #define LAS __attribute__((address_space(3)))
; __device__ __forceinline__ unsigned pk2(float lo, float hi) { return pg8::cvt_pk_bf16(lo, hi); }
; template <int MODE>
; __device__ __forceinline__ void p0_item(const float* W, int K, int N, bf16u* WT, const float* ks, LAS float* scr, int item, int lane) {
;     ...
;     for (int kk = 0; kk < 64; ++kk) scr[kk * 65 + lane] = v[kk];
;     asm volatile("s_waitcnt lgkmcnt(0)" ::: "memory");
;     const int c = lane & 7;
; #pragma unroll
;     for (int j = 0; j < 8; ++j) { const int n = (lane >> 3) + 8 * j; const LAS float* s = scr + (8 * c) * 65 + n;
;         v4u o; o.x = pk2(s[0 * 65], s[1 * 65]); o.y = pk2(s[2 * 65], s[3 * 65]); o.z = pk2(s[4 * 65], s[5 * 65]); o.w = pk2(s[6 * 65], s[7 * 65]);
;         *(v4u*)(WT + (size_t)(drow + n) * K + k0 + 8 * c) = o; }
;     asm volatile("s_waitcnt lgkmcnt(0)" ::: "memory");
	ds_write2_b32 v31, v0, v6 offset1:65
	ds_write2_b32 v31, v7, v8 offset0:130 offset1:195
	v_add_u32_e32 v0, 0x400, v31
	ds_write2_b32 v0, v9, v10 offset0:4 offset1:69
	ds_write2_b32 v0, v11, v12 offset0:134 offset1:199
	v_add_u32_e32 v0, 0x800, v31
	ds_write2_b32 v0, v13, v14 offset0:8 offset1:73
	ds_write2_b32 v0, v15, v16 offset0:138 offset1:203
	v_add_u32_e32 v0, 0xc00, v31
	ds_write2_b32 v0, v17, v47 offset0:12 offset1:77
	ds_write2_b32 v0, v48, v49 offset0:142 offset1:207
	v_add_u32_e32 v0, 0x1000, v31
	ds_write2_b32 v0, v50, v51 offset0:16 offset1:81
	ds_write2_b32 v0, v52, v53 offset0:146 offset1:211
	v_add_u32_e32 v0, 0x1400, v31
	ds_write2_b32 v0, v54, v55 offset0:20 offset1:85
	ds_write2_b32 v0, v56, v57 offset0:150 offset1:215
	v_add_u32_e32 v0, 0x1800, v31
	ds_write2_b32 v0, v58, v59 offset0:24 offset1:89
	ds_write2_b32 v0, v60, v61 offset0:154 offset1:219
	v_add_u32_e32 v0, 0x1c00, v31
	ds_write2_b32 v0, v62, v63 offset0:28 offset1:93
	ds_write2_b32 v0, v64, v65 offset0:158 offset1:223
	v_add_u32_e32 v0, 0x2000, v31
	ds_write2_b32 v0, v66, v67 offset0:32 offset1:97
	ds_write2_b32 v0, v68, v69 offset0:162 offset1:227
	v_add_u32_e32 v0, 0x2400, v31
	ds_write2_b32 v0, v70, v71 offset0:36 offset1:101
	ds_write2_b32 v0, v72, v73 offset0:166 offset1:231
	v_add_u32_e32 v0, 0x2800, v31
	ds_write2_b32 v0, v74, v75 offset0:40 offset1:105
	ds_write2_b32 v0, v76, v77 offset0:170 offset1:235
	v_add_u32_e32 v0, 0x2c00, v31
	ds_write2_b32 v0, v78, v79 offset0:44 offset1:109
	ds_write2_b32 v0, v80, v81 offset0:174 offset1:239
	v_add_u32_e32 v0, 0x3000, v31
	ds_write2_b32 v0, v82, v83 offset0:48 offset1:113
	ds_write2_b32 v0, v84, v85 offset0:178 offset1:243
	v_add_u32_e32 v0, 0x3400, v31
	ds_write2_b32 v0, v86, v87 offset0:52 offset1:117
	ds_write2_b32 v0, v88, v89 offset0:182 offset1:247
	v_add_u32_e32 v0, 0x3800, v31
	ds_write2_b32 v0, v90, v91 offset0:56 offset1:121
	ds_write2_b32 v0, v92, v93 offset0:186 offset1:251
	v_add_u32_e32 v0, 0x3c00, v31
	ds_write2_b32 v0, v94, v95 offset0:60 offset1:125
	ds_write2_b32 v0, v4, v2 offset0:190 offset1:255
	s_waitcnt lgkmcnt(0)
	v_add_u32_e32 v47, 0x400, v33
	ds_read2_b32 v[8:9], v33 offset0:65 offset1:73
	ds_read2_b32 v[10:11], v33 offset1:8
	ds_read2_b32 v[12:13], v33 offset0:130 offset1:138
	ds_read2_b32 v[14:15], v33 offset0:195 offset1:203
	ds_read2_b32 v[16:17], v47 offset0:4 offset1:12
	ds_read2_b32 v[48:49], v47 offset0:69 offset1:77
	ds_read2_b32 v[50:51], v47 offset0:134 offset1:142
	ds_read2_b32 v[52:53], v47 offset0:199 offset1:207
	v_or_b32_e32 v0, s4, v32
	v_mul_u32_u24_e32 v0, 0xb00, v0
	v_lshl_add_u64 v[2:3], v[20:21], 0, s[90:91]
	v_lshlrev_b32_e32 v0, 1, v0
	v_lshl_add_u64 v[54:55], v[2:3], 0, v[0:1]
	v_or_b32_e32 v0, s4, v34
	v_mul_u32_u24_e32 v0, 0xb00, v0
	s_waitcnt lgkmcnt(6)
	v_cvt_pk_bf16_f32 v4, v10, v8
	s_waitcnt lgkmcnt(4)
	v_cvt_pk_bf16_f32 v5, v12, v14
	s_waitcnt lgkmcnt(2)
	v_cvt_pk_bf16_f32 v6, v16, v48
	s_waitcnt lgkmcnt(0)
	v_cvt_pk_bf16_f32 v7, v50, v52
	v_lshlrev_b32_e32 v0, 1, v0
	global_store_dwordx4 v[54:55], v[4:7], off sc1
	s_mov_b64 s[16:17], 0
	s_nop 0
	v_cvt_pk_bf16_f32 v4, v11, v9
	v_cvt_pk_bf16_f32 v5, v13, v15
	v_cvt_pk_bf16_f32 v6, v17, v49
	v_cvt_pk_bf16_f32 v7, v51, v53
	v_lshl_add_u64 v[8:9], v[2:3], 0, v[0:1]
	global_store_dwordx4 v[8:9], v[4:7], off sc1
	ds_read2_b32 v[8:9], v33 offset0:16 offset1:24
	ds_read2_b32 v[10:11], v33 offset0:81 offset1:89
	ds_read2_b32 v[12:13], v33 offset0:146 offset1:154
	ds_read2_b32 v[14:15], v33 offset0:211 offset1:219
	ds_read2_b32 v[16:17], v47 offset0:20 offset1:28
	ds_read2_b32 v[48:49], v47 offset0:85 offset1:93
	ds_read2_b32 v[50:51], v47 offset0:150 offset1:158
	ds_read2_b32 v[52:53], v47 offset0:215 offset1:223
	v_or_b32_e32 v0, s4, v35
	v_mul_u32_u24_e32 v0, 0xb00, v0
	v_lshlrev_b32_e32 v0, 1, v0
	v_lshl_add_u64 v[54:55], v[2:3], 0, v[0:1]
	v_or_b32_e32 v0, s4, v36
	v_mul_u32_u24_e32 v0, 0xb00, v0
	s_waitcnt lgkmcnt(6)
	v_cvt_pk_bf16_f32 v4, v8, v10
	s_waitcnt lgkmcnt(4)
	v_cvt_pk_bf16_f32 v5, v12, v14
	s_waitcnt lgkmcnt(2)
	v_cvt_pk_bf16_f32 v6, v16, v48
	s_waitcnt lgkmcnt(0)
	v_cvt_pk_bf16_f32 v7, v50, v52
	v_lshlrev_b32_e32 v0, 1, v0
	global_store_dwordx4 v[54:55], v[4:7], off sc1
	s_nop 1
	v_cvt_pk_bf16_f32 v4, v9, v11
	v_cvt_pk_bf16_f32 v5, v13, v15
	v_cvt_pk_bf16_f32 v6, v17, v49
	v_cvt_pk_bf16_f32 v7, v51, v53
	v_lshl_add_u64 v[8:9], v[2:3], 0, v[0:1]
	global_store_dwordx4 v[8:9], v[4:7], off sc1
	ds_read2_b32 v[8:9], v33 offset0:32 offset1:40
	ds_read2_b32 v[10:11], v33 offset0:97 offset1:105
	ds_read2_b32 v[12:13], v33 offset0:162 offset1:170
	ds_read2_b32 v[14:15], v33 offset0:227 offset1:235
	ds_read2_b32 v[16:17], v47 offset0:36 offset1:44
	ds_read2_b32 v[48:49], v47 offset0:101 offset1:109
	ds_read2_b32 v[50:51], v47 offset0:166 offset1:174
	ds_read2_b32 v[52:53], v47 offset0:231 offset1:239
	v_or_b32_e32 v0, s4, v37
	v_mul_u32_u24_e32 v0, 0xb00, v0
	v_lshlrev_b32_e32 v0, 1, v0
	v_lshl_add_u64 v[54:55], v[2:3], 0, v[0:1]
	v_or_b32_e32 v0, s4, v38
	v_mul_u32_u24_e32 v0, 0xb00, v0
	s_waitcnt lgkmcnt(6)
	v_cvt_pk_bf16_f32 v4, v8, v10
	s_waitcnt lgkmcnt(4)
	v_cvt_pk_bf16_f32 v5, v12, v14
	s_waitcnt lgkmcnt(2)
	v_cvt_pk_bf16_f32 v6, v16, v48
	s_waitcnt lgkmcnt(0)
	v_cvt_pk_bf16_f32 v7, v50, v52
	v_lshlrev_b32_e32 v0, 1, v0
	global_store_dwordx4 v[54:55], v[4:7], off sc1
	s_nop 1
	v_cvt_pk_bf16_f32 v4, v9, v11
	v_cvt_pk_bf16_f32 v5, v13, v15
	v_cvt_pk_bf16_f32 v6, v17, v49
	v_cvt_pk_bf16_f32 v7, v51, v53
	v_lshl_add_u64 v[8:9], v[2:3], 0, v[0:1]
	global_store_dwordx4 v[8:9], v[4:7], off sc1
	ds_read2_b32 v[8:9], v33 offset0:48 offset1:56
	ds_read2_b32 v[10:11], v33 offset0:113 offset1:121
	ds_read2_b32 v[12:13], v33 offset0:178 offset1:186
	ds_read2_b32 v[14:15], v33 offset0:243 offset1:251
	ds_read2_b32 v[16:17], v47 offset0:52 offset1:60
	ds_read2_b32 v[48:49], v47 offset0:117 offset1:125
	ds_read2_b32 v[50:51], v47 offset0:182 offset1:190
	ds_read2_b32 v[52:53], v47 offset0:247 offset1:255
	v_or_b32_e32 v0, s4, v39
	v_mul_u32_u24_e32 v0, 0xb00, v0
	v_lshlrev_b32_e32 v0, 1, v0
	v_lshl_add_u64 v[54:55], v[2:3], 0, v[0:1]
	v_or_b32_e32 v0, s4, v40
	v_mul_u32_u24_e32 v0, 0xb00, v0
	s_waitcnt lgkmcnt(6)
	v_cvt_pk_bf16_f32 v4, v8, v10
	s_waitcnt lgkmcnt(4)
	v_cvt_pk_bf16_f32 v5, v12, v14
	s_waitcnt lgkmcnt(2)
	v_cvt_pk_bf16_f32 v6, v16, v48
	s_waitcnt lgkmcnt(0)
	v_cvt_pk_bf16_f32 v7, v50, v52
	v_lshlrev_b32_e32 v0, 1, v0
	global_store_dwordx4 v[54:55], v[4:7], off sc1
	v_lshl_add_u64 v[2:3], v[2:3], 0, v[0:1]
	s_nop 0
	v_cvt_pk_bf16_f32 v4, v9, v11
	v_cvt_pk_bf16_f32 v5, v13, v15
	v_cvt_pk_bf16_f32 v6, v17, v49
	v_cvt_pk_bf16_f32 v7, v51, v53
	global_store_dwordx4 v[2:3], v[4:7], off sc1
	s_waitcnt lgkmcnt(0)
; template <int MODE>
; __device__ __forceinline__ void p0_item(const float* W, int K, int N, bf16u* WT, const float* ks, LAS float* scr, int item, int lane) {
;     const int nblk = N / 64, kb = item / nblk, nb = item - kb * nblk, k0 = 64 * kb, n0 = 64 * nb;
;     int nn = n0 + lane;
;     if (MODE == 1) {
;         if (nn < 2048) { const int p = nn & 63; if (p < 16) nn = (nn & ~15) | (p & 3) | ((p & 4) << 1) | ((p & 8) >> 1); }
;         else if (nn >= 4096) { const int sec = nn >= 6144 ? 6144 : 4096, r = nn - sec, q = r & 255; nn = sec + ((q >> 7) << 10) + 128 * (r >> 8) + (q & 127); }
;     }
;     int drow = n0;
;     if (MODE == 2) drow = 256 * (n0 >> 7) + (n0 & 127);
;     if (MODE == 3) drow = 256 * (n0 >> 7) + 128 + (n0 & 127);
;     const float* src = W + (size_t)k0 * N + nn;
;     float v[64];
; #pragma unroll
;     for (int kk = 0; kk < 64; ++kk) v[kk] = src[(size_t)kk * N];
.LBB0_606:
	s_andn2_b64 vcc, exec, s[16:17]
	s_cbranch_vccnz .LBB0_608
	s_and_b32 s4, s55, 0xffff
	s_mul_hi_u32 s12, s4, 0x5d1745e
	s_mul_i32 s16, s12, 0xb00
	s_sub_i32 s17, s58, s16
	s_and_b32 s17, s17, 64
	s_mul_i32 s4, s4, 0xba2f
	v_add_u32_e32 v0, s17, v41
	s_mulk_i32 s12, 0x1600
	s_lshr_b32 s4, s4, 21
	v_subrev_u32_e32 v0, s12, v0
	v_subrev_u32_e32 v2, s16, v42
	s_mul_i32 s12, s4, 0xb0000
	v_add_u32_e32 v2, s59, v2
	s_add_u32 s16, s35, s12
	s_addc_u32 s17, s36, 0
	v_ashrrev_i32_e32 v3, 31, v2
	v_lshl_add_u64 v[2:3], v[2:3], 2, s[16:17]
	v_add_co_u32_e32 v6, vcc, s61, v2
	s_movk_i32 s12, 0x5000
	s_nop 0
	v_addc_co_u32_e32 v7, vcc, 0, v3, vcc
	global_load_dword v5, v[6:7], off offset:3072
	v_add_co_u32_e32 v6, vcc, s12, v2
	s_mov_b32 s12, 0xb000
	s_nop 0
	v_addc_co_u32_e32 v7, vcc, 0, v3, vcc
	v_add_co_u32_e32 v8, vcc, s88, v2
	global_load_dword v4, v[2:3], off
	s_nop 0
	v_addc_co_u32_e32 v9, vcc, 0, v3, vcc
	global_load_dword v6, v[6:7], off offset:2048
	s_lshl_b32 s90, s4, 7
	global_load_dword v7, v[8:9], off offset:1024
	v_add_co_u32_e32 v8, vcc, s12, v2
	s_mov_b32 s12, 0xd000
	s_nop 0
	v_addc_co_u32_e32 v9, vcc, 0, v3, vcc
	v_add_co_u32_e32 v10, vcc, s12, v2
	s_mov_b32 s12, 0x10000
	s_nop 0
	v_addc_co_u32_e32 v11, vcc, 0, v3, vcc
	global_load_dword v8, v[8:9], off
	s_nop 0
	global_load_dword v9, v[10:11], off offset:3072
	v_add_co_u32_e32 v10, vcc, s12, v2
	s_mov_b32 s12, 0x13000
	s_nop 0
	v_addc_co_u32_e32 v11, vcc, 0, v3, vcc
	v_add_co_u32_e32 v12, vcc, s12, v2
	s_mov_b32 s12, 0x16000
	s_nop 0
	v_addc_co_u32_e32 v13, vcc, 0, v3, vcc
	global_load_dword v16, v[12:13], off offset:1024
	v_add_co_u32_e32 v12, vcc, s12, v2
	global_load_dword v11, v[10:11], off offset:2048
	s_nop 0
	v_addc_co_u32_e32 v13, vcc, 0, v3, vcc
	global_load_dword v63, v[12:13], off
	v_add_co_u32_e32 v12, vcc, s5, v2
	s_mov_b32 s12, 0x1b000
	s_nop 0
	v_addc_co_u32_e32 v13, vcc, 0, v3, vcc
	global_load_dword v65, v[12:13], off offset:3072
	v_add_co_u32_e32 v12, vcc, s12, v2
	s_mov_b32 s12, 0x1e000
	s_nop 0
	v_addc_co_u32_e32 v13, vcc, 0, v3, vcc
	global_load_dword v67, v[12:13], off offset:2048
	v_add_co_u32_e32 v12, vcc, s12, v2
	s_mov_b32 s12, 0x21000
	s_nop 0
	v_addc_co_u32_e32 v13, vcc, 0, v3, vcc
	global_load_dword v69, v[12:13], off offset:1024
	v_add_co_u32_e32 v12, vcc, s12, v2
	s_mov_b32 s12, 0x23000
	s_nop 0
	v_addc_co_u32_e32 v13, vcc, 0, v3, vcc
	global_load_dword v72, v[12:13], off
	v_add_co_u32_e32 v12, vcc, s12, v2
	s_mov_b32 s12, 0x26000
	s_nop 0
	v_addc_co_u32_e32 v13, vcc, 0, v3, vcc
	global_load_dword v81, v[12:13], off offset:3072
	v_add_co_u32_e32 v12, vcc, s12, v2
	s_mov_b32 s12, 0x29000
	s_nop 0
	v_addc_co_u32_e32 v13, vcc, 0, v3, vcc
	global_load_dword v83, v[12:13], off offset:2048
	v_add_co_u32_e32 v12, vcc, s12, v2
	s_mov_b32 s12, 0x2c000
	s_nop 0
	v_addc_co_u32_e32 v13, vcc, 0, v3, vcc
	global_load_dword v93, v[12:13], off offset:1024
	v_add_co_u32_e32 v12, vcc, s12, v2
	s_mov_b32 s12, 0x2e000
	s_nop 0
	v_addc_co_u32_e32 v13, vcc, 0, v3, vcc
	global_load_dword v10, v[12:13], off
	v_add_co_u32_e32 v12, vcc, s12, v2
	s_mov_b32 s12, 0x31000
	s_nop 0
	v_addc_co_u32_e32 v13, vcc, 0, v3, vcc
	v_add_co_u32_e32 v14, vcc, s12, v2
	s_mov_b32 s12, 0x34000
	s_nop 0
	v_addc_co_u32_e32 v15, vcc, 0, v3, vcc
	global_load_dword v12, v[12:13], off offset:3072
	s_nop 0
	global_load_dword v13, v[14:15], off offset:2048
	v_add_co_u32_e32 v14, vcc, s12, v2
	s_mov_b32 s12, 0x37000
	s_nop 0
	v_addc_co_u32_e32 v15, vcc, 0, v3, vcc
	v_add_co_u32_e32 v48, vcc, s12, v2
	s_mov_b32 s12, 0x39000
	s_nop 0
	v_addc_co_u32_e32 v49, vcc, 0, v3, vcc
	global_load_dword v14, v[14:15], off offset:1024
	s_nop 0
	global_load_dword v15, v[48:49], off
	v_add_co_u32_e32 v48, vcc, s12, v2
	s_mov_b32 s12, 0x3c000
	s_nop 0
	v_addc_co_u32_e32 v49, vcc, 0, v3, vcc
	global_load_dword v17, v[48:49], off offset:3072
	v_add_co_u32_e32 v48, vcc, s12, v2
	s_mov_b32 s12, 0x3f000
	s_nop 0
	v_addc_co_u32_e32 v49, vcc, 0, v3, vcc
	global_load_dword v64, v[48:49], off offset:2048
	v_add_co_u32_e32 v48, vcc, s12, v2
	s_mov_b32 s12, 0x42000
	s_nop 0
	v_addc_co_u32_e32 v49, vcc, 0, v3, vcc
	global_load_dword v84, v[48:49], off offset:1024
	v_add_co_u32_e32 v48, vcc, s12, v2
	s_mov_b32 s12, 0x44000
	s_nop 0
	v_addc_co_u32_e32 v49, vcc, 0, v3, vcc
	global_load_dword v85, v[48:49], off
	v_add_co_u32_e32 v48, vcc, s12, v2
	s_mov_b32 s12, 0x47000
	s_nop 0
	v_addc_co_u32_e32 v49, vcc, 0, v3, vcc
	global_load_dword v87, v[48:49], off offset:3072
	v_add_co_u32_e32 v48, vcc, s12, v2
	s_mov_b32 s12, 0x4a000
	s_nop 0
	v_addc_co_u32_e32 v49, vcc, 0, v3, vcc
	global_load_dword v89, v[48:49], off offset:2048
	v_add_co_u32_e32 v48, vcc, s12, v2
	s_mov_b32 s12, 0x4d000
	s_nop 0
	v_addc_co_u32_e32 v49, vcc, 0, v3, vcc
	global_load_dword v91, v[48:49], off offset:1024
	v_add_co_u32_e32 v48, vcc, s12, v2
	s_mov_b32 s12, 0x4f000
	s_nop 0
	v_addc_co_u32_e32 v49, vcc, 0, v3, vcc
	global_load_dword v92, v[48:49], off
	v_add_co_u32_e32 v48, vcc, s12, v2
	s_mov_b32 s12, 0x52000
	s_nop 0
	v_addc_co_u32_e32 v49, vcc, 0, v3, vcc
	global_load_dword v94, v[48:49], off offset:3072
	v_add_co_u32_e32 v48, vcc, s12, v2
	s_mov_b32 s12, 0x55000
	s_nop 0
	v_addc_co_u32_e32 v49, vcc, 0, v3, vcc
	global_load_dword v95, v[48:49], off offset:2048
	v_add_co_u32_e32 v48, vcc, s12, v2
	s_mov_b32 s12, 0x58000
	s_nop 0
	v_addc_co_u32_e32 v49, vcc, 0, v3, vcc
	global_load_dword v101, v[48:49], off offset:1024
	v_add_co_u32_e32 v48, vcc, s12, v2
	s_mov_b32 s12, 0x5a000
	s_nop 0
	v_addc_co_u32_e32 v49, vcc, 0, v3, vcc
	global_load_dword v66, v[48:49], off
	v_add_co_u32_e32 v48, vcc, s12, v2
	s_mov_b32 s12, 0x5d000
	s_nop 0
; template <int MODE>
; __device__ __forceinline__ void p0_item(const float* W, int K, int N, bf16u* WT, const float* ks, LAS float* scr, int item, int lane) {
;     ...
;     const float* src = W + (size_t)k0 * N + nn;
;     float v[64];
; #pragma unroll
;     for (int kk = 0; kk < 64; ++kk) v[kk] = src[(size_t)kk * N];
;     if (ks) {
; #pragma unroll
;         for (int kk = 0; kk < 64; ++kk) v[kk] *= ks[k0 + kk];
	v_addc_co_u32_e32 v49, vcc, 0, v3, vcc
	global_load_dword v68, v[48:49], off offset:3072
	v_add_co_u32_e32 v48, vcc, s12, v2
	s_mov_b32 s12, 0x60000
	s_nop 0
	v_addc_co_u32_e32 v49, vcc, 0, v3, vcc
	global_load_dword v70, v[48:49], off offset:2048
	v_add_co_u32_e32 v48, vcc, s12, v2
	s_mov_b32 s12, 0x63000
	s_nop 0
	v_addc_co_u32_e32 v49, vcc, 0, v3, vcc
	global_load_dword v82, v[48:49], off offset:1024
	v_add_co_u32_e32 v48, vcc, s12, v2
	s_mov_b32 s12, 0x65000
	s_nop 0
	v_addc_co_u32_e32 v49, vcc, 0, v3, vcc
	global_load_dword v86, v[48:49], off
	v_add_co_u32_e32 v48, vcc, s12, v2
	s_mov_b32 s12, 0x68000
	s_nop 0
	v_addc_co_u32_e32 v49, vcc, 0, v3, vcc
	global_load_dword v88, v[48:49], off offset:3072
	v_add_co_u32_e32 v48, vcc, s12, v2
	s_mov_b32 s12, 0x6b000
	s_nop 0
	v_addc_co_u32_e32 v49, vcc, 0, v3, vcc
	global_load_dword v90, v[48:49], off offset:2048
	v_add_co_u32_e32 v48, vcc, s12, v2
	s_mov_b32 s12, 0x6e000
	s_nop 0
	v_addc_co_u32_e32 v49, vcc, 0, v3, vcc
	global_load_dword v96, v[48:49], off offset:1024
	v_add_co_u32_e32 v48, vcc, s12, v2
	s_mov_b32 s12, 0x70000
	s_nop 0
	v_addc_co_u32_e32 v49, vcc, 0, v3, vcc
	global_load_dword v97, v[48:49], off
	v_add_co_u32_e32 v48, vcc, s12, v2
	s_mov_b32 s12, 0x73000
	s_nop 0
	v_addc_co_u32_e32 v49, vcc, 0, v3, vcc
	global_load_dword v98, v[48:49], off offset:3072
	v_add_co_u32_e32 v48, vcc, s12, v2
	s_mov_b32 s12, 0x76000
	s_nop 0
	v_addc_co_u32_e32 v49, vcc, 0, v3, vcc
	global_load_dword v99, v[48:49], off offset:2048
	v_add_co_u32_e32 v48, vcc, s12, v2
	s_mov_b32 s12, 0x79000
	s_nop 0
	v_addc_co_u32_e32 v49, vcc, 0, v3, vcc
	global_load_dword v100, v[48:49], off offset:1024
	v_add_co_u32_e32 v48, vcc, s12, v2
	s_mov_b32 s12, 0x7b000
	s_nop 0
	v_addc_co_u32_e32 v49, vcc, 0, v3, vcc
	global_load_dword v102, v[48:49], off
	v_add_co_u32_e32 v48, vcc, s12, v2
	s_mov_b32 s12, 0x7e000
	s_nop 0
	v_addc_co_u32_e32 v49, vcc, 0, v3, vcc
	global_load_dword v103, v[48:49], off offset:3072
	v_add_co_u32_e32 v48, vcc, s12, v2
	s_mov_b32 s12, 0x81000
	s_nop 0
	v_addc_co_u32_e32 v49, vcc, 0, v3, vcc
	global_load_dword v104, v[48:49], off offset:2048
	v_add_co_u32_e32 v48, vcc, s12, v2
	s_mov_b32 s12, 0x84000
	s_nop 0
	v_addc_co_u32_e32 v49, vcc, 0, v3, vcc
	global_load_dword v111, v[48:49], off offset:1024
	v_add_co_u32_e32 v48, vcc, s12, v2
	s_mov_b32 s12, 0x86000
	s_nop 0
	v_addc_co_u32_e32 v49, vcc, 0, v3, vcc
	global_load_dword v47, v[48:49], off
	v_add_co_u32_e32 v48, vcc, s12, v2
	s_mov_b32 s12, 0x89000
	s_nop 0
	v_addc_co_u32_e32 v49, vcc, 0, v3, vcc
	v_add_co_u32_e32 v50, vcc, s12, v2
	s_mov_b32 s12, 0x8c000
	s_nop 0
	v_addc_co_u32_e32 v51, vcc, 0, v3, vcc
	global_load_dword v48, v[48:49], off offset:3072
	s_nop 0
	global_load_dword v49, v[50:51], off offset:2048
	v_add_co_u32_e32 v50, vcc, s12, v2
	s_mov_b32 s12, 0x8f000
	s_nop 0
	v_addc_co_u32_e32 v51, vcc, 0, v3, vcc
	v_add_co_u32_e32 v52, vcc, s12, v2
	s_mov_b32 s12, 0x91000
	s_nop 0
	v_addc_co_u32_e32 v53, vcc, 0, v3, vcc
	global_load_dword v50, v[50:51], off offset:1024
	s_nop 0
	global_load_dword v51, v[52:53], off
	v_add_co_u32_e32 v52, vcc, s12, v2
	s_mov_b32 s12, 0x94000
	s_nop 0
	v_addc_co_u32_e32 v53, vcc, 0, v3, vcc
	v_add_co_u32_e32 v54, vcc, s12, v2
	s_mov_b32 s12, 0x97000
	s_nop 0
	v_addc_co_u32_e32 v55, vcc, 0, v3, vcc
	global_load_dword v52, v[52:53], off offset:3072
	s_nop 0
	global_load_dword v53, v[54:55], off offset:2048
	v_add_co_u32_e32 v54, vcc, s12, v2
	s_mov_b32 s12, 0x9a000
	s_nop 0
	v_addc_co_u32_e32 v55, vcc, 0, v3, vcc
	v_add_co_u32_e32 v56, vcc, s12, v2
	s_mov_b32 s12, 0x9c000
	s_nop 0
	v_addc_co_u32_e32 v57, vcc, 0, v3, vcc
	global_load_dword v54, v[54:55], off offset:1024
	s_nop 0
	global_load_dword v55, v[56:57], off
	v_add_co_u32_e32 v56, vcc, s12, v2
	s_mov_b32 s12, 0x9f000
	s_nop 0
	v_addc_co_u32_e32 v57, vcc, 0, v3, vcc
	v_add_co_u32_e32 v58, vcc, s12, v2
	s_mov_b32 s12, 0xa2000
	s_nop 0
	v_addc_co_u32_e32 v59, vcc, 0, v3, vcc
	global_load_dword v56, v[56:57], off offset:3072
	s_nop 0
	global_load_dword v57, v[58:59], off offset:2048
	v_add_co_u32_e32 v58, vcc, s12, v2
	s_mov_b32 s12, 0xa5000
	s_nop 0
	v_addc_co_u32_e32 v59, vcc, 0, v3, vcc
	v_add_co_u32_e32 v60, vcc, s12, v2
	s_mov_b32 s12, 0xa7000
	s_nop 0
	v_addc_co_u32_e32 v61, vcc, 0, v3, vcc
	global_load_dword v58, v[58:59], off offset:1024
	s_nop 0
	global_load_dword v59, v[60:61], off
	v_add_co_u32_e32 v60, vcc, s12, v2
	s_mov_b32 s12, 0xaa000
	s_nop 0
	v_addc_co_u32_e32 v61, vcc, 0, v3, vcc
	v_add_co_u32_e32 v74, vcc, s12, v2
	s_mov_b32 s12, 0xad000
	s_nop 0
	v_addc_co_u32_e32 v75, vcc, 0, v3, vcc
	v_add_co_u32_e32 v2, vcc, s12, v2
	s_lshl_b32 s12, s4, 8
	s_nop 0
	v_addc_co_u32_e32 v3, vcc, 0, v3, vcc
	v_mov_b32_e32 v120, s12
	global_load_dword v60, v[60:61], off offset:3072
	s_nop 0
	global_load_dword v62, v[2:3], off offset:1024
	global_load_dword v61, v[74:75], off offset:2048
	global_load_dwordx4 v[106:109], v120, s[18:19] offset:48
	global_load_dwordx4 v[112:115], v120, s[18:19] offset:32
	global_load_dwordx4 v[116:119], v120, s[18:19] offset:16
	s_nop 0
	global_load_dwordx4 v[74:77], v120, s[18:19]
	s_waitcnt vmcnt(0)
	v_mul_f32_e32 v63, v63, v112
	v_mul_f32_e32 v65, v65, v113
	v_mul_f32_e32 v71, v4, v74
	v_mul_f32_e32 v73, v5, v75
	v_mul_f32_e32 v74, v6, v76
	v_mul_f32_e32 v76, v7, v77
	v_mul_f32_e32 v75, v8, v116
	v_mul_f32_e32 v77, v9, v117
	v_mul_f32_e32 v67, v67, v114
	v_mul_f32_e32 v80, v69, v115
	v_mul_f32_e32 v69, v72, v106
	v_mul_f32_e32 v72, v81, v107
	v_mul_f32_e32 v81, v83, v108
	v_mul_f32_e32 v83, v93, v109
	global_load_dwordx4 v[2:5], v120, s[18:19] offset:112
	global_load_dwordx4 v[6:9], v120, s[18:19] offset:96
	global_load_dwordx4 v[112:115], v120, s[18:19] offset:80
	global_load_dwordx4 v[106:109], v120, s[18:19] offset:64
	v_mul_f32_e32 v78, v11, v118
	v_mul_f32_e32 v79, v16, v119
	s_waitcnt vmcnt(2)
; template <int MODE>
; __device__ __forceinline__ void p0_item(const float* W, int K, int N, bf16u* WT, const float* ks, LAS float* scr, int item, int lane) {
;     ...
;         for (int kk = 0; kk < 64; ++kk) v[kk] *= ks[k0 + kk];
;     }
; #pragma unroll
;     for (int kk = 0; kk < 64; ++kk) scr[kk * 65 + lane] = v[kk];
;     asm volatile("s_waitcnt lgkmcnt(0)" ::: "memory");
	v_mul_f32_e32 v91, v91, v9
	s_waitcnt vmcnt(1)
	v_mul_f32_e32 v110, v84, v115
	s_waitcnt vmcnt(0)
	v_mul_f32_e32 v93, v10, v106
	v_mul_f32_e32 v105, v12, v107
	v_mul_f32_e32 v106, v13, v108
	v_mul_f32_e32 v108, v14, v109
	v_mul_f32_e32 v107, v15, v112
	v_mul_f32_e32 v109, v17, v113
	v_mul_f32_e32 v84, v85, v6
	v_mul_f32_e32 v85, v87, v7
	v_mul_f32_e32 v87, v89, v8
	v_mul_f32_e32 v89, v92, v2
	v_mul_f32_e32 v92, v94, v3
	v_mul_f32_e32 v94, v95, v4
	v_mul_f32_e32 v95, v101, v5
	global_load_dwordx4 v[2:5], v120, s[18:19] offset:176
	global_load_dwordx4 v[6:9], v120, s[18:19] offset:160
	global_load_dwordx4 v[10:13], v120, s[18:19] offset:144
	global_load_dwordx4 v[14:17], v120, s[18:19] offset:128
	v_mul_f32_e32 v64, v64, v114
	s_waitcnt vmcnt(3)
	v_mul_f32_e32 v101, v102, v2
	s_waitcnt vmcnt(2)
	v_mul_f32_e32 v97, v97, v6
	s_waitcnt vmcnt(1)
	v_mul_f32_e32 v86, v86, v10
	s_waitcnt vmcnt(0)
	v_mul_f32_e32 v66, v66, v14
	v_mul_f32_e32 v68, v68, v15
	v_mul_f32_e32 v70, v70, v16
	v_mul_f32_e32 v82, v82, v17
	v_mul_f32_e32 v88, v88, v11
	v_mul_f32_e32 v90, v90, v12
	v_mul_f32_e32 v96, v96, v13
	v_mul_f32_e32 v98, v98, v7
	v_mul_f32_e32 v99, v99, v8
	v_mul_f32_e32 v100, v100, v9
	v_mul_f32_e32 v102, v103, v3
	v_mul_f32_e32 v103, v104, v4
	v_mul_f32_e32 v104, v111, v5
	global_load_dwordx4 v[2:5], v120, s[18:19] offset:240
	global_load_dwordx4 v[6:9], v120, s[18:19] offset:224
	global_load_dwordx4 v[10:13], v120, s[18:19] offset:208
	global_load_dwordx4 v[14:17], v120, s[18:19] offset:192
	ds_write2_b32 v31, v71, v73 offset1:65
	ds_write2_b32 v31, v74, v76 offset0:130 offset1:195
	s_waitcnt vmcnt(3)
	v_mul_f32_e32 v2, v59, v2
	s_waitcnt vmcnt(2)
	v_mul_f32_e32 v6, v55, v6
	s_waitcnt vmcnt(1)
	v_mul_f32_e32 v10, v51, v10
	s_waitcnt vmcnt(0)
	v_mul_f32_e32 v14, v47, v14
	v_add_u32_e32 v47, 0x400, v31
	ds_write2_b32 v47, v75, v77 offset0:4 offset1:69
	ds_write2_b32 v47, v78, v79 offset0:134 offset1:199
	v_add_u32_e32 v47, 0x800, v31
	ds_write2_b32 v47, v63, v65 offset0:8 offset1:73
	ds_write2_b32 v47, v67, v80 offset0:138 offset1:203
	v_add_u32_e32 v47, 0xc00, v31
	ds_write2_b32 v47, v69, v72 offset0:12 offset1:77
	ds_write2_b32 v47, v81, v83 offset0:142 offset1:207
	v_add_u32_e32 v47, 0x1000, v31
	ds_write2_b32 v47, v93, v105 offset0:16 offset1:81
	ds_write2_b32 v47, v106, v108 offset0:146 offset1:211
	v_add_u32_e32 v47, 0x1400, v31
	ds_write2_b32 v47, v107, v109 offset0:20 offset1:85
	ds_write2_b32 v47, v64, v110 offset0:150 offset1:215
	v_add_u32_e32 v47, 0x1800, v31
	ds_write2_b32 v47, v84, v85 offset0:24 offset1:89
	ds_write2_b32 v47, v87, v91 offset0:154 offset1:219
	v_add_u32_e32 v47, 0x1c00, v31
	ds_write2_b32 v47, v89, v92 offset0:28 offset1:93
	ds_write2_b32 v47, v94, v95 offset0:158 offset1:223
	v_add_u32_e32 v47, 0x2000, v31
	ds_write2_b32 v47, v66, v68 offset0:32 offset1:97
	ds_write2_b32 v47, v70, v82 offset0:162 offset1:227
	v_add_u32_e32 v47, 0x2400, v31
	ds_write2_b32 v47, v86, v88 offset0:36 offset1:101
	ds_write2_b32 v47, v90, v96 offset0:166 offset1:231
	v_add_u32_e32 v47, 0x2800, v31
	ds_write2_b32 v47, v97, v98 offset0:40 offset1:105
	ds_write2_b32 v47, v99, v100 offset0:170 offset1:235
	v_add_u32_e32 v47, 0x2c00, v31
	v_mul_f32_e32 v15, v48, v15
	ds_write2_b32 v47, v101, v102 offset0:44 offset1:109
	ds_write2_b32 v47, v103, v104 offset0:174 offset1:239
	v_add_u32_e32 v47, 0x3000, v31
	v_mul_f32_e32 v16, v49, v16
	v_mul_f32_e32 v17, v50, v17
	v_mul_f32_e32 v11, v52, v11
	ds_write2_b32 v47, v14, v15 offset0:48 offset1:113
	ds_write2_b32 v47, v16, v17 offset0:178 offset1:243
	v_add_u32_e32 v14, 0x3400, v31
	v_mul_f32_e32 v12, v53, v12
	v_mul_f32_e32 v13, v54, v13
	v_mul_f32_e32 v7, v56, v7
	ds_write2_b32 v14, v10, v11 offset0:52 offset1:117
	ds_write2_b32 v14, v12, v13 offset0:182 offset1:247
	v_add_u32_e32 v10, 0x3800, v31
	v_mul_f32_e32 v8, v57, v8
	v_mul_f32_e32 v9, v58, v9
	v_mul_f32_e32 v3, v60, v3
	ds_write2_b32 v10, v6, v7 offset0:56 offset1:121
	ds_write2_b32 v10, v8, v9 offset0:186 offset1:251
	v_add_u32_e32 v6, 0x3c00, v31
	v_mul_f32_e32 v4, v61, v4
	v_mul_f32_e32 v5, v62, v5
	ds_write2_b32 v6, v2, v3 offset0:60 offset1:125
	ds_write2_b32 v6, v4, v5 offset0:190 offset1:255
	s_waitcnt lgkmcnt(0)
; #define LAS __attribute__((address_space(3)))
; __device__ __forceinline__ unsigned pk2(float lo, float hi) { return pg8::cvt_pk_bf16(lo, hi); }
; template <int MODE>
; __device__ __forceinline__ void p0_item(const float* W, int K, int N, bf16u* WT, const float* ks, LAS float* scr, int item, int lane) {
;     ...
;     const int c = lane & 7;
; #pragma unroll
;     for (int j = 0; j < 8; ++j) { const int n = (lane >> 3) + 8 * j; const LAS float* s = scr + (8 * c) * 65 + n;
;         v4u o; o.x = pk2(s[0 * 65], s[1 * 65]); o.y = pk2(s[2 * 65], s[3 * 65]); o.z = pk2(s[4 * 65], s[5 * 65]); o.w = pk2(s[6 * 65], s[7 * 65]);
;         *(v4u*)(WT + (size_t)(drow + n) * K + k0 + 8 * c) = o; }
;     asm volatile("s_waitcnt lgkmcnt(0)" ::: "memory");
	v_add_u32_e32 v47, 0x400, v33
	ds_read2_b32 v[8:9], v33 offset0:65 offset1:73
	ds_read2_b32 v[10:11], v33 offset1:8
	ds_read2_b32 v[12:13], v33 offset0:130 offset1:138
	ds_read2_b32 v[14:15], v33 offset0:195 offset1:203
	ds_read2_b32 v[16:17], v47 offset0:4 offset1:12
	ds_read2_b32 v[48:49], v47 offset0:69 offset1:77
	ds_read2_b32 v[50:51], v47 offset0:134 offset1:142
	ds_read2_b32 v[52:53], v47 offset0:199 offset1:207
	v_or_b32_e32 v54, 0x80, v0
	v_ashrrev_i32_e32 v55, 31, v54
	v_lshl_add_u64 v[2:3], v[22:23], 0, s[90:91]
	v_lshlrev_b64 v[54:55], 11, v[54:55]
	s_waitcnt lgkmcnt(6)
	v_cvt_pk_bf16_f32 v4, v10, v8
	s_waitcnt lgkmcnt(4)
	v_cvt_pk_bf16_f32 v5, v12, v14
	s_waitcnt lgkmcnt(2)
	v_cvt_pk_bf16_f32 v6, v16, v48
	s_waitcnt lgkmcnt(0)
	v_cvt_pk_bf16_f32 v7, v50, v52
	v_lshl_add_u64 v[54:55], v[2:3], 0, v[54:55]
	v_or_b32_e32 v8, 0x88, v0
	global_store_dwordx4 v[54:55], v[4:7], off sc1
	v_or_b32_e32 v54, 0x90, v0
	v_ashrrev_i32_e32 v55, 31, v54
	v_cvt_pk_bf16_f32 v4, v11, v9
	v_ashrrev_i32_e32 v9, 31, v8
	v_lshlrev_b64 v[8:9], 11, v[8:9]
	v_cvt_pk_bf16_f32 v5, v13, v15
	v_cvt_pk_bf16_f32 v6, v17, v49
	v_cvt_pk_bf16_f32 v7, v51, v53
	v_lshl_add_u64 v[8:9], v[2:3], 0, v[8:9]
	global_store_dwordx4 v[8:9], v[4:7], off sc1
	ds_read2_b32 v[8:9], v33 offset0:16 offset1:24
	ds_read2_b32 v[10:11], v33 offset0:81 offset1:89
	ds_read2_b32 v[12:13], v33 offset0:146 offset1:154
	ds_read2_b32 v[14:15], v33 offset0:211 offset1:219
	ds_read2_b32 v[16:17], v47 offset0:20 offset1:28
	ds_read2_b32 v[48:49], v47 offset0:85 offset1:93
	ds_read2_b32 v[50:51], v47 offset0:150 offset1:158
	ds_read2_b32 v[52:53], v47 offset0:215 offset1:223
	v_lshlrev_b64 v[54:55], 11, v[54:55]
	s_waitcnt lgkmcnt(6)
	v_cvt_pk_bf16_f32 v4, v8, v10
	s_waitcnt lgkmcnt(4)
	v_cvt_pk_bf16_f32 v5, v12, v14
	s_waitcnt lgkmcnt(2)
	v_cvt_pk_bf16_f32 v6, v16, v48
	s_waitcnt lgkmcnt(0)
	v_cvt_pk_bf16_f32 v7, v50, v52
	v_lshl_add_u64 v[54:55], v[2:3], 0, v[54:55]
	v_or_b32_e32 v8, 0x98, v0
	global_store_dwordx4 v[54:55], v[4:7], off sc1
	v_or_b32_e32 v54, 0xa0, v0
	v_ashrrev_i32_e32 v55, 31, v54
	v_cvt_pk_bf16_f32 v4, v9, v11
	v_ashrrev_i32_e32 v9, 31, v8
	v_lshlrev_b64 v[8:9], 11, v[8:9]
	v_cvt_pk_bf16_f32 v5, v13, v15
	v_cvt_pk_bf16_f32 v6, v17, v49
	v_cvt_pk_bf16_f32 v7, v51, v53
	v_lshl_add_u64 v[8:9], v[2:3], 0, v[8:9]
	global_store_dwordx4 v[8:9], v[4:7], off sc1
	ds_read2_b32 v[8:9], v33 offset0:32 offset1:40
	ds_read2_b32 v[10:11], v33 offset0:97 offset1:105
	ds_read2_b32 v[12:13], v33 offset0:162 offset1:170
	ds_read2_b32 v[14:15], v33 offset0:227 offset1:235
	ds_read2_b32 v[16:17], v47 offset0:36 offset1:44
	ds_read2_b32 v[48:49], v47 offset0:101 offset1:109
	ds_read2_b32 v[50:51], v47 offset0:166 offset1:174
	ds_read2_b32 v[52:53], v47 offset0:231 offset1:239
	v_lshlrev_b64 v[54:55], 11, v[54:55]
	s_waitcnt lgkmcnt(6)
	v_cvt_pk_bf16_f32 v4, v8, v10
	s_waitcnt lgkmcnt(4)
	v_cvt_pk_bf16_f32 v5, v12, v14
	s_waitcnt lgkmcnt(2)
	v_cvt_pk_bf16_f32 v6, v16, v48
	s_waitcnt lgkmcnt(0)
	v_cvt_pk_bf16_f32 v7, v50, v52
	v_lshl_add_u64 v[54:55], v[2:3], 0, v[54:55]
	v_or_b32_e32 v8, 0xa8, v0
	global_store_dwordx4 v[54:55], v[4:7], off sc1
	v_or_b32_e32 v54, 0xb0, v0
	v_ashrrev_i32_e32 v55, 31, v54
	v_cvt_pk_bf16_f32 v4, v9, v11
	v_ashrrev_i32_e32 v9, 31, v8
	v_lshlrev_b64 v[8:9], 11, v[8:9]
	v_cvt_pk_bf16_f32 v5, v13, v15
	v_cvt_pk_bf16_f32 v6, v17, v49
	v_cvt_pk_bf16_f32 v7, v51, v53
	v_lshl_add_u64 v[8:9], v[2:3], 0, v[8:9]
	global_store_dwordx4 v[8:9], v[4:7], off sc1
	ds_read2_b32 v[8:9], v33 offset0:48 offset1:56
	ds_read2_b32 v[10:11], v33 offset0:113 offset1:121
	ds_read2_b32 v[12:13], v33 offset0:178 offset1:186
	ds_read2_b32 v[14:15], v33 offset0:243 offset1:251
	ds_read2_b32 v[16:17], v47 offset0:52 offset1:60
	ds_read2_b32 v[48:49], v47 offset0:117 offset1:125
	ds_read2_b32 v[50:51], v47 offset0:182 offset1:190
	ds_read2_b32 v[52:53], v47 offset0:247 offset1:255
	v_lshlrev_b64 v[54:55], 11, v[54:55]
	s_waitcnt lgkmcnt(6)
	v_cvt_pk_bf16_f32 v4, v8, v10
	s_waitcnt lgkmcnt(4)
	v_cvt_pk_bf16_f32 v5, v12, v14
	s_waitcnt lgkmcnt(2)
	v_cvt_pk_bf16_f32 v6, v16, v48
	s_waitcnt lgkmcnt(0)
	v_cvt_pk_bf16_f32 v7, v50, v52
	v_lshl_add_u64 v[54:55], v[2:3], 0, v[54:55]
	v_or_b32_e32 v8, 0xb8, v0
	global_store_dwordx4 v[54:55], v[4:7], off sc1
	s_nop 1
	v_cvt_pk_bf16_f32 v4, v9, v11
	v_ashrrev_i32_e32 v9, 31, v8
	v_lshlrev_b64 v[8:9], 11, v[8:9]
	v_cvt_pk_bf16_f32 v5, v13, v15
	v_cvt_pk_bf16_f32 v6, v17, v49
	v_cvt_pk_bf16_f32 v7, v51, v53
	v_lshl_add_u64 v[2:3], v[2:3], 0, v[8:9]
	global_store_dwordx4 v[2:3], v[4:7], off sc1
	s_waitcnt lgkmcnt(0)

; template <int MODE>
; __device__ __forceinline__ void p0_item(const float* W, int K, int N, bf16u* WT, const float* ks, LAS float* scr, int item, int lane) {
;     const int nblk = N / 64, kb = item / nblk, nb = item - kb * nblk, k0 = 64 * kb, n0 = 64 * nb;
;     int nn = n0 + lane;
;     if (MODE == 1) {
;         if (nn < 2048) { const int p = nn & 63; if (p < 16) nn = (nn & ~15) | (p & 3) | ((p & 4) << 1) | ((p & 8) >> 1); }
;         else if (nn >= 4096) { const int sec = nn >= 6144 ? 6144 : 4096, r = nn - sec, q = r & 255; nn = sec + ((q >> 7) << 10) + 128 * (r >> 8) + (q & 127); }
;     }
;     int drow = n0;
;     if (MODE == 2) drow = 256 * (n0 >> 7) + (n0 & 127);
;     if (MODE == 3) drow = 256 * (n0 >> 7) + 128 + (n0 & 127);
;     const float* src = W + (size_t)k0 * N + nn;
;     float v[64];
; #pragma unroll
;     for (int kk = 0; kk < 64; ++kk) v[kk] = src[(size_t)kk * N];
.LBB0_609:
	s_andn2_b64 vcc, exec, s[16:17]
	s_cbranch_vccnz .LBB0_611
	s_and_b32 s4, 0xffff, s56
	s_mul_hi_u32 s4, s4, 0x5d1745e
	s_mul_i32 s12, s4, 0x1600
	s_mulk_i32 s4, 0xb00
	v_subrev_u32_e32 v0, s4, v43
	s_mul_i32 s4, s55, 0xba2f
	s_add_i32 s4, s4, 0x2000140
	s_lshr_b32 s4, s4, 21
	s_add_i32 s17, s52, s59
	s_sub_i32 s16, s54, s12
	s_add_i32 s17, s17, 0xfffd4000
	s_mul_i32 s12, s4, 0xb0000
	v_add_u32_e32 v2, s59, v0
	s_add_u32 s20, s37, s12
	s_addc_u32 s21, s40, 0
	v_ashrrev_i32_e32 v3, 31, v2
	v_lshl_add_u64 v[2:3], v[2:3], 2, s[20:21]
	v_add_co_u32_e32 v6, vcc, s61, v2
	s_movk_i32 s12, 0x5000
	s_nop 0
	v_addc_co_u32_e32 v7, vcc, 0, v3, vcc
	global_load_dword v5, v[6:7], off offset:3072
	v_add_co_u32_e32 v6, vcc, s12, v2
	s_mov_b32 s12, 0xb000
	s_nop 0
	v_addc_co_u32_e32 v7, vcc, 0, v3, vcc
	v_add_co_u32_e32 v8, vcc, s88, v2
	global_load_dword v4, v[2:3], off
	s_nop 0
	v_addc_co_u32_e32 v9, vcc, 0, v3, vcc
	global_load_dword v6, v[6:7], off offset:2048
	s_lshl_b32 s90, s4, 7
	global_load_dword v7, v[8:9], off offset:1024
	v_add_co_u32_e32 v8, vcc, s12, v2
	s_mov_b32 s12, 0xd000
	s_nop 0
	v_addc_co_u32_e32 v9, vcc, 0, v3, vcc
	v_add_co_u32_e32 v10, vcc, s12, v2
	s_mov_b32 s12, 0x10000
	s_nop 0
	v_addc_co_u32_e32 v11, vcc, 0, v3, vcc
	global_load_dword v8, v[8:9], off
	s_nop 0
	global_load_dword v9, v[10:11], off offset:3072
	v_add_co_u32_e32 v10, vcc, s12, v2
	s_mov_b32 s12, 0x13000
	s_nop 0
	v_addc_co_u32_e32 v11, vcc, 0, v3, vcc
	v_add_co_u32_e32 v12, vcc, s12, v2
	s_mov_b32 s12, 0x16000
	s_nop 0
	v_addc_co_u32_e32 v13, vcc, 0, v3, vcc
	global_load_dword v60, v[12:13], off offset:1024
	v_add_co_u32_e32 v12, vcc, s12, v2
	global_load_dword v11, v[10:11], off offset:2048
	s_nop 0
	v_addc_co_u32_e32 v13, vcc, 0, v3, vcc
	global_load_dword v62, v[12:13], off
	v_add_co_u32_e32 v12, vcc, s5, v2
	s_mov_b32 s12, 0x1b000
	s_nop 0
	v_addc_co_u32_e32 v13, vcc, 0, v3, vcc
	global_load_dword v64, v[12:13], off offset:3072
	v_add_co_u32_e32 v12, vcc, s12, v2
	s_mov_b32 s12, 0x1e000
	s_nop 0
	v_addc_co_u32_e32 v13, vcc, 0, v3, vcc
	global_load_dword v66, v[12:13], off offset:2048
	v_add_co_u32_e32 v12, vcc, s12, v2
	s_mov_b32 s12, 0x21000
	s_nop 0
	v_addc_co_u32_e32 v13, vcc, 0, v3, vcc
	global_load_dword v68, v[12:13], off offset:1024
	v_add_co_u32_e32 v12, vcc, s12, v2
	s_mov_b32 s12, 0x23000
	s_nop 0
	v_addc_co_u32_e32 v13, vcc, 0, v3, vcc
	global_load_dword v70, v[12:13], off
	v_add_co_u32_e32 v12, vcc, s12, v2
	s_mov_b32 s12, 0x26000
	s_nop 0
	v_addc_co_u32_e32 v13, vcc, 0, v3, vcc
	global_load_dword v73, v[12:13], off offset:3072
	v_add_co_u32_e32 v12, vcc, s12, v2
	s_mov_b32 s12, 0x29000
	s_nop 0
	v_addc_co_u32_e32 v13, vcc, 0, v3, vcc
	global_load_dword v84, v[12:13], off offset:2048
	v_add_co_u32_e32 v12, vcc, s12, v2
	s_mov_b32 s12, 0x2c000
	s_nop 0
	v_addc_co_u32_e32 v13, vcc, 0, v3, vcc
	global_load_dword v91, v[12:13], off offset:1024
	v_add_co_u32_e32 v12, vcc, s12, v2
	s_mov_b32 s12, 0x2e000
	s_nop 0
	v_addc_co_u32_e32 v13, vcc, 0, v3, vcc
	global_load_dword v10, v[12:13], off
	v_add_co_u32_e32 v12, vcc, s12, v2
	s_mov_b32 s12, 0x31000
	s_nop 0
	v_addc_co_u32_e32 v13, vcc, 0, v3, vcc
	v_add_co_u32_e32 v14, vcc, s12, v2
	s_mov_b32 s12, 0x34000
	s_nop 0
	v_addc_co_u32_e32 v15, vcc, 0, v3, vcc
	global_load_dword v12, v[12:13], off offset:3072
	s_nop 0
	global_load_dword v13, v[14:15], off offset:2048
	v_add_co_u32_e32 v14, vcc, s12, v2
	s_mov_b32 s12, 0x37000
	s_nop 0
	v_addc_co_u32_e32 v15, vcc, 0, v3, vcc
	global_load_dword v58, v[14:15], off offset:1024
	v_add_co_u32_e32 v14, vcc, s12, v2
	s_mov_b32 s12, 0x39000
	s_nop 0
	v_addc_co_u32_e32 v15, vcc, 0, v3, vcc
	global_load_dword v59, v[14:15], off
	v_add_co_u32_e32 v14, vcc, s12, v2
	s_mov_b32 s12, 0x3c000
	s_nop 0
	v_addc_co_u32_e32 v15, vcc, 0, v3, vcc
	global_load_dword v61, v[14:15], off offset:3072
	v_add_co_u32_e32 v14, vcc, s12, v2
	s_mov_b32 s12, 0x3f000
	s_nop 0
	v_addc_co_u32_e32 v15, vcc, 0, v3, vcc
	global_load_dword v63, v[14:15], off offset:2048
	v_add_co_u32_e32 v14, vcc, s12, v2
	s_mov_b32 s12, 0x42000
	s_nop 0
	v_addc_co_u32_e32 v15, vcc, 0, v3, vcc
	global_load_dword v72, v[14:15], off offset:1024
	v_add_co_u32_e32 v14, vcc, s12, v2
	s_mov_b32 s12, 0x44000
	s_nop 0
	v_addc_co_u32_e32 v15, vcc, 0, v3, vcc
	global_load_dword v75, v[14:15], off
	v_add_co_u32_e32 v14, vcc, s12, v2
	s_mov_b32 s12, 0x47000
	s_nop 0
	v_addc_co_u32_e32 v15, vcc, 0, v3, vcc
	global_load_dword v85, v[14:15], off offset:3072
	v_add_co_u32_e32 v14, vcc, s12, v2
	s_mov_b32 s12, 0x4a000
	s_nop 0
	v_addc_co_u32_e32 v15, vcc, 0, v3, vcc
	global_load_dword v87, v[14:15], off offset:2048
	v_add_co_u32_e32 v14, vcc, s12, v2
	s_mov_b32 s12, 0x4d000
	s_nop 0
	v_addc_co_u32_e32 v15, vcc, 0, v3, vcc
	global_load_dword v89, v[14:15], off offset:1024
	v_add_co_u32_e32 v14, vcc, s12, v2
	s_mov_b32 s12, 0x4f000
	s_nop 0
	v_addc_co_u32_e32 v15, vcc, 0, v3, vcc
	global_load_dword v90, v[14:15], off
	v_add_co_u32_e32 v14, vcc, s12, v2
	s_mov_b32 s12, 0x52000
	s_nop 0
	v_addc_co_u32_e32 v15, vcc, 0, v3, vcc
	global_load_dword v92, v[14:15], off offset:3072
	v_add_co_u32_e32 v14, vcc, s12, v2
	s_mov_b32 s12, 0x55000
	s_nop 0
	v_addc_co_u32_e32 v15, vcc, 0, v3, vcc
	global_load_dword v93, v[14:15], off offset:2048
	v_add_co_u32_e32 v14, vcc, s12, v2
	s_mov_b32 s12, 0x58000
	s_nop 0
	v_addc_co_u32_e32 v15, vcc, 0, v3, vcc
	global_load_dword v99, v[14:15], off offset:1024
	v_add_co_u32_e32 v14, vcc, s12, v2
	s_mov_b32 s12, 0x5a000
	s_nop 0
	v_addc_co_u32_e32 v15, vcc, 0, v3, vcc
	global_load_dword v65, v[14:15], off
	v_add_co_u32_e32 v14, vcc, s12, v2
	s_mov_b32 s12, 0x5d000
	s_nop 0
	v_addc_co_u32_e32 v15, vcc, 0, v3, vcc
; template <int MODE>
; __device__ __forceinline__ void p0_item(const float* W, int K, int N, bf16u* WT, const float* ks, LAS float* scr, int item, int lane) {
;     ...
;     const float* src = W + (size_t)k0 * N + nn;
;     float v[64];
; #pragma unroll
;     for (int kk = 0; kk < 64; ++kk) v[kk] = src[(size_t)kk * N];
;     if (ks) {
; #pragma unroll
;         for (int kk = 0; kk < 64; ++kk) v[kk] *= ks[k0 + kk];
	global_load_dword v67, v[14:15], off offset:3072
	v_add_co_u32_e32 v14, vcc, s12, v2
	s_mov_b32 s12, 0x60000
	s_nop 0
	v_addc_co_u32_e32 v15, vcc, 0, v3, vcc
	global_load_dword v69, v[14:15], off offset:2048
	v_add_co_u32_e32 v14, vcc, s12, v2
	s_mov_b32 s12, 0x63000
	s_nop 0
	v_addc_co_u32_e32 v15, vcc, 0, v3, vcc
	global_load_dword v71, v[14:15], off offset:1024
	v_add_co_u32_e32 v14, vcc, s12, v2
	s_mov_b32 s12, 0x65000
	s_nop 0
	v_addc_co_u32_e32 v15, vcc, 0, v3, vcc
	global_load_dword v83, v[14:15], off
	v_add_co_u32_e32 v14, vcc, s12, v2
	s_mov_b32 s12, 0x68000
	s_nop 0
	v_addc_co_u32_e32 v15, vcc, 0, v3, vcc
	global_load_dword v86, v[14:15], off offset:3072
	v_add_co_u32_e32 v14, vcc, s12, v2
	s_mov_b32 s12, 0x6b000
	s_nop 0
	v_addc_co_u32_e32 v15, vcc, 0, v3, vcc
	global_load_dword v88, v[14:15], off offset:2048
	v_add_co_u32_e32 v14, vcc, s12, v2
	s_mov_b32 s12, 0x6e000
	s_nop 0
	v_addc_co_u32_e32 v15, vcc, 0, v3, vcc
	global_load_dword v94, v[14:15], off offset:1024
	v_add_co_u32_e32 v14, vcc, s12, v2
	s_mov_b32 s12, 0x70000
	s_nop 0
	v_addc_co_u32_e32 v15, vcc, 0, v3, vcc
	global_load_dword v95, v[14:15], off
	v_add_co_u32_e32 v14, vcc, s12, v2
	s_mov_b32 s12, 0x73000
	s_nop 0
	v_addc_co_u32_e32 v15, vcc, 0, v3, vcc
	global_load_dword v96, v[14:15], off offset:3072
	v_add_co_u32_e32 v14, vcc, s12, v2
	s_mov_b32 s12, 0x76000
	s_nop 0
	v_addc_co_u32_e32 v15, vcc, 0, v3, vcc
	global_load_dword v97, v[14:15], off offset:2048
	v_add_co_u32_e32 v14, vcc, s12, v2
	s_mov_b32 s12, 0x79000
	s_nop 0
	v_addc_co_u32_e32 v15, vcc, 0, v3, vcc
	global_load_dword v98, v[14:15], off offset:1024
	v_add_co_u32_e32 v14, vcc, s12, v2
	s_mov_b32 s12, 0x7b000
	s_nop 0
	v_addc_co_u32_e32 v15, vcc, 0, v3, vcc
	global_load_dword v100, v[14:15], off
	v_add_co_u32_e32 v14, vcc, s12, v2
	s_mov_b32 s12, 0x7e000
	s_nop 0
	v_addc_co_u32_e32 v15, vcc, 0, v3, vcc
	global_load_dword v101, v[14:15], off offset:3072
	v_add_co_u32_e32 v14, vcc, s12, v2
	s_mov_b32 s12, 0x81000
	s_nop 0
	v_addc_co_u32_e32 v15, vcc, 0, v3, vcc
	global_load_dword v102, v[14:15], off offset:2048
	v_add_co_u32_e32 v14, vcc, s12, v2
	s_mov_b32 s12, 0x84000
	s_nop 0
	v_addc_co_u32_e32 v15, vcc, 0, v3, vcc
	global_load_dword v106, v[14:15], off offset:1024
	v_add_co_u32_e32 v14, vcc, s12, v2
	s_mov_b32 s12, 0x86000
	s_nop 0
	v_addc_co_u32_e32 v15, vcc, 0, v3, vcc
	global_load_dword v0, v[14:15], off
	v_add_co_u32_e32 v14, vcc, s12, v2
	s_mov_b32 s12, 0x89000
	s_nop 0
	v_addc_co_u32_e32 v15, vcc, 0, v3, vcc
	v_add_co_u32_e32 v16, vcc, s12, v2
	s_mov_b32 s12, 0x8c000
	s_nop 0
	v_addc_co_u32_e32 v17, vcc, 0, v3, vcc
	global_load_dword v14, v[14:15], off offset:3072
	s_nop 0
	global_load_dword v15, v[16:17], off offset:2048
	v_add_co_u32_e32 v16, vcc, s12, v2
	s_mov_b32 s12, 0x8f000
	s_nop 0
	v_addc_co_u32_e32 v17, vcc, 0, v3, vcc
	v_add_co_u32_e32 v48, vcc, s12, v2
	s_mov_b32 s12, 0x91000
	s_nop 0
	v_addc_co_u32_e32 v49, vcc, 0, v3, vcc
	global_load_dword v16, v[16:17], off offset:1024
	s_nop 0
	global_load_dword v17, v[48:49], off
	v_add_co_u32_e32 v48, vcc, s12, v2
	s_mov_b32 s12, 0x94000
	s_nop 0
	v_addc_co_u32_e32 v49, vcc, 0, v3, vcc
	global_load_dword v47, v[48:49], off offset:3072
	v_add_co_u32_e32 v48, vcc, s12, v2
	s_mov_b32 s12, 0x97000
	s_nop 0
	v_addc_co_u32_e32 v49, vcc, 0, v3, vcc
	v_add_co_u32_e32 v50, vcc, s12, v2
	s_mov_b32 s12, 0x9a000
	s_nop 0
	v_addc_co_u32_e32 v51, vcc, 0, v3, vcc
	global_load_dword v48, v[48:49], off offset:2048
	s_nop 0
	global_load_dword v49, v[50:51], off offset:1024
	v_add_co_u32_e32 v50, vcc, s12, v2
	s_mov_b32 s12, 0x9c000
	s_nop 0
	v_addc_co_u32_e32 v51, vcc, 0, v3, vcc
	v_add_co_u32_e32 v52, vcc, s12, v2
	s_mov_b32 s12, 0x9f000
	s_nop 0
	v_addc_co_u32_e32 v53, vcc, 0, v3, vcc
	global_load_dword v50, v[50:51], off
	s_nop 0
	global_load_dword v51, v[52:53], off offset:3072
	v_add_co_u32_e32 v52, vcc, s12, v2
	s_mov_b32 s12, 0xa2000
	s_nop 0
	v_addc_co_u32_e32 v53, vcc, 0, v3, vcc
	v_add_co_u32_e32 v54, vcc, s12, v2
	s_mov_b32 s12, 0xa5000
	s_nop 0
	v_addc_co_u32_e32 v55, vcc, 0, v3, vcc
	global_load_dword v52, v[52:53], off offset:2048
	s_nop 0
	global_load_dword v53, v[54:55], off offset:1024
	v_add_co_u32_e32 v54, vcc, s12, v2
	s_mov_b32 s12, 0xa7000
	s_nop 0
	v_addc_co_u32_e32 v55, vcc, 0, v3, vcc
	v_add_co_u32_e32 v56, vcc, s12, v2
	s_mov_b32 s12, 0xaa000
	s_nop 0
	v_addc_co_u32_e32 v57, vcc, 0, v3, vcc
	global_load_dword v54, v[54:55], off
	s_nop 0
	global_load_dword v55, v[56:57], off offset:3072
	v_add_co_u32_e32 v56, vcc, s12, v2
	s_mov_b32 s12, 0xad000
	s_nop 0
	v_addc_co_u32_e32 v57, vcc, 0, v3, vcc
	v_add_co_u32_e32 v2, vcc, s12, v2
	s_lshl_b32 s12, s4, 8
	s_nop 0
	v_addc_co_u32_e32 v3, vcc, 0, v3, vcc
	v_mov_b32_e32 v107, s12
	global_load_dword v56, v[56:57], off offset:2048
	s_and_b32 s12, s16, 0xffffff00
	global_load_dword v57, v[2:3], off offset:1024
	global_load_dwordx4 v[108:111], v107, s[18:19] offset:48
	global_load_dwordx4 v[112:115], v107, s[18:19] offset:32
	global_load_dwordx4 v[116:119], v107, s[18:19] offset:16
	global_load_dwordx4 v[76:79], v107, s[18:19]
	s_and_b32 s16, s17, 64
	s_or_b32 s12, s12, s16
	s_waitcnt vmcnt(0)
	v_mul_f32_e32 v68, v68, v115
	v_mul_f32_e32 v80, v9, v117
	v_mul_f32_e32 v74, v4, v76
	v_mul_f32_e32 v76, v5, v77
	v_mul_f32_e32 v77, v6, v78
	v_mul_f32_e32 v79, v7, v79
	v_mul_f32_e32 v78, v8, v116
	v_mul_f32_e32 v82, v60, v119
	v_mul_f32_e32 v60, v62, v112
	v_mul_f32_e32 v62, v64, v113
	v_mul_f32_e32 v64, v66, v114
	v_mul_f32_e32 v66, v70, v108
	v_mul_f32_e32 v70, v73, v109
	v_mul_f32_e32 v73, v84, v110
	v_mul_f32_e32 v84, v91, v111
	global_load_dwordx4 v[2:5], v107, s[18:19] offset:112
	global_load_dwordx4 v[6:9], v107, s[18:19] offset:96
	global_load_dwordx4 v[108:111], v107, s[18:19] offset:80
	global_load_dwordx4 v[112:115], v107, s[18:19] offset:64
	v_mul_f32_e32 v81, v11, v118
	s_waitcnt vmcnt(2)
; template <int MODE>
; __device__ __forceinline__ void p0_item(const float* W, int K, int N, bf16u* WT, const float* ks, LAS float* scr, int item, int lane) {
;     ...
;         for (int kk = 0; kk < 64; ++kk) v[kk] *= ks[k0 + kk];
;     }
; #pragma unroll
;     for (int kk = 0; kk < 64; ++kk) scr[kk * 65 + lane] = v[kk];
;     asm volatile("s_waitcnt lgkmcnt(0)" ::: "memory");
	v_mul_f32_e32 v89, v89, v9
	s_waitcnt vmcnt(1)
	v_mul_f32_e32 v72, v72, v111
	s_waitcnt vmcnt(0)
	v_mul_f32_e32 v91, v10, v112
	v_mul_f32_e32 v103, v12, v113
	v_mul_f32_e32 v104, v13, v114
	v_mul_f32_e32 v105, v58, v115
	v_mul_f32_e32 v58, v59, v108
	v_mul_f32_e32 v59, v61, v109
	v_mul_f32_e32 v61, v63, v110
	v_mul_f32_e32 v63, v75, v6
	v_mul_f32_e32 v75, v85, v7
	v_mul_f32_e32 v85, v87, v8
	v_mul_f32_e32 v87, v90, v2
	v_mul_f32_e32 v90, v92, v3
	v_mul_f32_e32 v92, v93, v4
	v_mul_f32_e32 v93, v99, v5
	global_load_dwordx4 v[2:5], v107, s[18:19] offset:176
	global_load_dwordx4 v[6:9], v107, s[18:19] offset:160
	global_load_dwordx4 v[10:13], v107, s[18:19] offset:144
	global_load_dwordx4 v[108:111], v107, s[18:19] offset:128
	s_waitcnt vmcnt(3)
	v_mul_f32_e32 v100, v100, v2
	s_waitcnt vmcnt(2)
	v_mul_f32_e32 v98, v98, v9
	s_waitcnt vmcnt(1)
	v_mul_f32_e32 v83, v83, v10
	s_waitcnt vmcnt(0)
	v_mul_f32_e32 v65, v65, v108
	v_mul_f32_e32 v67, v67, v109
	v_mul_f32_e32 v69, v69, v110
	v_mul_f32_e32 v86, v86, v11
	v_mul_f32_e32 v88, v88, v12
	v_mul_f32_e32 v99, v94, v13
	v_mul_f32_e32 v108, v95, v6
	v_mul_f32_e32 v109, v96, v7
	v_mul_f32_e32 v110, v97, v8
	v_mul_f32_e32 v101, v101, v3
	v_mul_f32_e32 v102, v102, v4
	v_mul_f32_e32 v106, v106, v5
	global_load_dwordx4 v[2:5], v107, s[18:19] offset:240
	global_load_dwordx4 v[6:9], v107, s[18:19] offset:224
	global_load_dwordx4 v[10:13], v107, s[18:19] offset:208
	global_load_dwordx4 v[94:97], v107, s[18:19] offset:192
	ds_write2_b32 v31, v74, v76 offset1:65
	ds_write2_b32 v31, v77, v79 offset0:130 offset1:195
	v_mul_f32_e32 v71, v71, v111
	s_waitcnt vmcnt(3)
	v_mul_f32_e32 v2, v54, v2
	s_waitcnt vmcnt(2)
	v_mul_f32_e32 v6, v50, v6
	s_waitcnt vmcnt(1)
	v_mul_f32_e32 v10, v17, v10
	v_add_u32_e32 v17, 0x400, v31
	ds_write2_b32 v17, v78, v80 offset0:4 offset1:69
	ds_write2_b32 v17, v81, v82 offset0:134 offset1:199
	v_add_u32_e32 v17, 0x800, v31
	ds_write2_b32 v17, v60, v62 offset0:8 offset1:73
	ds_write2_b32 v17, v64, v68 offset0:138 offset1:203
	v_add_u32_e32 v17, 0xc00, v31
	ds_write2_b32 v17, v66, v70 offset0:12 offset1:77
	ds_write2_b32 v17, v73, v84 offset0:142 offset1:207
	v_add_u32_e32 v17, 0x1000, v31
	ds_write2_b32 v17, v91, v103 offset0:16 offset1:81
	ds_write2_b32 v17, v104, v105 offset0:146 offset1:211
	v_add_u32_e32 v17, 0x1400, v31
	ds_write2_b32 v17, v58, v59 offset0:20 offset1:85
	ds_write2_b32 v17, v61, v72 offset0:150 offset1:215
	v_add_u32_e32 v17, 0x1800, v31
	ds_write2_b32 v17, v63, v75 offset0:24 offset1:89
	ds_write2_b32 v17, v85, v89 offset0:154 offset1:219
	v_add_u32_e32 v17, 0x1c00, v31
	ds_write2_b32 v17, v87, v90 offset0:28 offset1:93
	ds_write2_b32 v17, v92, v93 offset0:158 offset1:223
	v_add_u32_e32 v17, 0x2000, v31
	ds_write2_b32 v17, v65, v67 offset0:32 offset1:97
	ds_write2_b32 v17, v69, v71 offset0:162 offset1:227
	v_add_u32_e32 v17, 0x2400, v31
	ds_write2_b32 v17, v83, v86 offset0:36 offset1:101
	ds_write2_b32 v17, v88, v99 offset0:166 offset1:231
	v_add_u32_e32 v17, 0x2800, v31
	ds_write2_b32 v17, v108, v109 offset0:40 offset1:105
	ds_write2_b32 v17, v110, v98 offset0:170 offset1:235
	v_add_u32_e32 v17, 0x2c00, v31
	s_waitcnt vmcnt(0)
	v_mul_f32_e32 v0, v0, v94
	v_mul_f32_e32 v14, v14, v95
	ds_write2_b32 v17, v100, v101 offset0:44 offset1:109
	ds_write2_b32 v17, v102, v106 offset0:174 offset1:239
	v_add_u32_e32 v17, 0x3000, v31
	v_mul_f32_e32 v15, v15, v96
	v_mul_f32_e32 v16, v16, v97
	v_mul_f32_e32 v11, v47, v11
	ds_write2_b32 v17, v0, v14 offset0:48 offset1:113
	ds_write2_b32 v17, v15, v16 offset0:178 offset1:243
	v_add_u32_e32 v0, 0x3400, v31
	v_mul_f32_e32 v12, v48, v12
	v_mul_f32_e32 v13, v49, v13
	v_mul_f32_e32 v7, v51, v7
	ds_write2_b32 v0, v10, v11 offset0:52 offset1:117
	ds_write2_b32 v0, v12, v13 offset0:182 offset1:247
	v_add_u32_e32 v0, 0x3800, v31
	v_mul_f32_e32 v8, v52, v8
	v_mul_f32_e32 v9, v53, v9
	v_mul_f32_e32 v3, v55, v3
	ds_write2_b32 v0, v6, v7 offset0:56 offset1:121
	ds_write2_b32 v0, v8, v9 offset0:186 offset1:251
	v_add_u32_e32 v0, 0x3c00, v31
	v_mul_f32_e32 v4, v56, v4
	v_mul_f32_e32 v5, v57, v5
	ds_write2_b32 v0, v2, v3 offset0:60 offset1:125
	ds_write2_b32 v0, v4, v5 offset0:190 offset1:255
	s_waitcnt lgkmcnt(0)
; #define LAS __attribute__((address_space(3)))
; __device__ __forceinline__ unsigned pk2(float lo, float hi) { return pg8::cvt_pk_bf16(lo, hi); }
; template <int MODE>
; __device__ __forceinline__ void p0_item(const float* W, int K, int N, bf16u* WT, const float* ks, LAS float* scr, int item, int lane) {
;     ...
;     const int c = lane & 7;
; #pragma unroll
;     for (int j = 0; j < 8; ++j) { const int n = (lane >> 3) + 8 * j; const LAS float* s = scr + (8 * c) * 65 + n;
;         v4u o; o.x = pk2(s[0 * 65], s[1 * 65]); o.y = pk2(s[2 * 65], s[3 * 65]); o.z = pk2(s[4 * 65], s[5 * 65]); o.w = pk2(s[6 * 65], s[7 * 65]);
;         *(v4u*)(WT + (size_t)(drow + n) * K + k0 + 8 * c) = o; }
;     asm volatile("s_waitcnt lgkmcnt(0)" ::: "memory");
	v_add_u32_e32 v0, 0x400, v33
	ds_read2_b32 v[8:9], v33 offset0:65 offset1:73
	ds_read2_b32 v[10:11], v33 offset1:8
	ds_read2_b32 v[12:13], v33 offset0:130 offset1:138
	ds_read2_b32 v[14:15], v33 offset0:195 offset1:203
	ds_read2_b32 v[16:17], v0 offset0:4 offset1:12
	ds_read2_b32 v[48:49], v0 offset0:69 offset1:77
	ds_read2_b32 v[50:51], v0 offset0:134 offset1:142
	ds_read2_b32 v[52:53], v0 offset0:199 offset1:207
	v_or_b32_e32 v54, s12, v32
	v_ashrrev_i32_e32 v55, 31, v54
	v_lshl_add_u64 v[2:3], v[22:23], 0, s[90:91]
	v_lshlrev_b64 v[54:55], 11, v[54:55]
	s_waitcnt lgkmcnt(6)
	v_cvt_pk_bf16_f32 v4, v10, v8
	s_waitcnt lgkmcnt(4)
	v_cvt_pk_bf16_f32 v5, v12, v14
	s_waitcnt lgkmcnt(2)
	v_cvt_pk_bf16_f32 v6, v16, v48
	s_waitcnt lgkmcnt(0)
	v_cvt_pk_bf16_f32 v7, v50, v52
	v_lshl_add_u64 v[54:55], v[2:3], 0, v[54:55]
	v_or_b32_e32 v8, s12, v34
	global_store_dwordx4 v[54:55], v[4:7], off sc1
	v_or_b32_e32 v54, s12, v35
	v_ashrrev_i32_e32 v55, 31, v54
	v_cvt_pk_bf16_f32 v4, v11, v9
	v_ashrrev_i32_e32 v9, 31, v8
	v_lshlrev_b64 v[8:9], 11, v[8:9]
	v_cvt_pk_bf16_f32 v5, v13, v15
	v_cvt_pk_bf16_f32 v6, v17, v49
	v_cvt_pk_bf16_f32 v7, v51, v53
	v_lshl_add_u64 v[8:9], v[2:3], 0, v[8:9]
	global_store_dwordx4 v[8:9], v[4:7], off sc1
	ds_read2_b32 v[8:9], v33 offset0:81 offset1:89
	ds_read2_b32 v[10:11], v33 offset0:16 offset1:24
	ds_read2_b32 v[12:13], v33 offset0:146 offset1:154
	ds_read2_b32 v[14:15], v33 offset0:211 offset1:219
	ds_read2_b32 v[16:17], v0 offset0:20 offset1:28
	ds_read2_b32 v[48:49], v0 offset0:85 offset1:93
	ds_read2_b32 v[50:51], v0 offset0:150 offset1:158
	ds_read2_b32 v[52:53], v0 offset0:215 offset1:223
	v_lshlrev_b64 v[54:55], 11, v[54:55]
	s_waitcnt lgkmcnt(6)
	v_cvt_pk_bf16_f32 v4, v10, v8
	s_waitcnt lgkmcnt(4)
	v_cvt_pk_bf16_f32 v5, v12, v14
	s_waitcnt lgkmcnt(2)
	v_cvt_pk_bf16_f32 v6, v16, v48
	s_waitcnt lgkmcnt(0)
	v_cvt_pk_bf16_f32 v7, v50, v52
	v_lshl_add_u64 v[54:55], v[2:3], 0, v[54:55]
	v_or_b32_e32 v8, s12, v36
	global_store_dwordx4 v[54:55], v[4:7], off sc1
	v_or_b32_e32 v54, s12, v37
	v_ashrrev_i32_e32 v55, 31, v54
	v_cvt_pk_bf16_f32 v4, v11, v9
	v_ashrrev_i32_e32 v9, 31, v8
	v_lshlrev_b64 v[8:9], 11, v[8:9]
	v_cvt_pk_bf16_f32 v5, v13, v15
	v_cvt_pk_bf16_f32 v6, v17, v49
	v_cvt_pk_bf16_f32 v7, v51, v53
	v_lshl_add_u64 v[8:9], v[2:3], 0, v[8:9]
	global_store_dwordx4 v[8:9], v[4:7], off sc1
	ds_read2_b32 v[8:9], v33 offset0:32 offset1:40
	ds_read2_b32 v[10:11], v33 offset0:97 offset1:105
	ds_read2_b32 v[12:13], v33 offset0:162 offset1:170
	ds_read2_b32 v[14:15], v33 offset0:227 offset1:235
	ds_read2_b32 v[16:17], v0 offset0:36 offset1:44
	ds_read2_b32 v[48:49], v0 offset0:101 offset1:109
	ds_read2_b32 v[50:51], v0 offset0:166 offset1:174
	ds_read2_b32 v[52:53], v0 offset0:231 offset1:239
	v_lshlrev_b64 v[54:55], 11, v[54:55]
	s_waitcnt lgkmcnt(6)
	v_cvt_pk_bf16_f32 v4, v8, v10
	s_waitcnt lgkmcnt(4)
	v_cvt_pk_bf16_f32 v5, v12, v14
	s_waitcnt lgkmcnt(2)
	v_cvt_pk_bf16_f32 v6, v16, v48
	s_waitcnt lgkmcnt(0)
	v_cvt_pk_bf16_f32 v7, v50, v52
	v_lshl_add_u64 v[54:55], v[2:3], 0, v[54:55]
	v_or_b32_e32 v8, s12, v38
	global_store_dwordx4 v[54:55], v[4:7], off sc1
	v_or_b32_e32 v54, s12, v39
	v_ashrrev_i32_e32 v55, 31, v54
	v_cvt_pk_bf16_f32 v4, v9, v11
	v_ashrrev_i32_e32 v9, 31, v8
	v_lshlrev_b64 v[8:9], 11, v[8:9]
	v_cvt_pk_bf16_f32 v5, v13, v15
	v_cvt_pk_bf16_f32 v6, v17, v49
	v_cvt_pk_bf16_f32 v7, v51, v53
	v_lshl_add_u64 v[8:9], v[2:3], 0, v[8:9]
	global_store_dwordx4 v[8:9], v[4:7], off sc1
	ds_read2_b32 v[8:9], v33 offset0:48 offset1:56
	ds_read2_b32 v[10:11], v33 offset0:113 offset1:121
	ds_read2_b32 v[12:13], v33 offset0:178 offset1:186
	ds_read2_b32 v[14:15], v33 offset0:243 offset1:251
	ds_read2_b32 v[16:17], v0 offset0:52 offset1:60
	ds_read2_b32 v[48:49], v0 offset0:117 offset1:125
	ds_read2_b32 v[50:51], v0 offset0:182 offset1:190
	ds_read2_b32 v[52:53], v0 offset0:247 offset1:255
	v_lshlrev_b64 v[54:55], 11, v[54:55]
	s_waitcnt lgkmcnt(6)
	v_cvt_pk_bf16_f32 v4, v8, v10
	s_waitcnt lgkmcnt(4)
	v_cvt_pk_bf16_f32 v5, v12, v14
	s_waitcnt lgkmcnt(2)
	v_cvt_pk_bf16_f32 v6, v16, v48
	s_waitcnt lgkmcnt(0)
	v_cvt_pk_bf16_f32 v7, v50, v52
	v_lshl_add_u64 v[54:55], v[2:3], 0, v[54:55]
	v_or_b32_e32 v8, s12, v40
	global_store_dwordx4 v[54:55], v[4:7], off sc1
	s_nop 1
	v_cvt_pk_bf16_f32 v4, v9, v11
	v_ashrrev_i32_e32 v9, 31, v8
	v_lshlrev_b64 v[8:9], 11, v[8:9]
	v_cvt_pk_bf16_f32 v5, v13, v15
	v_cvt_pk_bf16_f32 v6, v17, v49
	v_cvt_pk_bf16_f32 v7, v51, v53
	v_lshl_add_u64 v[2:3], v[2:3], 0, v[8:9]
	global_store_dwordx4 v[2:3], v[4:7], off sc1
	s_waitcnt lgkmcnt(0)

; template <int MODE>
; __device__ __forceinline__ void p0_item(const float* W, int K, int N, bf16u* WT, const float* ks, LAS float* scr, int item, int lane) {
;     ...
;     const float* src = W + (size_t)k0 * N + nn;
;     float v[64];
; #pragma unroll
;     for (int kk = 0; kk < 64; ++kk) v[kk] = src[(size_t)kk * N];
.LBB0_612:
	s_andn2_b64 vcc, exec, s[16:17]
	s_cbranch_vccnz .LBB0_614
	s_add_i32 s4, s53, 0xffffd800
	s_and_b32 s12, s4, 0xfc0
	s_add_i32 s4, s52, s59
	s_add_i32 s4, s4, 0xfffd8000
	s_and_b32 s4, s4, 0x3c0
	s_lshl_b32 s16, s12, 12
	v_or_b32_e32 v0, s4, v30
	s_add_u32 s16, s41, s16
	s_addc_u32 s17, s42, 0
	v_lshlrev_b32_e32 v0, 2, v0
	v_lshl_add_u64 v[2:3], s[16:17], 0, v[0:1]
	v_add_co_u32_e32 v4, vcc, s61, v2
	global_load_dword v0, v0, s[16:17]
	s_nop 0
	v_addc_co_u32_e32 v5, vcc, 0, v3, vcc
	s_movk_i32 s16, 0x4000
	global_load_dword v6, v[4:5], off offset:-4096
	global_load_dword v7, v[4:5], off
	v_add_co_u32_e32 v4, vcc, s16, v2
	s_movk_i32 s16, 0x6000
	s_nop 0
	v_addc_co_u32_e32 v5, vcc, 0, v3, vcc
	global_load_dword v8, v[4:5], off offset:-4096
	global_load_dword v9, v[4:5], off
	v_add_co_u32_e32 v4, vcc, s16, v2
	s_mov_b32 s16, 0xe000
	s_nop 0
	v_addc_co_u32_e32 v5, vcc, 0, v3, vcc
	global_load_dword v10, v[4:5], off offset:-4096
	global_load_dword v11, v[4:5], off
	v_add_co_u32_e32 v4, vcc, s88, v2
	s_lshl_b32 s90, s12, 1
	s_nop 0
	v_addc_co_u32_e32 v5, vcc, 0, v3, vcc
	global_load_dword v12, v[4:5], off offset:-4096
	global_load_dword v13, v[4:5], off
	v_add_co_u32_e32 v4, vcc, s27, v2
	s_nop 1
	v_addc_co_u32_e32 v5, vcc, 0, v3, vcc
	global_load_dword v14, v[4:5], off offset:-4096
	global_load_dword v15, v[4:5], off
	v_add_co_u32_e32 v4, vcc, s26, v2
	s_nop 1
	v_addc_co_u32_e32 v5, vcc, 0, v3, vcc
	global_load_dword v16, v[4:5], off offset:-4096
	global_load_dword v17, v[4:5], off
	v_add_co_u32_e32 v4, vcc, s16, v2
	s_mov_b32 s16, 0x10000
	s_nop 0
	v_addc_co_u32_e32 v5, vcc, 0, v3, vcc
	global_load_dword v47, v[4:5], off offset:-4096
	global_load_dword v48, v[4:5], off
	v_add_co_u32_e32 v4, vcc, s16, v2
	s_mov_b32 s16, 0x14000
	s_nop 0
	v_addc_co_u32_e32 v5, vcc, 0, v3, vcc
	global_load_dword v49, v[4:5], off offset:-4096
	global_load_dword v50, v[4:5], off
	v_add_co_u32_e32 v4, vcc, s22, v2
	s_nop 1
	v_addc_co_u32_e32 v5, vcc, 0, v3, vcc
	global_load_dword v51, v[4:5], off offset:-4096
	global_load_dword v52, v[4:5], off
	v_add_co_u32_e32 v4, vcc, s16, v2
	s_mov_b32 s16, 0x16000
	s_nop 0
	v_addc_co_u32_e32 v5, vcc, 0, v3, vcc
	global_load_dword v53, v[4:5], off offset:-4096
	global_load_dword v54, v[4:5], off
	v_add_co_u32_e32 v4, vcc, s16, v2
	s_mov_b32 s16, 0x1a000
	s_nop 0
	v_addc_co_u32_e32 v5, vcc, 0, v3, vcc
	global_load_dword v55, v[4:5], off offset:-4096
	global_load_dword v56, v[4:5], off
	v_add_co_u32_e32 v4, vcc, s5, v2
	s_nop 1
	v_addc_co_u32_e32 v5, vcc, 0, v3, vcc
	global_load_dword v57, v[4:5], off offset:-4096
	global_load_dword v58, v[4:5], off
	v_add_co_u32_e32 v4, vcc, s16, v2
	s_mov_b32 s16, 0x1c000
	s_nop 0
	v_addc_co_u32_e32 v5, vcc, 0, v3, vcc
	global_load_dword v59, v[4:5], off offset:-4096
	global_load_dword v60, v[4:5], off
	v_add_co_u32_e32 v4, vcc, s16, v2
	s_mov_b32 s16, 0x1e000
	s_nop 0
	v_addc_co_u32_e32 v5, vcc, 0, v3, vcc
	global_load_dword v61, v[4:5], off offset:-4096
	global_load_dword v62, v[4:5], off
	v_add_co_u32_e32 v4, vcc, s16, v2
	s_mov_b32 s16, 0x20000
	s_nop 0
	v_addc_co_u32_e32 v5, vcc, 0, v3, vcc
	global_load_dword v63, v[4:5], off offset:-4096
	global_load_dword v64, v[4:5], off
	v_add_co_u32_e32 v4, vcc, s16, v2
	s_mov_b32 s16, 0x22000
	s_nop 0
	v_addc_co_u32_e32 v5, vcc, 0, v3, vcc
	global_load_dword v65, v[4:5], off offset:-4096
	global_load_dword v66, v[4:5], off
	v_add_co_u32_e32 v4, vcc, s16, v2
	s_mov_b32 s16, 0x24000
	s_nop 0
	v_addc_co_u32_e32 v5, vcc, 0, v3, vcc
	global_load_dword v67, v[4:5], off offset:-4096
	global_load_dword v68, v[4:5], off
	v_add_co_u32_e32 v4, vcc, s16, v2
	s_mov_b32 s16, 0x26000
	s_nop 0
	v_addc_co_u32_e32 v5, vcc, 0, v3, vcc
	global_load_dword v69, v[4:5], off offset:-4096
	global_load_dword v70, v[4:5], off
	v_add_co_u32_e32 v4, vcc, s16, v2
	s_mov_b32 s16, 0x28000
	s_nop 0
	v_addc_co_u32_e32 v5, vcc, 0, v3, vcc
	global_load_dword v71, v[4:5], off offset:-4096
	global_load_dword v72, v[4:5], off
	v_add_co_u32_e32 v4, vcc, s16, v2
	s_mov_b32 s16, 0x2a000
	s_nop 0
	v_addc_co_u32_e32 v5, vcc, 0, v3, vcc
	global_load_dword v73, v[4:5], off offset:-4096
	global_load_dword v74, v[4:5], off
	v_add_co_u32_e32 v4, vcc, s16, v2
	s_mov_b32 s16, 0x2c000
	s_nop 0
	v_addc_co_u32_e32 v5, vcc, 0, v3, vcc
	global_load_dword v75, v[4:5], off offset:-4096
	global_load_dword v76, v[4:5], off
	v_add_co_u32_e32 v4, vcc, s16, v2
	s_mov_b32 s16, 0x2e000
	s_nop 0
	v_addc_co_u32_e32 v5, vcc, 0, v3, vcc
	global_load_dword v77, v[4:5], off offset:-4096
	global_load_dword v78, v[4:5], off
	v_add_co_u32_e32 v4, vcc, s16, v2
	s_mov_b32 s16, 0x30000
	s_nop 0
	v_addc_co_u32_e32 v5, vcc, 0, v3, vcc
	global_load_dword v79, v[4:5], off offset:-4096
	global_load_dword v80, v[4:5], off
	v_add_co_u32_e32 v4, vcc, s16, v2
	s_mov_b32 s16, 0x32000
	s_nop 0
	v_addc_co_u32_e32 v5, vcc, 0, v3, vcc
	global_load_dword v81, v[4:5], off offset:-4096
	global_load_dword v82, v[4:5], off
	v_add_co_u32_e32 v4, vcc, s16, v2
	s_mov_b32 s16, 0x34000
	s_nop 0
	v_addc_co_u32_e32 v5, vcc, 0, v3, vcc
	global_load_dword v83, v[4:5], off offset:-4096
	global_load_dword v84, v[4:5], off
	v_add_co_u32_e32 v4, vcc, s16, v2
	s_mov_b32 s16, 0x36000
	s_nop 0
	v_addc_co_u32_e32 v5, vcc, 0, v3, vcc
	global_load_dword v85, v[4:5], off offset:-4096
	global_load_dword v86, v[4:5], off
	v_add_co_u32_e32 v4, vcc, s16, v2
	s_mov_b32 s16, 0x38000
	s_nop 0
	v_addc_co_u32_e32 v5, vcc, 0, v3, vcc
	global_load_dword v87, v[4:5], off offset:-4096
	global_load_dword v88, v[4:5], off
	v_add_co_u32_e32 v4, vcc, s16, v2
	s_mov_b32 s16, 0x3a000
	s_nop 0
	v_addc_co_u32_e32 v5, vcc, 0, v3, vcc
	global_load_dword v89, v[4:5], off offset:-4096
	global_load_dword v90, v[4:5], off
	v_add_co_u32_e32 v4, vcc, s16, v2
	s_mov_b32 s16, 0x3c000
	s_nop 0
	v_addc_co_u32_e32 v5, vcc, 0, v3, vcc
	global_load_dword v91, v[4:5], off offset:-4096
	global_load_dword v92, v[4:5], off
	v_add_co_u32_e32 v4, vcc, s16, v2
	s_mov_b32 s16, 0x3e000
	s_nop 0
	v_addc_co_u32_e32 v5, vcc, 0, v3, vcc
	global_load_dword v93, v[4:5], off offset:-4096
	global_load_dword v94, v[4:5], off
	v_add_co_u32_e32 v4, vcc, s16, v2
	s_mov_b32 s16, 0x3f000
	s_nop 0
	v_addc_co_u32_e32 v5, vcc, 0, v3, vcc
	v_add_co_u32_e32 v2, vcc, s16, v2
	global_load_dword v95, v[4:5], off offset:-4096
	s_nop 0
	global_load_dword v4, v[4:5], off
	v_addc_co_u32_e32 v3, vcc, 0, v3, vcc
	global_load_dword v2, v[2:3], off
	s_waitcnt vmcnt(0)
; #define LAS __attribute__((address_space(3)))
; __device__ __forceinline__ unsigned pk2(float lo, float hi) { return pg8::cvt_pk_bf16(lo, hi); }
; template <int MODE>
; __device__ __forceinline__ void p0_item(const float* W, int K, int N, bf16u* WT, const float* ks, LAS float* scr, int item, int lane) {
;     ...
;     for (int kk = 0; kk < 64; ++kk) scr[kk * 65 + lane] = v[kk];
;     asm volatile("s_waitcnt lgkmcnt(0)" ::: "memory");
;     const int c = lane & 7;
; #pragma unroll
;     for (int j = 0; j < 8; ++j) { const int n = (lane >> 3) + 8 * j; const LAS float* s = scr + (8 * c) * 65 + n;
;         v4u o; o.x = pk2(s[0 * 65], s[1 * 65]); o.y = pk2(s[2 * 65], s[3 * 65]); o.z = pk2(s[4 * 65], s[5 * 65]); o.w = pk2(s[6 * 65], s[7 * 65]);
;         *(v4u*)(WT + (size_t)(drow + n) * K + k0 + 8 * c) = o; }
;     asm volatile("s_waitcnt lgkmcnt(0)" ::: "memory");
	ds_write2_b32 v31, v0, v6 offset1:65
	ds_write2_b32 v31, v7, v8 offset0:130 offset1:195
	v_add_u32_e32 v0, 0x400, v31
	ds_write2_b32 v0, v9, v10 offset0:4 offset1:69
	ds_write2_b32 v0, v11, v12 offset0:134 offset1:199
	v_add_u32_e32 v0, 0x800, v31
	ds_write2_b32 v0, v13, v14 offset0:8 offset1:73
	ds_write2_b32 v0, v15, v16 offset0:138 offset1:203
	v_add_u32_e32 v0, 0xc00, v31
	ds_write2_b32 v0, v17, v47 offset0:12 offset1:77
	ds_write2_b32 v0, v48, v49 offset0:142 offset1:207
	v_add_u32_e32 v0, 0x1000, v31
	ds_write2_b32 v0, v50, v51 offset0:16 offset1:81
	ds_write2_b32 v0, v52, v53 offset0:146 offset1:211
	v_add_u32_e32 v0, 0x1400, v31
	ds_write2_b32 v0, v54, v55 offset0:20 offset1:85
	ds_write2_b32 v0, v56, v57 offset0:150 offset1:215
	v_add_u32_e32 v0, 0x1800, v31
	ds_write2_b32 v0, v58, v59 offset0:24 offset1:89
	ds_write2_b32 v0, v60, v61 offset0:154 offset1:219
	v_add_u32_e32 v0, 0x1c00, v31
	ds_write2_b32 v0, v62, v63 offset0:28 offset1:93
	ds_write2_b32 v0, v64, v65 offset0:158 offset1:223
	v_add_u32_e32 v0, 0x2000, v31
	ds_write2_b32 v0, v66, v67 offset0:32 offset1:97
	ds_write2_b32 v0, v68, v69 offset0:162 offset1:227
	v_add_u32_e32 v0, 0x2400, v31
	ds_write2_b32 v0, v70, v71 offset0:36 offset1:101
	ds_write2_b32 v0, v72, v73 offset0:166 offset1:231
	v_add_u32_e32 v0, 0x2800, v31
	ds_write2_b32 v0, v74, v75 offset0:40 offset1:105
	ds_write2_b32 v0, v76, v77 offset0:170 offset1:235
	v_add_u32_e32 v0, 0x2c00, v31
	ds_write2_b32 v0, v78, v79 offset0:44 offset1:109
	ds_write2_b32 v0, v80, v81 offset0:174 offset1:239
	v_add_u32_e32 v0, 0x3000, v31
	ds_write2_b32 v0, v82, v83 offset0:48 offset1:113
	ds_write2_b32 v0, v84, v85 offset0:178 offset1:243
	v_add_u32_e32 v0, 0x3400, v31
	ds_write2_b32 v0, v86, v87 offset0:52 offset1:117
	ds_write2_b32 v0, v88, v89 offset0:182 offset1:247
	v_add_u32_e32 v0, 0x3800, v31
	ds_write2_b32 v0, v90, v91 offset0:56 offset1:121
	ds_write2_b32 v0, v92, v93 offset0:186 offset1:251
	v_add_u32_e32 v0, 0x3c00, v31
	ds_write2_b32 v0, v94, v95 offset0:60 offset1:125
	ds_write2_b32 v0, v4, v2 offset0:190 offset1:255
	s_waitcnt lgkmcnt(0)
	v_add_u32_e32 v47, 0x400, v33
	ds_read2_b32 v[8:9], v33 offset0:65 offset1:73
	ds_read2_b32 v[10:11], v33 offset1:8
	ds_read2_b32 v[12:13], v33 offset0:130 offset1:138
	ds_read2_b32 v[14:15], v33 offset0:195 offset1:203
	ds_read2_b32 v[16:17], v47 offset0:4 offset1:12
	ds_read2_b32 v[48:49], v47 offset0:69 offset1:77
	ds_read2_b32 v[50:51], v47 offset0:134 offset1:142
	ds_read2_b32 v[52:53], v47 offset0:199 offset1:207
	v_or_b32_e32 v0, s4, v32
	v_lshl_add_u64 v[2:3], v[24:25], 0, s[90:91]
	v_lshlrev_b32_e32 v0, 11, v0
	v_lshl_add_u64 v[54:55], v[2:3], 0, v[0:1]
	v_or_b32_e32 v0, s4, v34
	s_waitcnt lgkmcnt(6)
	v_cvt_pk_bf16_f32 v4, v10, v8
	s_waitcnt lgkmcnt(4)
	v_cvt_pk_bf16_f32 v5, v12, v14
	s_waitcnt lgkmcnt(2)
	v_cvt_pk_bf16_f32 v6, v16, v48
	s_waitcnt lgkmcnt(0)
	v_cvt_pk_bf16_f32 v7, v50, v52
	v_lshlrev_b32_e32 v0, 11, v0
	global_store_dwordx4 v[54:55], v[4:7], off sc1
	s_nop 1
	v_cvt_pk_bf16_f32 v4, v11, v9
	v_cvt_pk_bf16_f32 v5, v13, v15
	v_cvt_pk_bf16_f32 v6, v17, v49
	v_cvt_pk_bf16_f32 v7, v51, v53
	v_lshl_add_u64 v[8:9], v[2:3], 0, v[0:1]
	global_store_dwordx4 v[8:9], v[4:7], off sc1
	ds_read2_b32 v[8:9], v33 offset0:81 offset1:89
	ds_read2_b32 v[10:11], v33 offset0:16 offset1:24
	ds_read2_b32 v[12:13], v33 offset0:146 offset1:154
	ds_read2_b32 v[14:15], v33 offset0:211 offset1:219
	ds_read2_b32 v[16:17], v47 offset0:20 offset1:28
	ds_read2_b32 v[48:49], v47 offset0:85 offset1:93
	ds_read2_b32 v[50:51], v47 offset0:150 offset1:158
	ds_read2_b32 v[52:53], v47 offset0:215 offset1:223
	v_or_b32_e32 v0, s4, v35
	v_lshlrev_b32_e32 v0, 11, v0
	v_lshl_add_u64 v[54:55], v[2:3], 0, v[0:1]
	v_or_b32_e32 v0, s4, v36
	s_waitcnt lgkmcnt(6)
	v_cvt_pk_bf16_f32 v4, v10, v8
	s_waitcnt lgkmcnt(4)
	v_cvt_pk_bf16_f32 v5, v12, v14
	s_waitcnt lgkmcnt(2)
	v_cvt_pk_bf16_f32 v6, v16, v48
	s_waitcnt lgkmcnt(0)
	v_cvt_pk_bf16_f32 v7, v50, v52
	v_lshlrev_b32_e32 v0, 11, v0
	global_store_dwordx4 v[54:55], v[4:7], off sc1
	s_nop 1
	v_cvt_pk_bf16_f32 v4, v11, v9
	v_cvt_pk_bf16_f32 v5, v13, v15
	v_cvt_pk_bf16_f32 v6, v17, v49
	v_cvt_pk_bf16_f32 v7, v51, v53
	v_lshl_add_u64 v[8:9], v[2:3], 0, v[0:1]
	global_store_dwordx4 v[8:9], v[4:7], off sc1
	ds_read2_b32 v[8:9], v33 offset0:32 offset1:40
	ds_read2_b32 v[10:11], v33 offset0:97 offset1:105
	ds_read2_b32 v[12:13], v33 offset0:162 offset1:170
	ds_read2_b32 v[14:15], v33 offset0:227 offset1:235
	ds_read2_b32 v[16:17], v47 offset0:36 offset1:44
	ds_read2_b32 v[48:49], v47 offset0:101 offset1:109
	ds_read2_b32 v[50:51], v47 offset0:166 offset1:174
	ds_read2_b32 v[52:53], v47 offset0:231 offset1:239
	v_or_b32_e32 v0, s4, v37
	v_lshlrev_b32_e32 v0, 11, v0
	v_lshl_add_u64 v[54:55], v[2:3], 0, v[0:1]
	v_or_b32_e32 v0, s4, v38
	s_waitcnt lgkmcnt(6)
	v_cvt_pk_bf16_f32 v4, v8, v10
	s_waitcnt lgkmcnt(4)
	v_cvt_pk_bf16_f32 v5, v12, v14
	s_waitcnt lgkmcnt(2)
	v_cvt_pk_bf16_f32 v6, v16, v48
	s_waitcnt lgkmcnt(0)
	v_cvt_pk_bf16_f32 v7, v50, v52
	v_lshlrev_b32_e32 v0, 11, v0
	global_store_dwordx4 v[54:55], v[4:7], off sc1
	s_nop 1
	v_cvt_pk_bf16_f32 v4, v9, v11
	v_cvt_pk_bf16_f32 v5, v13, v15
	v_cvt_pk_bf16_f32 v6, v17, v49
	v_cvt_pk_bf16_f32 v7, v51, v53
	v_lshl_add_u64 v[8:9], v[2:3], 0, v[0:1]
	global_store_dwordx4 v[8:9], v[4:7], off sc1
	ds_read2_b32 v[8:9], v33 offset0:48 offset1:56
	ds_read2_b32 v[10:11], v33 offset0:113 offset1:121
	ds_read2_b32 v[12:13], v33 offset0:178 offset1:186
	ds_read2_b32 v[14:15], v33 offset0:243 offset1:251
	ds_read2_b32 v[16:17], v47 offset0:52 offset1:60
	ds_read2_b32 v[48:49], v47 offset0:117 offset1:125
	ds_read2_b32 v[50:51], v47 offset0:182 offset1:190
	ds_read2_b32 v[52:53], v47 offset0:247 offset1:255
	v_or_b32_e32 v0, s4, v39
	v_lshlrev_b32_e32 v0, 11, v0
	v_lshl_add_u64 v[54:55], v[2:3], 0, v[0:1]
	v_or_b32_e32 v0, s4, v40
	s_waitcnt lgkmcnt(6)
	v_cvt_pk_bf16_f32 v4, v8, v10
	s_waitcnt lgkmcnt(4)
	v_cvt_pk_bf16_f32 v5, v12, v14
	s_waitcnt lgkmcnt(2)
	v_cvt_pk_bf16_f32 v6, v16, v48
	s_waitcnt lgkmcnt(0)
	v_cvt_pk_bf16_f32 v7, v50, v52
	v_lshlrev_b32_e32 v0, 11, v0
	global_store_dwordx4 v[54:55], v[4:7], off sc1
	v_lshl_add_u64 v[2:3], v[2:3], 0, v[0:1]
	s_nop 0
	v_cvt_pk_bf16_f32 v4, v9, v11
	v_cvt_pk_bf16_f32 v5, v13, v15
	v_cvt_pk_bf16_f32 v6, v17, v49
	v_cvt_pk_bf16_f32 v7, v51, v53
	global_store_dwordx4 v[2:3], v[4:7], off sc1
	s_waitcnt lgkmcnt(0)

; template <int MODE>
; __device__ __forceinline__ void p0_item(const float* W, int K, int N, bf16u* WT, const float* ks, LAS float* scr, int item, int lane) {
;     ...
;     const float* src = W + (size_t)k0 * N + nn;
;     float v[64];
; #pragma unroll
;     for (int kk = 0; kk < 64; ++kk) v[kk] = src[(size_t)kk * N];
.LBB0_615:
	s_andn2_b64 vcc, exec, s[16:17]
	s_cbranch_vccnz .LBB0_617
	s_add_i32 s4, s53, 0xffffdc00
	s_and_b32 s12, s4, 0xfc0
	s_add_i32 s4, s52, s59
	s_add_i32 s4, s4, 0xfffdc000
	s_and_b32 s4, s4, 0x3c0
	s_lshl_b32 s16, s12, 12
	v_or_b32_e32 v0, s4, v30
	s_add_u32 s16, s43, s16
	s_addc_u32 s17, s46, 0
	v_lshlrev_b32_e32 v0, 2, v0
	v_lshl_add_u64 v[2:3], s[16:17], 0, v[0:1]
	v_add_co_u32_e32 v4, vcc, s61, v2
	global_load_dword v0, v0, s[16:17]
	s_nop 0
	v_addc_co_u32_e32 v5, vcc, 0, v3, vcc
	s_movk_i32 s16, 0x4000
	global_load_dword v6, v[4:5], off offset:-4096
	global_load_dword v7, v[4:5], off
	v_add_co_u32_e32 v4, vcc, s16, v2
	s_movk_i32 s16, 0x6000
	s_nop 0
	v_addc_co_u32_e32 v5, vcc, 0, v3, vcc
	global_load_dword v8, v[4:5], off offset:-4096
	global_load_dword v9, v[4:5], off
	v_add_co_u32_e32 v4, vcc, s16, v2
	s_mov_b32 s16, 0xe000
	s_nop 0
	v_addc_co_u32_e32 v5, vcc, 0, v3, vcc
	global_load_dword v10, v[4:5], off offset:-4096
	global_load_dword v11, v[4:5], off
	v_add_co_u32_e32 v4, vcc, s88, v2
	s_lshl_b32 s90, s12, 1
	s_nop 0
	v_addc_co_u32_e32 v5, vcc, 0, v3, vcc
	global_load_dword v12, v[4:5], off offset:-4096
	global_load_dword v13, v[4:5], off
	v_add_co_u32_e32 v4, vcc, s27, v2
	s_nop 1
	v_addc_co_u32_e32 v5, vcc, 0, v3, vcc
	global_load_dword v14, v[4:5], off offset:-4096
	global_load_dword v15, v[4:5], off
	v_add_co_u32_e32 v4, vcc, s26, v2
	s_nop 1
	v_addc_co_u32_e32 v5, vcc, 0, v3, vcc
	global_load_dword v16, v[4:5], off offset:-4096
	global_load_dword v17, v[4:5], off
	v_add_co_u32_e32 v4, vcc, s16, v2
	s_mov_b32 s16, 0x10000
	s_nop 0
	v_addc_co_u32_e32 v5, vcc, 0, v3, vcc
	global_load_dword v47, v[4:5], off offset:-4096
	global_load_dword v48, v[4:5], off
	v_add_co_u32_e32 v4, vcc, s16, v2
	s_mov_b32 s16, 0x14000
	s_nop 0
	v_addc_co_u32_e32 v5, vcc, 0, v3, vcc
	global_load_dword v49, v[4:5], off offset:-4096
	global_load_dword v50, v[4:5], off
	v_add_co_u32_e32 v4, vcc, s22, v2
	s_nop 1
	v_addc_co_u32_e32 v5, vcc, 0, v3, vcc
	global_load_dword v51, v[4:5], off offset:-4096
	global_load_dword v52, v[4:5], off
	v_add_co_u32_e32 v4, vcc, s16, v2
	s_mov_b32 s16, 0x16000
	s_nop 0
	v_addc_co_u32_e32 v5, vcc, 0, v3, vcc
	global_load_dword v53, v[4:5], off offset:-4096
	global_load_dword v54, v[4:5], off
	v_add_co_u32_e32 v4, vcc, s16, v2
	s_mov_b32 s16, 0x1a000
	s_nop 0
	v_addc_co_u32_e32 v5, vcc, 0, v3, vcc
	global_load_dword v55, v[4:5], off offset:-4096
	global_load_dword v56, v[4:5], off
	v_add_co_u32_e32 v4, vcc, s5, v2
	s_nop 1
	v_addc_co_u32_e32 v5, vcc, 0, v3, vcc
	global_load_dword v57, v[4:5], off offset:-4096
	global_load_dword v58, v[4:5], off
	v_add_co_u32_e32 v4, vcc, s16, v2
	s_mov_b32 s16, 0x1c000
	s_nop 0
	v_addc_co_u32_e32 v5, vcc, 0, v3, vcc
	global_load_dword v59, v[4:5], off offset:-4096
	global_load_dword v60, v[4:5], off
	v_add_co_u32_e32 v4, vcc, s16, v2
	s_mov_b32 s16, 0x1e000
	s_nop 0
	v_addc_co_u32_e32 v5, vcc, 0, v3, vcc
	global_load_dword v61, v[4:5], off offset:-4096
	global_load_dword v62, v[4:5], off
	v_add_co_u32_e32 v4, vcc, s16, v2
	s_mov_b32 s16, 0x20000
	s_nop 0
	v_addc_co_u32_e32 v5, vcc, 0, v3, vcc
	global_load_dword v63, v[4:5], off offset:-4096
	global_load_dword v64, v[4:5], off
	v_add_co_u32_e32 v4, vcc, s16, v2
	s_mov_b32 s16, 0x22000
	s_nop 0
	v_addc_co_u32_e32 v5, vcc, 0, v3, vcc
	global_load_dword v65, v[4:5], off offset:-4096
	global_load_dword v66, v[4:5], off
	v_add_co_u32_e32 v4, vcc, s16, v2
	s_mov_b32 s16, 0x24000
	s_nop 0
	v_addc_co_u32_e32 v5, vcc, 0, v3, vcc
	global_load_dword v67, v[4:5], off offset:-4096
	global_load_dword v68, v[4:5], off
	v_add_co_u32_e32 v4, vcc, s16, v2
	s_mov_b32 s16, 0x26000
	s_nop 0
	v_addc_co_u32_e32 v5, vcc, 0, v3, vcc
	global_load_dword v69, v[4:5], off offset:-4096
	global_load_dword v70, v[4:5], off
	v_add_co_u32_e32 v4, vcc, s16, v2
	s_mov_b32 s16, 0x28000
	s_nop 0
	v_addc_co_u32_e32 v5, vcc, 0, v3, vcc
	global_load_dword v71, v[4:5], off offset:-4096
	global_load_dword v72, v[4:5], off
	v_add_co_u32_e32 v4, vcc, s16, v2
	s_mov_b32 s16, 0x2a000
	s_nop 0
	v_addc_co_u32_e32 v5, vcc, 0, v3, vcc
	global_load_dword v73, v[4:5], off offset:-4096
	global_load_dword v74, v[4:5], off
	v_add_co_u32_e32 v4, vcc, s16, v2
	s_mov_b32 s16, 0x2c000
	s_nop 0
	v_addc_co_u32_e32 v5, vcc, 0, v3, vcc
	global_load_dword v75, v[4:5], off offset:-4096
	global_load_dword v76, v[4:5], off
	v_add_co_u32_e32 v4, vcc, s16, v2
	s_mov_b32 s16, 0x2e000
	s_nop 0
	v_addc_co_u32_e32 v5, vcc, 0, v3, vcc
	global_load_dword v77, v[4:5], off offset:-4096
	global_load_dword v78, v[4:5], off
	v_add_co_u32_e32 v4, vcc, s16, v2
	s_mov_b32 s16, 0x30000
	s_nop 0
	v_addc_co_u32_e32 v5, vcc, 0, v3, vcc
	global_load_dword v79, v[4:5], off offset:-4096
	global_load_dword v80, v[4:5], off
	v_add_co_u32_e32 v4, vcc, s16, v2
	s_mov_b32 s16, 0x32000
	s_nop 0
	v_addc_co_u32_e32 v5, vcc, 0, v3, vcc
	global_load_dword v81, v[4:5], off offset:-4096
	global_load_dword v82, v[4:5], off
	v_add_co_u32_e32 v4, vcc, s16, v2
	s_mov_b32 s16, 0x34000
	s_nop 0
	v_addc_co_u32_e32 v5, vcc, 0, v3, vcc
	global_load_dword v83, v[4:5], off offset:-4096
	global_load_dword v84, v[4:5], off
	v_add_co_u32_e32 v4, vcc, s16, v2
	s_mov_b32 s16, 0x36000
	s_nop 0
	v_addc_co_u32_e32 v5, vcc, 0, v3, vcc
	global_load_dword v85, v[4:5], off offset:-4096
	global_load_dword v86, v[4:5], off
	v_add_co_u32_e32 v4, vcc, s16, v2
	s_mov_b32 s16, 0x38000
	s_nop 0
	v_addc_co_u32_e32 v5, vcc, 0, v3, vcc
	global_load_dword v87, v[4:5], off offset:-4096
	global_load_dword v88, v[4:5], off
	v_add_co_u32_e32 v4, vcc, s16, v2
	s_mov_b32 s16, 0x3a000
	s_nop 0
	v_addc_co_u32_e32 v5, vcc, 0, v3, vcc
	global_load_dword v89, v[4:5], off offset:-4096
	global_load_dword v90, v[4:5], off
	v_add_co_u32_e32 v4, vcc, s16, v2
	s_mov_b32 s16, 0x3c000
	s_nop 0
	v_addc_co_u32_e32 v5, vcc, 0, v3, vcc
	global_load_dword v91, v[4:5], off offset:-4096
	global_load_dword v92, v[4:5], off
	v_add_co_u32_e32 v4, vcc, s16, v2
	s_mov_b32 s16, 0x3e000
	s_nop 0
	v_addc_co_u32_e32 v5, vcc, 0, v3, vcc
	global_load_dword v93, v[4:5], off offset:-4096
	global_load_dword v94, v[4:5], off
	v_add_co_u32_e32 v4, vcc, s16, v2
	s_mov_b32 s16, 0x3f000
	s_nop 0
	v_addc_co_u32_e32 v5, vcc, 0, v3, vcc
	v_add_co_u32_e32 v2, vcc, s16, v2
	global_load_dword v95, v[4:5], off offset:-4096
	s_nop 0
	global_load_dword v4, v[4:5], off
	v_addc_co_u32_e32 v3, vcc, 0, v3, vcc
	global_load_dword v2, v[2:3], off
	s_waitcnt vmcnt(0)
; #define LAS __attribute__((address_space(3)))
; __device__ __forceinline__ unsigned pk2(float lo, float hi) { return pg8::cvt_pk_bf16(lo, hi); }
; template <int MODE>
; __device__ __forceinline__ void p0_item(const float* W, int K, int N, bf16u* WT, const float* ks, LAS float* scr, int item, int lane) {
;     ...
;     for (int kk = 0; kk < 64; ++kk) scr[kk * 65 + lane] = v[kk];
;     asm volatile("s_waitcnt lgkmcnt(0)" ::: "memory");
;     const int c = lane & 7;
; #pragma unroll
;     for (int j = 0; j < 8; ++j) { const int n = (lane >> 3) + 8 * j; const LAS float* s = scr + (8 * c) * 65 + n;
;         v4u o; o.x = pk2(s[0 * 65], s[1 * 65]); o.y = pk2(s[2 * 65], s[3 * 65]); o.z = pk2(s[4 * 65], s[5 * 65]); o.w = pk2(s[6 * 65], s[7 * 65]);
;         *(v4u*)(WT + (size_t)(drow + n) * K + k0 + 8 * c) = o; }
;     asm volatile("s_waitcnt lgkmcnt(0)" ::: "memory");
	ds_write2_b32 v31, v0, v6 offset1:65
	ds_write2_b32 v31, v7, v8 offset0:130 offset1:195
	v_add_u32_e32 v0, 0x400, v31
	ds_write2_b32 v0, v9, v10 offset0:4 offset1:69
	ds_write2_b32 v0, v11, v12 offset0:134 offset1:199
	v_add_u32_e32 v0, 0x800, v31
	ds_write2_b32 v0, v13, v14 offset0:8 offset1:73
	ds_write2_b32 v0, v15, v16 offset0:138 offset1:203
	v_add_u32_e32 v0, 0xc00, v31
	ds_write2_b32 v0, v17, v47 offset0:12 offset1:77
	ds_write2_b32 v0, v48, v49 offset0:142 offset1:207
	v_add_u32_e32 v0, 0x1000, v31
	ds_write2_b32 v0, v50, v51 offset0:16 offset1:81
	ds_write2_b32 v0, v52, v53 offset0:146 offset1:211
	v_add_u32_e32 v0, 0x1400, v31
	ds_write2_b32 v0, v54, v55 offset0:20 offset1:85
	ds_write2_b32 v0, v56, v57 offset0:150 offset1:215
	v_add_u32_e32 v0, 0x1800, v31
	ds_write2_b32 v0, v58, v59 offset0:24 offset1:89
	ds_write2_b32 v0, v60, v61 offset0:154 offset1:219
	v_add_u32_e32 v0, 0x1c00, v31
	ds_write2_b32 v0, v62, v63 offset0:28 offset1:93
	ds_write2_b32 v0, v64, v65 offset0:158 offset1:223
	v_add_u32_e32 v0, 0x2000, v31
	ds_write2_b32 v0, v66, v67 offset0:32 offset1:97
	ds_write2_b32 v0, v68, v69 offset0:162 offset1:227
	v_add_u32_e32 v0, 0x2400, v31
	ds_write2_b32 v0, v70, v71 offset0:36 offset1:101
	ds_write2_b32 v0, v72, v73 offset0:166 offset1:231
	v_add_u32_e32 v0, 0x2800, v31
	ds_write2_b32 v0, v74, v75 offset0:40 offset1:105
	ds_write2_b32 v0, v76, v77 offset0:170 offset1:235
	v_add_u32_e32 v0, 0x2c00, v31
	ds_write2_b32 v0, v78, v79 offset0:44 offset1:109
	ds_write2_b32 v0, v80, v81 offset0:174 offset1:239
	v_add_u32_e32 v0, 0x3000, v31
	ds_write2_b32 v0, v82, v83 offset0:48 offset1:113
	ds_write2_b32 v0, v84, v85 offset0:178 offset1:243
	v_add_u32_e32 v0, 0x3400, v31
	ds_write2_b32 v0, v86, v87 offset0:52 offset1:117
	ds_write2_b32 v0, v88, v89 offset0:182 offset1:247
	v_add_u32_e32 v0, 0x3800, v31
	ds_write2_b32 v0, v90, v91 offset0:56 offset1:121
	ds_write2_b32 v0, v92, v93 offset0:186 offset1:251
	v_add_u32_e32 v0, 0x3c00, v31
	ds_write2_b32 v0, v94, v95 offset0:60 offset1:125
	ds_write2_b32 v0, v4, v2 offset0:190 offset1:255
	s_waitcnt lgkmcnt(0)
	v_add_u32_e32 v47, 0x400, v33
	ds_read2_b32 v[8:9], v33 offset0:65 offset1:73
	ds_read2_b32 v[10:11], v33 offset1:8
	ds_read2_b32 v[12:13], v33 offset0:130 offset1:138
	ds_read2_b32 v[14:15], v33 offset0:195 offset1:203
	ds_read2_b32 v[16:17], v47 offset0:4 offset1:12
	ds_read2_b32 v[48:49], v47 offset0:69 offset1:77
	ds_read2_b32 v[50:51], v47 offset0:134 offset1:142
	ds_read2_b32 v[52:53], v47 offset0:199 offset1:207
	v_or_b32_e32 v0, s4, v32
	v_lshl_add_u64 v[2:3], v[26:27], 0, s[90:91]
	v_lshlrev_b32_e32 v0, 11, v0
	v_lshl_add_u64 v[54:55], v[2:3], 0, v[0:1]
	v_or_b32_e32 v0, s4, v34
	s_waitcnt lgkmcnt(6)
	v_cvt_pk_bf16_f32 v4, v10, v8
	s_waitcnt lgkmcnt(4)
	v_cvt_pk_bf16_f32 v5, v12, v14
	s_waitcnt lgkmcnt(2)
	v_cvt_pk_bf16_f32 v6, v16, v48
	s_waitcnt lgkmcnt(0)
	v_cvt_pk_bf16_f32 v7, v50, v52
	v_lshlrev_b32_e32 v0, 11, v0
	global_store_dwordx4 v[54:55], v[4:7], off sc1
	s_nop 1
	v_cvt_pk_bf16_f32 v4, v11, v9
	v_cvt_pk_bf16_f32 v5, v13, v15
	v_cvt_pk_bf16_f32 v6, v17, v49
	v_cvt_pk_bf16_f32 v7, v51, v53
	v_lshl_add_u64 v[8:9], v[2:3], 0, v[0:1]
	global_store_dwordx4 v[8:9], v[4:7], off sc1
	ds_read2_b32 v[8:9], v33 offset0:81 offset1:89
	ds_read2_b32 v[10:11], v33 offset0:16 offset1:24
	ds_read2_b32 v[12:13], v33 offset0:146 offset1:154
	ds_read2_b32 v[14:15], v33 offset0:211 offset1:219
	ds_read2_b32 v[16:17], v47 offset0:20 offset1:28
	ds_read2_b32 v[48:49], v47 offset0:85 offset1:93
	ds_read2_b32 v[50:51], v47 offset0:150 offset1:158
	ds_read2_b32 v[52:53], v47 offset0:215 offset1:223
	v_or_b32_e32 v0, s4, v35
	v_lshlrev_b32_e32 v0, 11, v0
	v_lshl_add_u64 v[54:55], v[2:3], 0, v[0:1]
	v_or_b32_e32 v0, s4, v36
	s_waitcnt lgkmcnt(6)
	v_cvt_pk_bf16_f32 v4, v10, v8
	s_waitcnt lgkmcnt(4)
	v_cvt_pk_bf16_f32 v5, v12, v14
	s_waitcnt lgkmcnt(2)
	v_cvt_pk_bf16_f32 v6, v16, v48
	s_waitcnt lgkmcnt(0)
	v_cvt_pk_bf16_f32 v7, v50, v52
	v_lshlrev_b32_e32 v0, 11, v0
	global_store_dwordx4 v[54:55], v[4:7], off sc1
	s_nop 1
	v_cvt_pk_bf16_f32 v4, v11, v9
	v_cvt_pk_bf16_f32 v5, v13, v15
	v_cvt_pk_bf16_f32 v6, v17, v49
	v_cvt_pk_bf16_f32 v7, v51, v53
	v_lshl_add_u64 v[8:9], v[2:3], 0, v[0:1]
	global_store_dwordx4 v[8:9], v[4:7], off sc1
	ds_read2_b32 v[8:9], v33 offset0:32 offset1:40
	ds_read2_b32 v[10:11], v33 offset0:97 offset1:105
	ds_read2_b32 v[12:13], v33 offset0:162 offset1:170
	ds_read2_b32 v[14:15], v33 offset0:227 offset1:235
	ds_read2_b32 v[16:17], v47 offset0:36 offset1:44
	ds_read2_b32 v[48:49], v47 offset0:101 offset1:109
	ds_read2_b32 v[50:51], v47 offset0:166 offset1:174
	ds_read2_b32 v[52:53], v47 offset0:231 offset1:239
	v_or_b32_e32 v0, s4, v37
	v_lshlrev_b32_e32 v0, 11, v0
	v_lshl_add_u64 v[54:55], v[2:3], 0, v[0:1]
	v_or_b32_e32 v0, s4, v38
	s_waitcnt lgkmcnt(6)
	v_cvt_pk_bf16_f32 v4, v8, v10
	s_waitcnt lgkmcnt(4)
	v_cvt_pk_bf16_f32 v5, v12, v14
	s_waitcnt lgkmcnt(2)
	v_cvt_pk_bf16_f32 v6, v16, v48
	s_waitcnt lgkmcnt(0)
	v_cvt_pk_bf16_f32 v7, v50, v52
	v_lshlrev_b32_e32 v0, 11, v0
	global_store_dwordx4 v[54:55], v[4:7], off sc1
	s_nop 1
	v_cvt_pk_bf16_f32 v4, v9, v11
	v_cvt_pk_bf16_f32 v5, v13, v15
	v_cvt_pk_bf16_f32 v6, v17, v49
	v_cvt_pk_bf16_f32 v7, v51, v53
	v_lshl_add_u64 v[8:9], v[2:3], 0, v[0:1]
	global_store_dwordx4 v[8:9], v[4:7], off sc1
	ds_read2_b32 v[8:9], v33 offset0:48 offset1:56
	ds_read2_b32 v[10:11], v33 offset0:113 offset1:121
	ds_read2_b32 v[12:13], v33 offset0:178 offset1:186
	ds_read2_b32 v[14:15], v33 offset0:243 offset1:251
	ds_read2_b32 v[16:17], v47 offset0:52 offset1:60
	ds_read2_b32 v[48:49], v47 offset0:117 offset1:125
	ds_read2_b32 v[50:51], v47 offset0:182 offset1:190
	ds_read2_b32 v[52:53], v47 offset0:247 offset1:255
	v_or_b32_e32 v0, s4, v39
	v_lshlrev_b32_e32 v0, 11, v0
	v_lshl_add_u64 v[54:55], v[2:3], 0, v[0:1]
	v_or_b32_e32 v0, s4, v40
	s_waitcnt lgkmcnt(6)
	v_cvt_pk_bf16_f32 v4, v8, v10
	s_waitcnt lgkmcnt(4)
	v_cvt_pk_bf16_f32 v5, v12, v14
	s_waitcnt lgkmcnt(2)
	v_cvt_pk_bf16_f32 v6, v16, v48
	s_waitcnt lgkmcnt(0)
	v_cvt_pk_bf16_f32 v7, v50, v52
	v_lshlrev_b32_e32 v0, 11, v0
	global_store_dwordx4 v[54:55], v[4:7], off sc1
	v_lshl_add_u64 v[2:3], v[2:3], 0, v[0:1]
	s_nop 0
	v_cvt_pk_bf16_f32 v4, v9, v11
	v_cvt_pk_bf16_f32 v5, v13, v15
	v_cvt_pk_bf16_f32 v6, v17, v49
	v_cvt_pk_bf16_f32 v7, v51, v53
	global_store_dwordx4 v[2:3], v[4:7], off sc1
	s_waitcnt lgkmcnt(0)

; template <int MODE>
; __device__ __forceinline__ void p0_item(const float* W, int K, int N, bf16u* WT, const float* ks, LAS float* scr, int item, int lane) {
;     const int nblk = N / 64, kb = item / nblk, nb = item - kb * nblk, k0 = 64 * kb, n0 = 64 * nb;
;     int nn = n0 + lane;
;     if (MODE == 1) {
;         if (nn < 2048) { const int p = nn & 63; if (p < 16) nn = (nn & ~15) | (p & 3) | ((p & 4) << 1) | ((p & 8) >> 1); }
;         else if (nn >= 4096) { const int sec = nn >= 6144 ? 6144 : 4096, r = nn - sec, q = r & 255; nn = sec + ((q >> 7) << 10) + 128 * (r >> 8) + (q & 127); }
;     }
;     int drow = n0;
;     if (MODE == 2) drow = 256 * (n0 >> 7) + (n0 & 127);
;     if (MODE == 3) drow = 256 * (n0 >> 7) + 128 + (n0 & 127);
;     const float* src = W + (size_t)k0 * N + nn;
;     float v[64];
; #pragma unroll
;     for (int kk = 0; kk < 64; ++kk) v[kk] = src[(size_t)kk * N];
.LBB0_618:
	s_andn2_b64 vcc, exec, s[16:17]
	s_cbranch_vccnz .LBB0_620
	s_add_i32 s4, s53, 0xffffe000
	s_and_b32 s12, s4, 0xfc0
	s_add_i32 s4, s52, s59
	s_add_i32 s4, s4, 0xfffe0000
	s_and_b32 s4, s4, 0x3c0
	s_lshl_b32 s16, s12, 12
	v_or_b32_e32 v0, s4, v30
	s_add_u32 s16, s47, s16
	s_addc_u32 s17, s24, 0
	v_lshlrev_b32_e32 v0, 2, v0
	v_lshl_add_u64 v[2:3], s[16:17], 0, v[0:1]
	v_add_co_u32_e32 v4, vcc, s61, v2
	global_load_dword v0, v0, s[16:17]
	s_nop 0
	v_addc_co_u32_e32 v5, vcc, 0, v3, vcc
	s_movk_i32 s16, 0x4000
	global_load_dword v6, v[4:5], off offset:-4096
	global_load_dword v7, v[4:5], off
	v_add_co_u32_e32 v4, vcc, s16, v2
	s_movk_i32 s16, 0x6000
	s_nop 0
	v_addc_co_u32_e32 v5, vcc, 0, v3, vcc
	global_load_dword v8, v[4:5], off offset:-4096
	global_load_dword v9, v[4:5], off
	v_add_co_u32_e32 v4, vcc, s16, v2
	s_mov_b32 s16, 0xe000
	s_nop 0
	v_addc_co_u32_e32 v5, vcc, 0, v3, vcc
	global_load_dword v10, v[4:5], off offset:-4096
	global_load_dword v11, v[4:5], off
	v_add_co_u32_e32 v4, vcc, s88, v2
	s_lshl_b32 s90, s12, 1
	s_nop 0
	v_addc_co_u32_e32 v5, vcc, 0, v3, vcc
	global_load_dword v12, v[4:5], off offset:-4096
	global_load_dword v13, v[4:5], off
	v_add_co_u32_e32 v4, vcc, s27, v2
	s_nop 1
	v_addc_co_u32_e32 v5, vcc, 0, v3, vcc
	global_load_dword v14, v[4:5], off offset:-4096
	global_load_dword v15, v[4:5], off
	v_add_co_u32_e32 v4, vcc, s26, v2
	s_nop 1
	v_addc_co_u32_e32 v5, vcc, 0, v3, vcc
	global_load_dword v16, v[4:5], off offset:-4096
	global_load_dword v17, v[4:5], off
	v_add_co_u32_e32 v4, vcc, s16, v2
	s_mov_b32 s16, 0x10000
	s_nop 0
	v_addc_co_u32_e32 v5, vcc, 0, v3, vcc
	global_load_dword v47, v[4:5], off offset:-4096
	global_load_dword v48, v[4:5], off
	v_add_co_u32_e32 v4, vcc, s16, v2
	s_mov_b32 s16, 0x14000
	s_nop 0
	v_addc_co_u32_e32 v5, vcc, 0, v3, vcc
	global_load_dword v49, v[4:5], off offset:-4096
	global_load_dword v50, v[4:5], off
	v_add_co_u32_e32 v4, vcc, s22, v2
	s_nop 1
	v_addc_co_u32_e32 v5, vcc, 0, v3, vcc
	global_load_dword v51, v[4:5], off offset:-4096
	global_load_dword v52, v[4:5], off
	v_add_co_u32_e32 v4, vcc, s16, v2
	s_mov_b32 s16, 0x16000
	s_nop 0
	v_addc_co_u32_e32 v5, vcc, 0, v3, vcc
	global_load_dword v53, v[4:5], off offset:-4096
	global_load_dword v54, v[4:5], off
	v_add_co_u32_e32 v4, vcc, s16, v2
	s_mov_b32 s16, 0x1a000
	s_nop 0
	v_addc_co_u32_e32 v5, vcc, 0, v3, vcc
	global_load_dword v55, v[4:5], off offset:-4096
	global_load_dword v56, v[4:5], off
	v_add_co_u32_e32 v4, vcc, s5, v2
	s_nop 1
	v_addc_co_u32_e32 v5, vcc, 0, v3, vcc
	global_load_dword v57, v[4:5], off offset:-4096
	global_load_dword v58, v[4:5], off
	v_add_co_u32_e32 v4, vcc, s16, v2
	s_mov_b32 s16, 0x1c000
	s_nop 0
	v_addc_co_u32_e32 v5, vcc, 0, v3, vcc
	global_load_dword v59, v[4:5], off offset:-4096
	global_load_dword v60, v[4:5], off
	v_add_co_u32_e32 v4, vcc, s16, v2
	s_mov_b32 s16, 0x1e000
	s_nop 0
	v_addc_co_u32_e32 v5, vcc, 0, v3, vcc
	global_load_dword v61, v[4:5], off offset:-4096
	global_load_dword v62, v[4:5], off
	v_add_co_u32_e32 v4, vcc, s16, v2
	s_mov_b32 s16, 0x20000
	s_nop 0
	v_addc_co_u32_e32 v5, vcc, 0, v3, vcc
	global_load_dword v63, v[4:5], off offset:-4096
	global_load_dword v64, v[4:5], off
	v_add_co_u32_e32 v4, vcc, s16, v2
	s_mov_b32 s16, 0x22000
	s_nop 0
	v_addc_co_u32_e32 v5, vcc, 0, v3, vcc
	global_load_dword v65, v[4:5], off offset:-4096
	global_load_dword v66, v[4:5], off
	v_add_co_u32_e32 v4, vcc, s16, v2
	s_mov_b32 s16, 0x24000
	s_nop 0
	v_addc_co_u32_e32 v5, vcc, 0, v3, vcc
	global_load_dword v67, v[4:5], off offset:-4096
	global_load_dword v68, v[4:5], off
	v_add_co_u32_e32 v4, vcc, s16, v2
	s_mov_b32 s16, 0x26000
	s_nop 0
	v_addc_co_u32_e32 v5, vcc, 0, v3, vcc
	global_load_dword v69, v[4:5], off offset:-4096
	global_load_dword v70, v[4:5], off
	v_add_co_u32_e32 v4, vcc, s16, v2
	s_mov_b32 s16, 0x28000
	s_nop 0
	v_addc_co_u32_e32 v5, vcc, 0, v3, vcc
	global_load_dword v71, v[4:5], off offset:-4096
	global_load_dword v72, v[4:5], off
	v_add_co_u32_e32 v4, vcc, s16, v2
	s_mov_b32 s16, 0x2a000
	s_nop 0
	v_addc_co_u32_e32 v5, vcc, 0, v3, vcc
	global_load_dword v73, v[4:5], off offset:-4096
	global_load_dword v74, v[4:5], off
	v_add_co_u32_e32 v4, vcc, s16, v2
	s_mov_b32 s16, 0x2c000
	s_nop 0
	v_addc_co_u32_e32 v5, vcc, 0, v3, vcc
	global_load_dword v75, v[4:5], off offset:-4096
	global_load_dword v76, v[4:5], off
	v_add_co_u32_e32 v4, vcc, s16, v2
	s_mov_b32 s16, 0x2e000
	s_nop 0
	v_addc_co_u32_e32 v5, vcc, 0, v3, vcc
	global_load_dword v77, v[4:5], off offset:-4096
	global_load_dword v78, v[4:5], off
	v_add_co_u32_e32 v4, vcc, s16, v2
	s_mov_b32 s16, 0x30000
	s_nop 0
	v_addc_co_u32_e32 v5, vcc, 0, v3, vcc
	global_load_dword v79, v[4:5], off offset:-4096
	global_load_dword v80, v[4:5], off
	v_add_co_u32_e32 v4, vcc, s16, v2
	s_mov_b32 s16, 0x32000
	s_nop 0
	v_addc_co_u32_e32 v5, vcc, 0, v3, vcc
	global_load_dword v81, v[4:5], off offset:-4096
	global_load_dword v82, v[4:5], off
	v_add_co_u32_e32 v4, vcc, s16, v2
	s_mov_b32 s16, 0x34000
	s_nop 0
	v_addc_co_u32_e32 v5, vcc, 0, v3, vcc
	global_load_dword v83, v[4:5], off offset:-4096
	global_load_dword v84, v[4:5], off
	v_add_co_u32_e32 v4, vcc, s16, v2
	s_mov_b32 s16, 0x36000
	s_nop 0
	v_addc_co_u32_e32 v5, vcc, 0, v3, vcc
	global_load_dword v85, v[4:5], off offset:-4096
	global_load_dword v86, v[4:5], off
	v_add_co_u32_e32 v4, vcc, s16, v2
	s_mov_b32 s16, 0x38000
	s_nop 0
	v_addc_co_u32_e32 v5, vcc, 0, v3, vcc
	global_load_dword v87, v[4:5], off offset:-4096
	global_load_dword v88, v[4:5], off
	v_add_co_u32_e32 v4, vcc, s16, v2
	s_mov_b32 s16, 0x3a000
	s_nop 0
	v_addc_co_u32_e32 v5, vcc, 0, v3, vcc
	global_load_dword v89, v[4:5], off offset:-4096
	global_load_dword v90, v[4:5], off
	v_add_co_u32_e32 v4, vcc, s16, v2
	s_mov_b32 s16, 0x3c000
	s_nop 0
	v_addc_co_u32_e32 v5, vcc, 0, v3, vcc
	global_load_dword v91, v[4:5], off offset:-4096
	global_load_dword v92, v[4:5], off
	v_add_co_u32_e32 v4, vcc, s16, v2
	s_mov_b32 s16, 0x3e000
	s_nop 0
	v_addc_co_u32_e32 v5, vcc, 0, v3, vcc
	global_load_dword v93, v[4:5], off offset:-4096
	global_load_dword v94, v[4:5], off
	v_add_co_u32_e32 v4, vcc, s16, v2
	s_mov_b32 s16, 0x3f000
	s_nop 0
	v_addc_co_u32_e32 v5, vcc, 0, v3, vcc
	v_add_co_u32_e32 v2, vcc, s16, v2
	global_load_dword v95, v[4:5], off offset:-4096
	s_nop 0
	global_load_dword v4, v[4:5], off
	v_addc_co_u32_e32 v3, vcc, 0, v3, vcc
	global_load_dword v2, v[2:3], off
	s_waitcnt vmcnt(0)
; #define LAS __attribute__((address_space(3)))
; __device__ __forceinline__ unsigned pk2(float lo, float hi) { return pg8::cvt_pk_bf16(lo, hi); }
; template <int MODE>
; __device__ __forceinline__ void p0_item(const float* W, int K, int N, bf16u* WT, const float* ks, LAS float* scr, int item, int lane) {
;     ...
;     for (int kk = 0; kk < 64; ++kk) scr[kk * 65 + lane] = v[kk];
;     asm volatile("s_waitcnt lgkmcnt(0)" ::: "memory");
;     const int c = lane & 7;
; #pragma unroll
;     for (int j = 0; j < 8; ++j) { const int n = (lane >> 3) + 8 * j; const LAS float* s = scr + (8 * c) * 65 + n;
;         v4u o; o.x = pk2(s[0 * 65], s[1 * 65]); o.y = pk2(s[2 * 65], s[3 * 65]); o.z = pk2(s[4 * 65], s[5 * 65]); o.w = pk2(s[6 * 65], s[7 * 65]);
;         *(v4u*)(WT + (size_t)(drow + n) * K + k0 + 8 * c) = o; }
;     asm volatile("s_waitcnt lgkmcnt(0)" ::: "memory");
	ds_write2_b32 v31, v0, v6 offset1:65
	ds_write2_b32 v31, v7, v8 offset0:130 offset1:195
	v_add_u32_e32 v0, 0x400, v31
	ds_write2_b32 v0, v9, v10 offset0:4 offset1:69
	ds_write2_b32 v0, v11, v12 offset0:134 offset1:199
	v_add_u32_e32 v0, 0x800, v31
	ds_write2_b32 v0, v13, v14 offset0:8 offset1:73
	ds_write2_b32 v0, v15, v16 offset0:138 offset1:203
	v_add_u32_e32 v0, 0xc00, v31
	ds_write2_b32 v0, v17, v47 offset0:12 offset1:77
	ds_write2_b32 v0, v48, v49 offset0:142 offset1:207
	v_add_u32_e32 v0, 0x1000, v31
	ds_write2_b32 v0, v50, v51 offset0:16 offset1:81
	ds_write2_b32 v0, v52, v53 offset0:146 offset1:211
	v_add_u32_e32 v0, 0x1400, v31
	ds_write2_b32 v0, v54, v55 offset0:20 offset1:85
	ds_write2_b32 v0, v56, v57 offset0:150 offset1:215
	v_add_u32_e32 v0, 0x1800, v31
	ds_write2_b32 v0, v58, v59 offset0:24 offset1:89
	ds_write2_b32 v0, v60, v61 offset0:154 offset1:219
	v_add_u32_e32 v0, 0x1c00, v31
	ds_write2_b32 v0, v62, v63 offset0:28 offset1:93
	ds_write2_b32 v0, v64, v65 offset0:158 offset1:223
	v_add_u32_e32 v0, 0x2000, v31
	ds_write2_b32 v0, v66, v67 offset0:32 offset1:97
	ds_write2_b32 v0, v68, v69 offset0:162 offset1:227
	v_add_u32_e32 v0, 0x2400, v31
	ds_write2_b32 v0, v70, v71 offset0:36 offset1:101
	ds_write2_b32 v0, v72, v73 offset0:166 offset1:231
	v_add_u32_e32 v0, 0x2800, v31
	ds_write2_b32 v0, v74, v75 offset0:40 offset1:105
	ds_write2_b32 v0, v76, v77 offset0:170 offset1:235
	v_add_u32_e32 v0, 0x2c00, v31
	ds_write2_b32 v0, v78, v79 offset0:44 offset1:109
	ds_write2_b32 v0, v80, v81 offset0:174 offset1:239
	v_add_u32_e32 v0, 0x3000, v31
	ds_write2_b32 v0, v82, v83 offset0:48 offset1:113
	ds_write2_b32 v0, v84, v85 offset0:178 offset1:243
	v_add_u32_e32 v0, 0x3400, v31
	ds_write2_b32 v0, v86, v87 offset0:52 offset1:117
	ds_write2_b32 v0, v88, v89 offset0:182 offset1:247
	v_add_u32_e32 v0, 0x3800, v31
	ds_write2_b32 v0, v90, v91 offset0:56 offset1:121
	ds_write2_b32 v0, v92, v93 offset0:186 offset1:251
	v_add_u32_e32 v0, 0x3c00, v31
	ds_write2_b32 v0, v94, v95 offset0:60 offset1:125
	ds_write2_b32 v0, v4, v2 offset0:190 offset1:255
	s_waitcnt lgkmcnt(0)
	v_add_u32_e32 v47, 0x400, v33
	ds_read2_b32 v[8:9], v33 offset0:65 offset1:73
	ds_read2_b32 v[10:11], v33 offset1:8
	ds_read2_b32 v[12:13], v33 offset0:130 offset1:138
	ds_read2_b32 v[14:15], v33 offset0:195 offset1:203
	ds_read2_b32 v[16:17], v47 offset0:4 offset1:12
	ds_read2_b32 v[48:49], v47 offset0:69 offset1:77
	ds_read2_b32 v[50:51], v47 offset0:134 offset1:142
	ds_read2_b32 v[52:53], v47 offset0:199 offset1:207
	v_or_b32_e32 v0, s4, v32
	v_lshl_add_u64 v[2:3], v[28:29], 0, s[90:91]
	v_lshlrev_b32_e32 v0, 11, v0
	v_lshl_add_u64 v[54:55], v[2:3], 0, v[0:1]
	v_or_b32_e32 v0, s4, v34
	s_waitcnt lgkmcnt(6)
	v_cvt_pk_bf16_f32 v4, v10, v8
	s_waitcnt lgkmcnt(4)
	v_cvt_pk_bf16_f32 v5, v12, v14
	s_waitcnt lgkmcnt(2)
	v_cvt_pk_bf16_f32 v6, v16, v48
	s_waitcnt lgkmcnt(0)
	v_cvt_pk_bf16_f32 v7, v50, v52
	v_lshlrev_b32_e32 v0, 11, v0
	global_store_dwordx4 v[54:55], v[4:7], off sc1
	s_nop 1
	v_cvt_pk_bf16_f32 v4, v11, v9
	v_cvt_pk_bf16_f32 v5, v13, v15
	v_cvt_pk_bf16_f32 v6, v17, v49
	v_cvt_pk_bf16_f32 v7, v51, v53
	v_lshl_add_u64 v[8:9], v[2:3], 0, v[0:1]
	global_store_dwordx4 v[8:9], v[4:7], off sc1
	ds_read2_b32 v[8:9], v33 offset0:81 offset1:89
	ds_read2_b32 v[10:11], v33 offset0:16 offset1:24
	ds_read2_b32 v[12:13], v33 offset0:146 offset1:154
	ds_read2_b32 v[14:15], v33 offset0:211 offset1:219
	ds_read2_b32 v[16:17], v47 offset0:20 offset1:28
	ds_read2_b32 v[48:49], v47 offset0:85 offset1:93
	ds_read2_b32 v[50:51], v47 offset0:150 offset1:158
	ds_read2_b32 v[52:53], v47 offset0:215 offset1:223
	v_or_b32_e32 v0, s4, v35
	v_lshlrev_b32_e32 v0, 11, v0
	v_lshl_add_u64 v[54:55], v[2:3], 0, v[0:1]
	v_or_b32_e32 v0, s4, v36
	s_waitcnt lgkmcnt(6)
	v_cvt_pk_bf16_f32 v4, v10, v8
	s_waitcnt lgkmcnt(4)
	v_cvt_pk_bf16_f32 v5, v12, v14
	s_waitcnt lgkmcnt(2)
	v_cvt_pk_bf16_f32 v6, v16, v48
	s_waitcnt lgkmcnt(0)
	v_cvt_pk_bf16_f32 v7, v50, v52
	v_lshlrev_b32_e32 v0, 11, v0
	global_store_dwordx4 v[54:55], v[4:7], off sc1
	s_nop 1
	v_cvt_pk_bf16_f32 v4, v11, v9
	v_cvt_pk_bf16_f32 v5, v13, v15
	v_cvt_pk_bf16_f32 v6, v17, v49
	v_cvt_pk_bf16_f32 v7, v51, v53
	v_lshl_add_u64 v[8:9], v[2:3], 0, v[0:1]
	global_store_dwordx4 v[8:9], v[4:7], off sc1
	ds_read2_b32 v[8:9], v33 offset0:32 offset1:40
	ds_read2_b32 v[10:11], v33 offset0:97 offset1:105
	ds_read2_b32 v[12:13], v33 offset0:162 offset1:170
	ds_read2_b32 v[14:15], v33 offset0:227 offset1:235
	ds_read2_b32 v[16:17], v47 offset0:36 offset1:44
	ds_read2_b32 v[48:49], v47 offset0:101 offset1:109
	ds_read2_b32 v[50:51], v47 offset0:166 offset1:174
	ds_read2_b32 v[52:53], v47 offset0:231 offset1:239
	v_or_b32_e32 v0, s4, v37
	v_lshlrev_b32_e32 v0, 11, v0
	v_lshl_add_u64 v[54:55], v[2:3], 0, v[0:1]
	v_or_b32_e32 v0, s4, v38
	s_waitcnt lgkmcnt(6)
	v_cvt_pk_bf16_f32 v4, v8, v10
	s_waitcnt lgkmcnt(4)
	v_cvt_pk_bf16_f32 v5, v12, v14
	s_waitcnt lgkmcnt(2)
	v_cvt_pk_bf16_f32 v6, v16, v48
	s_waitcnt lgkmcnt(0)
	v_cvt_pk_bf16_f32 v7, v50, v52
	v_lshlrev_b32_e32 v0, 11, v0
	global_store_dwordx4 v[54:55], v[4:7], off sc1
	s_nop 1
	v_cvt_pk_bf16_f32 v4, v9, v11
	v_cvt_pk_bf16_f32 v5, v13, v15
	v_cvt_pk_bf16_f32 v6, v17, v49
	v_cvt_pk_bf16_f32 v7, v51, v53
	v_lshl_add_u64 v[8:9], v[2:3], 0, v[0:1]
	global_store_dwordx4 v[8:9], v[4:7], off sc1
	ds_read2_b32 v[8:9], v33 offset0:48 offset1:56
	ds_read2_b32 v[10:11], v33 offset0:113 offset1:121
	ds_read2_b32 v[12:13], v33 offset0:178 offset1:186
	ds_read2_b32 v[14:15], v33 offset0:243 offset1:251
	ds_read2_b32 v[16:17], v47 offset0:52 offset1:60
	ds_read2_b32 v[48:49], v47 offset0:117 offset1:125
	ds_read2_b32 v[50:51], v47 offset0:182 offset1:190
	ds_read2_b32 v[52:53], v47 offset0:247 offset1:255
	v_or_b32_e32 v0, s4, v39
	v_lshlrev_b32_e32 v0, 11, v0
	v_lshl_add_u64 v[54:55], v[2:3], 0, v[0:1]
	v_or_b32_e32 v0, s4, v40
	s_waitcnt lgkmcnt(6)
	v_cvt_pk_bf16_f32 v4, v8, v10
	s_waitcnt lgkmcnt(4)
	v_cvt_pk_bf16_f32 v5, v12, v14
	s_waitcnt lgkmcnt(2)
	v_cvt_pk_bf16_f32 v6, v16, v48
	s_waitcnt lgkmcnt(0)
	v_cvt_pk_bf16_f32 v7, v50, v52
	v_lshlrev_b32_e32 v0, 11, v0
	global_store_dwordx4 v[54:55], v[4:7], off sc1
	v_lshl_add_u64 v[2:3], v[2:3], 0, v[0:1]
	s_nop 0
	v_cvt_pk_bf16_f32 v4, v9, v11
	v_cvt_pk_bf16_f32 v5, v13, v15
	v_cvt_pk_bf16_f32 v6, v17, v49
	v_cvt_pk_bf16_f32 v7, v51, v53
	global_store_dwordx4 v[2:3], v[4:7], off sc1
	s_waitcnt lgkmcnt(0)

; #define PG8_WAIT_V(n) asm volatile("s_waitcnt vmcnt(" #n ")" ::: "memory")
; #define PG8_BAR __builtin_amdgcn_s_barrier()
; #define GSYNC() do { for (int r_ = 0; r_ < REP_SYNC; ++r_) xcd_barrier(bar); } while (0)
; template <class Epi, class Sched, bool ALIGN_EPI = false, bool SP2 = false, bool SPLITK = false>
; __device__ __forceinline__ void gemm_phase(PG8_LAS unsigned char* lds, const Gemm g, const Sched& S, const Epi& E) {
;     ...
;     PG8_WAIT_V(0);
;     if constexpr (!ALIGN_EPI) { if (wr == 0) PG8_BAR; }
;     PG8_BAR;
; __global__ void __launch_bounds__(NWAVES * 64, 2) mk_fwd(Args a) {
;     ...
;         GSYNC();
.LBB0_628:
	s_waitcnt vmcnt(0)
	s_waitcnt vmcnt(0)
	s_barrier
	s_mov_b64 s[16:17], exec
	v_readlane_b32 s12, v253, 36
	v_readlane_b32 s13, v253, 37
	s_and_b64 s[12:13], s[16:17], s[12:13]
	s_mov_b64 exec, s[12:13]
	s_cbranch_execz .LBB0_680
	s_cmp_lg_u32 s98, 0
	s_cbranch_scc0 .Lgb_full_680
	v_readlane_b32 s4, v253, 1
	v_readlane_b32 s12, v253, 56
	v_readlane_b32 s13, v253, 57
	s_add_i32 s99, s99, 4
	s_nop 2
	s_and_b32 s4, s4, 63
	s_lshl_b32 s4, s4, 7
	s_add_i32 s4, s4, 0x3e00
	v_mov_b32_e32 v2, s4
	s_mov_b32 s1, 0
	s_nop 1
	global_atomic_add v2, v234, s[12:13]
	v_mov_b32_e32 v4, 0x5ec0
	global_atomic_add v4, v234, s[12:13]

; #define PG8_WAIT_V(n) asm volatile("s_waitcnt vmcnt(" #n ")" ::: "memory")
; #define PG8_BAR __builtin_amdgcn_s_barrier()
; #define GSYNC() do { for (int r_ = 0; r_ < REP_SYNC; ++r_) xcd_barrier(bar); } while (0)
; template <class Epi, class Sched, bool ALIGN_EPI = false, bool SP2 = false, bool SPLITK = false>
; __device__ __forceinline__ void gemm_phase(PG8_LAS unsigned char* lds, const Gemm g, const Sched& S, const Epi& E) {
;     ...
;     PG8_WAIT_V(0);
;     if constexpr (!ALIGN_EPI) { if (wr == 0) PG8_BAR; }
;     PG8_BAR;
; __global__ void __launch_bounds__(NWAVES * 64, 2) mk_fwd(Args a) {
;     ...
;         GSYNC();
.LBB0_708:
	s_waitcnt vmcnt(0)
	s_barrier
	s_mov_b64 s[16:17], exec
	v_readlane_b32 s12, v253, 36
	v_readlane_b32 s13, v253, 37
	s_and_b64 s[12:13], s[16:17], s[12:13]
	s_mov_b64 exec, s[12:13]
	s_cbranch_execz .LBB0_137
	s_cmp_lg_u32 s98, 0
	s_cbranch_scc0 .Lgb_full_137
	s_cmp_eq_u32 s92, 3
	s_cbranch_scc1 .Lgb_full_137
	v_readlane_b32 s4, v253, 1
	v_readlane_b32 s12, v253, 56
	v_readlane_b32 s13, v253, 57
	s_add_i32 s99, s99, 4
	s_nop 2
	s_and_b32 s4, s4, 63
	s_lshl_b32 s4, s4, 7
	s_add_i32 s4, s4, 0x3e00
	v_mov_b32_e32 v2, s4
	s_mov_b32 s1, 0
	s_nop 1
	global_atomic_add v2, v234, s[12:13]
	v_mov_b32_e32 v4, 0x5e80
	global_atomic_add v4, v234, s[12:13]

; __device__ __forceinline__ unsigned xb_ld(unsigned* p)              { return __hip_atomic_load(p, __ATOMIC_RELAXED, __HIP_MEMORY_SCOPE_AGENT); }
; __device__ __forceinline__ unsigned xb_add(unsigned* p, unsigned v) { return __hip_atomic_fetch_add(p, v, __ATOMIC_RELAXED, __HIP_MEMORY_SCOPE_AGENT); }
; #define XB_SPIN(cond, bar) do { unsigned _sp = 0; while (cond) { __builtin_amdgcn_s_sleep(1); \
;     if ((++_sp & 255u) == 0u) { if (xb_ld(&(bar)[XB_TMO])) break; if (_sp > XB_SPIN_CAP) { atomicAdd(&(bar)[XB_TMO], 1u); break; } } } } while (0)
; __device__ __forceinline__ void xcd_barrier(const XcdBarrier& b) {
;     ...
;             else XB_SPIN(xb_ld(&bar[XB_TOPGEN]) == tg, bar);
;             __builtin_amdgcn_fence(__ATOMIC_ACQUIRE, "agent");
;             xb_add(&bar[XB_XGEN(b.x)], 1u);
;             asm volatile("s_waitcnt vmcnt(0)" ::: "memory");
;         } else {
;             XB_SPIN(xb_ld(&bar[XB_XGEN(b.x)]) == gen, bar);
.Lgb_grp_ok_137:
	v_mov_b32_e32 v4, 0x5ec0
	s_lshl_b32 s18, s92, 8
	s_add_i32 s18, s18, 0x100
.Lgb_cv_137:
	global_load_dword v3, v4, s[12:13] sc1
	s_waitcnt vmcnt(0)
	v_readfirstlane_b32 s19, v3
	s_nop 3
	s_cmp_ge_u32 s19, s18
	s_cbranch_scc1 .Lgb_cv_ok_137
	s_sleep 1
	s_add_i32 s1, s1, 1
	s_cmp_lt_u32 s1, 0x40000
	s_cbranch_scc1 .Lgb_cv_137
